# trim redundant waitcnt/setprio in GEMM MFMA segments; warm-up loads of LN stats and u/c vectors at top of MLP-up epilogues
# baseline (speedup 1.0000x reference)
.LBB0_310:
	ds_read_b128 v[148:151], v160
	ds_read_b128 v[164:167], v160 offset:1024
	ds_read_b128 v[168:171], v160 offset:2048
	ds_read_b128 v[172:175], v160 offset:3072
	ds_read_b128 v[176:179], v161
	ds_read_b128 v[180:183], v161 offset:1024
	ds_read_b128 v[184:187], v161 offset:2048
	ds_read_b128 v[188:191], v161 offset:3072
	s_add_i32 s26, s22, 2
	s_add_u32 s27, s8, 0x80
	s_addc_u32 s23, s9, 0
	s_cmp_eq_u32 s45, s22
	s_cselect_b32 s22, s0, s27
	s_cselect_b32 s23, s1, s23
	s_cselect_b32 s85, s21, s25
	s_cselect_b32 s84, s20, s24
	v_lshl_add_u64 v[152:153], s[8:9], 0, v[140:141]
	s_add_i32 m0, s35, 0xc000
	ds_read_b128 v[192:195], v162
	ds_read_b128 v[196:199], v162 offset:1024
	ds_read_b128 v[200:203], v162 offset:2048
	ds_read_b128 v[204:207], v162 offset:3072
	ds_read_b128 v[208:211], v162 offset:4096
	ds_read_b128 v[212:215], v162 offset:5120
	ds_read_b128 v[216:219], v162 offset:6144
	ds_read_b128 v[222:225], v162 offset:7168
	global_load_lds_dwordx4 v[152:153], off
	v_lshl_add_u64 v[152:153], s[8:9], 0, v[142:143]
	s_add_i32 m0, s35, 0xe000
	s_nop 0
	global_load_lds_dwordx4 v[152:153], off
	s_waitcnt vmcnt(8)
	s_waitcnt lgkmcnt(0)
	s_setprio 1
	s_barrier
	v_mfma_f32_16x16x32_bf16 v[124:127], v[148:151], v[192:195], v[124:127]
	v_mfma_f32_16x16x32_bf16 v[120:123], v[168:171], v[192:195], v[120:123]
	v_mfma_f32_16x16x32_bf16 v[108:111], v[148:151], v[200:203], v[108:111]
	v_mfma_f32_16x16x32_bf16 v[104:107], v[168:171], v[200:203], v[104:107]
	v_mfma_f32_16x16x32_bf16 v[92:95], v[148:151], v[208:211], v[92:95]
	v_mfma_f32_16x16x32_bf16 v[88:91], v[168:171], v[208:211], v[88:91]
	v_mfma_f32_16x16x32_bf16 v[76:79], v[148:151], v[216:219], v[76:79]
	v_mfma_f32_16x16x32_bf16 v[72:75], v[168:171], v[216:219], v[72:75]
	v_mfma_f32_16x16x32_bf16 v[124:127], v[164:167], v[196:199], v[124:127]
	v_mfma_f32_16x16x32_bf16 v[120:123], v[172:175], v[196:199], v[120:123]
	v_mfma_f32_16x16x32_bf16 v[108:111], v[164:167], v[204:207], v[108:111]
	v_mfma_f32_16x16x32_bf16 v[104:107], v[172:175], v[204:207], v[104:107]
	v_mfma_f32_16x16x32_bf16 v[92:95], v[164:167], v[212:215], v[92:95]
	v_mfma_f32_16x16x32_bf16 v[88:91], v[172:175], v[212:215], v[88:91]
	v_mfma_f32_16x16x32_bf16 v[76:79], v[164:167], v[222:225], v[76:79]
	v_mfma_f32_16x16x32_bf16 v[72:75], v[172:175], v[222:225], v[72:75]
	v_mfma_f32_16x16x32_bf16 v[116:119], v[176:179], v[192:195], v[116:119]
	v_mfma_f32_16x16x32_bf16 v[112:115], v[184:187], v[192:195], v[112:115]
	v_mfma_f32_16x16x32_bf16 v[100:103], v[176:179], v[200:203], v[100:103]
	v_mfma_f32_16x16x32_bf16 v[96:99], v[184:187], v[200:203], v[96:99]
	v_mfma_f32_16x16x32_bf16 v[84:87], v[176:179], v[208:211], v[84:87]
	v_mfma_f32_16x16x32_bf16 v[80:83], v[184:187], v[208:211], v[80:83]
	v_mfma_f32_16x16x32_bf16 v[68:71], v[176:179], v[216:219], v[68:71]
	v_mfma_f32_16x16x32_bf16 v[64:67], v[184:187], v[216:219], v[64:67]
	v_mfma_f32_16x16x32_bf16 v[116:119], v[180:183], v[196:199], v[116:119]
	v_mfma_f32_16x16x32_bf16 v[112:115], v[188:191], v[196:199], v[112:115]
	v_mfma_f32_16x16x32_bf16 v[100:103], v[180:183], v[204:207], v[100:103]
	v_mfma_f32_16x16x32_bf16 v[96:99], v[188:191], v[204:207], v[96:99]
	v_mfma_f32_16x16x32_bf16 v[84:87], v[180:183], v[212:215], v[84:87]
	v_mfma_f32_16x16x32_bf16 v[80:83], v[188:191], v[212:215], v[80:83]
	v_mfma_f32_16x16x32_bf16 v[68:71], v[180:183], v[222:225], v[68:71]
	v_mfma_f32_16x16x32_bf16 v[64:67], v[188:191], v[222:225], v[64:67]
	s_barrier
	s_setprio 0
	s_add_i32 s27, s77, s34
	v_lshl_add_u64 v[152:153], s[84:85], 0, v[130:131]
	s_mov_b32 m0, s27
	ds_read_b128 v[192:195], v162 offset:16384
	ds_read_b128 v[196:199], v162 offset:17408
	ds_read_b128 v[200:203], v162 offset:18432
	ds_read_b128 v[204:207], v162 offset:19456
	ds_read_b128 v[208:211], v162 offset:20480
	ds_read_b128 v[212:215], v162 offset:21504
	ds_read_b128 v[216:219], v162 offset:22528
	ds_read_b128 v[222:225], v162 offset:23552
	global_load_lds_dwordx4 v[152:153], off
	s_add_i32 m0, s27, 0x2000
	v_lshl_add_u64 v[226:227], s[84:85], 0, v[134:135]
	s_add_u32 s84, s84, s10
	s_addc_u32 s85, s85, s11
	s_add_i32 s27, s78, s34
	global_load_lds_dwordx4 v[226:227], off
	v_lshl_add_u64 v[228:229], s[84:85], 0, v[130:131]
	s_mov_b32 m0, s27
	v_lshl_add_u64 v[230:231], s[84:85], 0, v[134:135]
	global_load_lds_dwordx4 v[228:229], off
	s_add_i32 m0, s27, 0x2000
	v_lshl_add_u64 v[232:233], s[22:23], 0, v[128:129]
	global_load_lds_dwordx4 v[230:231], off
	s_mov_b32 m0, s35
	v_lshl_add_u64 v[234:235], s[22:23], 0, v[132:133]
	global_load_lds_dwordx4 v[232:233], off
	s_mov_b32 m0, s36
	s_nop 0
	global_load_lds_dwordx4 v[234:235], off
	s_waitcnt vmcnt(8)
	s_waitcnt lgkmcnt(0)
	s_setprio 1
	s_barrier
	v_mfma_f32_16x16x32_bf16 v[60:63], v[148:151], v[192:195], v[60:63]
	v_mfma_f32_16x16x32_bf16 v[56:59], v[168:171], v[192:195], v[56:59]
	v_mfma_f32_16x16x32_bf16 v[44:47], v[148:151], v[200:203], v[44:47]
	v_mfma_f32_16x16x32_bf16 v[40:43], v[168:171], v[200:203], v[40:43]
	v_mfma_f32_16x16x32_bf16 v[28:31], v[148:151], v[208:211], v[28:31]
	v_mfma_f32_16x16x32_bf16 v[24:27], v[168:171], v[208:211], v[24:27]
	v_mfma_f32_16x16x32_bf16 v[12:15], v[148:151], v[216:219], v[12:15]
	v_mfma_f32_16x16x32_bf16 v[8:11], v[168:171], v[216:219], v[8:11]
	v_mfma_f32_16x16x32_bf16 v[60:63], v[164:167], v[196:199], v[60:63]
	v_mfma_f32_16x16x32_bf16 v[56:59], v[172:175], v[196:199], v[56:59]
	v_mfma_f32_16x16x32_bf16 v[44:47], v[164:167], v[204:207], v[44:47]
	v_mfma_f32_16x16x32_bf16 v[40:43], v[172:175], v[204:207], v[40:43]
	v_mfma_f32_16x16x32_bf16 v[28:31], v[164:167], v[212:215], v[28:31]
	v_mfma_f32_16x16x32_bf16 v[24:27], v[172:175], v[212:215], v[24:27]
	v_mfma_f32_16x16x32_bf16 v[12:15], v[164:167], v[222:225], v[12:15]
	v_mfma_f32_16x16x32_bf16 v[8:11], v[172:175], v[222:225], v[8:11]
	v_mfma_f32_16x16x32_bf16 v[52:55], v[176:179], v[192:195], v[52:55]
	v_mfma_f32_16x16x32_bf16 v[48:51], v[184:187], v[192:195], v[48:51]
	v_mfma_f32_16x16x32_bf16 v[36:39], v[176:179], v[200:203], v[36:39]
	v_mfma_f32_16x16x32_bf16 v[32:35], v[184:187], v[200:203], v[32:35]
	v_mfma_f32_16x16x32_bf16 v[20:23], v[176:179], v[208:211], v[20:23]
	v_mfma_f32_16x16x32_bf16 v[16:19], v[184:187], v[208:211], v[16:19]
	v_mfma_f32_16x16x32_bf16 v[4:7], v[176:179], v[216:219], v[4:7]
	v_mfma_f32_16x16x32_bf16 v[0:3], v[184:187], v[216:219], v[0:3]
	v_mfma_f32_16x16x32_bf16 v[52:55], v[180:183], v[196:199], v[52:55]
	v_mfma_f32_16x16x32_bf16 v[48:51], v[188:191], v[196:199], v[48:51]
	v_mfma_f32_16x16x32_bf16 v[36:39], v[180:183], v[204:207], v[36:39]
	v_mfma_f32_16x16x32_bf16 v[32:35], v[188:191], v[204:207], v[32:35]
	v_mfma_f32_16x16x32_bf16 v[20:23], v[180:183], v[212:215], v[20:23]
	v_mfma_f32_16x16x32_bf16 v[16:19], v[188:191], v[212:215], v[16:19]
	v_mfma_f32_16x16x32_bf16 v[4:7], v[180:183], v[222:225], v[4:7]
	v_mfma_f32_16x16x32_bf16 v[0:3], v[188:191], v[222:225], v[0:3]
	s_barrier
	s_setprio 0
	s_add_i32 s27, 0, 0x18000
	v_add_u32_e32 v136, s27, v156
	s_add_i32 s81, 0, 0x1c000
	ds_read_b128 v[148:151], v136
	ds_read_b128 v[164:167], v136 offset:1024
	ds_read_b128 v[168:171], v136 offset:2048
	ds_read_b128 v[172:175], v136 offset:3072
	v_add_u32_e32 v136, s81, v156
	ds_read_b128 v[176:179], v136
	ds_read_b128 v[180:183], v136 offset:1024
	ds_read_b128 v[184:187], v136 offset:2048
	ds_read_b128 v[188:191], v136 offset:3072
	s_add_u32 s22, s22, s10
	s_addc_u32 s23, s23, s11
	s_mov_b32 m0, s37
	v_lshl_add_u64 v[236:237], s[22:23], 0, v[128:129]
	ds_read_b128 v[192:195], v162 offset:32768
	ds_read_b128 v[196:199], v162 offset:33792
	ds_read_b128 v[200:203], v162 offset:34816
	ds_read_b128 v[204:207], v162 offset:35840
	ds_read_b128 v[208:211], v162 offset:36864
	ds_read_b128 v[212:215], v162 offset:37888
	ds_read_b128 v[216:219], v162 offset:38912
	ds_read_b128 v[222:225], v162 offset:39936
	global_load_lds_dwordx4 v[236:237], off
	v_lshl_add_u64 v[236:237], s[22:23], 0, v[132:133]
	s_mov_b32 m0, s38
	s_nop 0
	global_load_lds_dwordx4 v[236:237], off
	s_waitcnt vmcnt(8)
	s_waitcnt lgkmcnt(0)
	s_setprio 1
	s_barrier
	v_mfma_f32_16x16x32_bf16 v[124:127], v[148:151], v[192:195], v[124:127]
	v_mfma_f32_16x16x32_bf16 v[120:123], v[168:171], v[192:195], v[120:123]
	v_mfma_f32_16x16x32_bf16 v[108:111], v[148:151], v[200:203], v[108:111]
	v_mfma_f32_16x16x32_bf16 v[104:107], v[168:171], v[200:203], v[104:107]
	v_mfma_f32_16x16x32_bf16 v[92:95], v[148:151], v[208:211], v[92:95]
	v_mfma_f32_16x16x32_bf16 v[88:91], v[168:171], v[208:211], v[88:91]
	v_mfma_f32_16x16x32_bf16 v[76:79], v[148:151], v[216:219], v[76:79]
	v_mfma_f32_16x16x32_bf16 v[72:75], v[168:171], v[216:219], v[72:75]
	v_mfma_f32_16x16x32_bf16 v[124:127], v[164:167], v[196:199], v[124:127]
	v_mfma_f32_16x16x32_bf16 v[120:123], v[172:175], v[196:199], v[120:123]
	v_mfma_f32_16x16x32_bf16 v[108:111], v[164:167], v[204:207], v[108:111]
	v_mfma_f32_16x16x32_bf16 v[104:107], v[172:175], v[204:207], v[104:107]
	v_mfma_f32_16x16x32_bf16 v[92:95], v[164:167], v[212:215], v[92:95]
	v_mfma_f32_16x16x32_bf16 v[88:91], v[172:175], v[212:215], v[88:91]
	v_mfma_f32_16x16x32_bf16 v[76:79], v[164:167], v[222:225], v[76:79]
	v_mfma_f32_16x16x32_bf16 v[72:75], v[172:175], v[222:225], v[72:75]
	v_mfma_f32_16x16x32_bf16 v[116:119], v[176:179], v[192:195], v[116:119]
	v_mfma_f32_16x16x32_bf16 v[112:115], v[184:187], v[192:195], v[112:115]
	v_mfma_f32_16x16x32_bf16 v[100:103], v[176:179], v[200:203], v[100:103]
	v_mfma_f32_16x16x32_bf16 v[96:99], v[184:187], v[200:203], v[96:99]
	v_mfma_f32_16x16x32_bf16 v[84:87], v[176:179], v[208:211], v[84:87]
	v_mfma_f32_16x16x32_bf16 v[80:83], v[184:187], v[208:211], v[80:83]
	v_mfma_f32_16x16x32_bf16 v[68:71], v[176:179], v[216:219], v[68:71]
	v_mfma_f32_16x16x32_bf16 v[64:67], v[184:187], v[216:219], v[64:67]
	v_mfma_f32_16x16x32_bf16 v[116:119], v[180:183], v[196:199], v[116:119]
	v_mfma_f32_16x16x32_bf16 v[112:115], v[188:191], v[196:199], v[112:115]
	v_mfma_f32_16x16x32_bf16 v[100:103], v[180:183], v[204:207], v[100:103]
	v_mfma_f32_16x16x32_bf16 v[96:99], v[188:191], v[204:207], v[96:99]
	v_mfma_f32_16x16x32_bf16 v[84:87], v[180:183], v[212:215], v[84:87]
	v_mfma_f32_16x16x32_bf16 v[80:83], v[188:191], v[212:215], v[80:83]
	v_mfma_f32_16x16x32_bf16 v[68:71], v[180:183], v[222:225], v[68:71]
	v_mfma_f32_16x16x32_bf16 v[64:67], v[188:191], v[222:225], v[64:67]
	s_barrier
	s_setprio 0
	s_add_i32 s22, s27, s34
	v_lshl_add_u64 v[152:153], v[152:153], 0, s[16:17]
	s_mov_b32 m0, s22
	ds_read_b128 v[192:195], v162 offset:49152
	ds_read_b128 v[196:199], v162 offset:50176
	ds_read_b128 v[200:203], v162 offset:51200
	ds_read_b128 v[204:207], v162 offset:52224
	ds_read_b128 v[208:211], v162 offset:53248
	ds_read_b128 v[212:215], v162 offset:54272
	ds_read_b128 v[216:219], v162 offset:55296
	ds_read_b128 v[222:225], v162 offset:56320
	global_load_lds_dwordx4 v[152:153], off
	v_lshl_add_u64 v[152:153], v[226:227], 0, s[16:17]
	s_add_i32 m0, s22, 0x2000
	s_add_i32 s22, s81, s34
	global_load_lds_dwordx4 v[152:153], off
	v_lshl_add_u64 v[152:153], v[228:229], 0, s[16:17]
	s_mov_b32 m0, s22
	s_nop 0
	global_load_lds_dwordx4 v[152:153], off
	v_lshl_add_u64 v[152:153], v[230:231], 0, s[16:17]
	s_add_i32 m0, s22, 0x2000
	s_nop 0
	global_load_lds_dwordx4 v[152:153], off
	v_lshl_add_u64 v[152:153], v[232:233], 0, s[16:17]
	s_mov_b32 m0, s40
	s_nop 0
	global_load_lds_dwordx4 v[152:153], off
	v_lshl_add_u64 v[152:153], v[234:235], 0, s[16:17]
	s_mov_b32 m0, s41
	s_nop 0
	global_load_lds_dwordx4 v[152:153], off
	s_waitcnt vmcnt(8)
	s_waitcnt lgkmcnt(0)
	s_setprio 1
	s_barrier
	v_mfma_f32_16x16x32_bf16 v[60:63], v[148:151], v[192:195], v[60:63]
	v_mfma_f32_16x16x32_bf16 v[56:59], v[168:171], v[192:195], v[56:59]
	v_mfma_f32_16x16x32_bf16 v[44:47], v[148:151], v[200:203], v[44:47]
	v_mfma_f32_16x16x32_bf16 v[40:43], v[168:171], v[200:203], v[40:43]
	v_mfma_f32_16x16x32_bf16 v[28:31], v[148:151], v[208:211], v[28:31]
	v_mfma_f32_16x16x32_bf16 v[24:27], v[168:171], v[208:211], v[24:27]
	v_mfma_f32_16x16x32_bf16 v[12:15], v[148:151], v[216:219], v[12:15]
	v_mfma_f32_16x16x32_bf16 v[8:11], v[168:171], v[216:219], v[8:11]
	v_mfma_f32_16x16x32_bf16 v[60:63], v[164:167], v[196:199], v[60:63]
	v_mfma_f32_16x16x32_bf16 v[56:59], v[172:175], v[196:199], v[56:59]
	v_mfma_f32_16x16x32_bf16 v[44:47], v[164:167], v[204:207], v[44:47]
	v_mfma_f32_16x16x32_bf16 v[40:43], v[172:175], v[204:207], v[40:43]
	v_mfma_f32_16x16x32_bf16 v[28:31], v[164:167], v[212:215], v[28:31]
	v_mfma_f32_16x16x32_bf16 v[24:27], v[172:175], v[212:215], v[24:27]
	v_mfma_f32_16x16x32_bf16 v[12:15], v[164:167], v[222:225], v[12:15]
	v_mfma_f32_16x16x32_bf16 v[8:11], v[172:175], v[222:225], v[8:11]
	v_mfma_f32_16x16x32_bf16 v[52:55], v[176:179], v[192:195], v[52:55]
	v_mfma_f32_16x16x32_bf16 v[48:51], v[184:187], v[192:195], v[48:51]
	v_mfma_f32_16x16x32_bf16 v[36:39], v[176:179], v[200:203], v[36:39]
	v_mfma_f32_16x16x32_bf16 v[32:35], v[184:187], v[200:203], v[32:35]
	v_mfma_f32_16x16x32_bf16 v[20:23], v[176:179], v[208:211], v[20:23]
	v_mfma_f32_16x16x32_bf16 v[16:19], v[184:187], v[208:211], v[16:19]
	v_mfma_f32_16x16x32_bf16 v[4:7], v[176:179], v[216:219], v[4:7]
	v_mfma_f32_16x16x32_bf16 v[0:3], v[184:187], v[216:219], v[0:3]
	v_mfma_f32_16x16x32_bf16 v[52:55], v[180:183], v[196:199], v[52:55]
	v_mfma_f32_16x16x32_bf16 v[48:51], v[188:191], v[196:199], v[48:51]
	v_mfma_f32_16x16x32_bf16 v[36:39], v[180:183], v[204:207], v[36:39]
	v_mfma_f32_16x16x32_bf16 v[32:35], v[188:191], v[204:207], v[32:35]
	v_mfma_f32_16x16x32_bf16 v[20:23], v[180:183], v[212:215], v[20:23]
	v_mfma_f32_16x16x32_bf16 v[16:19], v[188:191], v[212:215], v[16:19]
	v_mfma_f32_16x16x32_bf16 v[4:7], v[180:183], v[222:225], v[4:7]
	v_mfma_f32_16x16x32_bf16 v[0:3], v[188:191], v[222:225], v[0:3]
	s_barrier
	s_setprio 0
	s_add_u32 s8, s8, 0x100
	s_addc_u32 s9, s9, 0
	s_add_u32 s24, s24, 0x100
	s_addc_u32 s25, s25, 0
	s_cmp_ge_i32 s26, s42
	s_mov_b32 s22, s26
	s_cbranch_scc0 .LBB0_310

.LBB0_675:
	ds_read_b128 v[144:147], v193
	ds_read_b128 v[148:151], v193 offset:1024
	ds_read_b128 v[152:155], v193 offset:2048
	ds_read_b128 v[156:159], v193 offset:3072
	ds_read_b128 v[160:163], v194
	ds_read_b128 v[164:167], v194 offset:1024
	ds_read_b128 v[168:171], v194 offset:2048
	ds_read_b128 v[172:175], v194 offset:3072
	s_add_i32 s81, s36, 2
	s_add_u32 s84, s34, 0x80
	s_addc_u32 s37, s35, 0
	s_cmp_eq_u32 s55, s36
	s_cselect_b32 s36, s0, s84
	s_cselect_b32 s37, s1, s37
	s_cselect_b32 s85, s31, s80
	s_cselect_b32 s84, s30, s79
	v_lshl_add_u64 v[216:217], s[34:35], 0, v[136:137]
	s_add_i32 m0, s40, 0xc000
	ds_read_b128 v[176:179], v195
	ds_read_b128 v[180:183], v195 offset:1024
	ds_read_b128 v[184:187], v195 offset:2048
	ds_read_b128 v[196:199], v195 offset:3072
	ds_read_b128 v[200:203], v195 offset:4096
	ds_read_b128 v[204:207], v195 offset:5120
	ds_read_b128 v[208:211], v195 offset:6144
	ds_read_b128 v[212:215], v195 offset:7168
	global_load_lds_dwordx4 v[216:217], off
	v_lshl_add_u64 v[216:217], s[34:35], 0, v[138:139]
	s_add_i32 m0, s40, 0xe000
	s_nop 0
	global_load_lds_dwordx4 v[216:217], off
	s_waitcnt vmcnt(8)
	s_waitcnt lgkmcnt(0)
	s_setprio 1
	s_barrier
	v_mfma_f32_16x16x32_bf16 v[120:123], v[144:147], v[176:179], v[120:123]
	v_mfma_f32_16x16x32_bf16 v[124:127], v[152:155], v[176:179], v[124:127]
	v_mfma_f32_16x16x32_bf16 v[116:119], v[144:147], v[184:187], v[116:119]
	v_mfma_f32_16x16x32_bf16 v[112:115], v[152:155], v[184:187], v[112:115]
	v_mfma_f32_16x16x32_bf16 v[108:111], v[144:147], v[200:203], v[108:111]
	v_mfma_f32_16x16x32_bf16 v[104:107], v[152:155], v[200:203], v[104:107]
	v_mfma_f32_16x16x32_bf16 v[100:103], v[144:147], v[208:211], v[100:103]
	v_mfma_f32_16x16x32_bf16 v[96:99], v[152:155], v[208:211], v[96:99]
	v_mfma_f32_16x16x32_bf16 v[120:123], v[148:151], v[180:183], v[120:123]
	v_mfma_f32_16x16x32_bf16 v[124:127], v[156:159], v[180:183], v[124:127]
	v_mfma_f32_16x16x32_bf16 v[116:119], v[148:151], v[196:199], v[116:119]
	v_mfma_f32_16x16x32_bf16 v[112:115], v[156:159], v[196:199], v[112:115]
	v_mfma_f32_16x16x32_bf16 v[108:111], v[148:151], v[204:207], v[108:111]
	v_mfma_f32_16x16x32_bf16 v[104:107], v[156:159], v[204:207], v[104:107]
	v_mfma_f32_16x16x32_bf16 v[100:103], v[148:151], v[212:215], v[100:103]
	v_mfma_f32_16x16x32_bf16 v[96:99], v[156:159], v[212:215], v[96:99]
	v_mfma_f32_16x16x32_bf16 v[60:63], v[160:163], v[176:179], v[60:63]
	v_mfma_f32_16x16x32_bf16 v[56:59], v[168:171], v[176:179], v[56:59]
	v_mfma_f32_16x16x32_bf16 v[52:55], v[160:163], v[184:187], v[52:55]
	v_mfma_f32_16x16x32_bf16 v[48:51], v[168:171], v[184:187], v[48:51]
	v_mfma_f32_16x16x32_bf16 v[44:47], v[160:163], v[200:203], v[44:47]
	v_mfma_f32_16x16x32_bf16 v[40:43], v[168:171], v[200:203], v[40:43]
	v_mfma_f32_16x16x32_bf16 v[36:39], v[160:163], v[208:211], v[36:39]
	v_mfma_f32_16x16x32_bf16 v[32:35], v[168:171], v[208:211], v[32:35]
	v_mfma_f32_16x16x32_bf16 v[60:63], v[164:167], v[180:183], v[60:63]
	v_mfma_f32_16x16x32_bf16 v[56:59], v[172:175], v[180:183], v[56:59]
	v_mfma_f32_16x16x32_bf16 v[52:55], v[164:167], v[196:199], v[52:55]
	v_mfma_f32_16x16x32_bf16 v[48:51], v[172:175], v[196:199], v[48:51]
	v_mfma_f32_16x16x32_bf16 v[44:47], v[164:167], v[204:207], v[44:47]
	v_mfma_f32_16x16x32_bf16 v[40:43], v[172:175], v[204:207], v[40:43]
	v_mfma_f32_16x16x32_bf16 v[36:39], v[164:167], v[212:215], v[36:39]
	v_mfma_f32_16x16x32_bf16 v[32:35], v[172:175], v[212:215], v[32:35]
	s_barrier
	s_setprio 0
	s_add_i32 s86, s58, s39
	v_lshl_add_u64 v[216:217], s[84:85], 0, v[130:131]
	s_mov_b32 m0, s86
	ds_read_b128 v[176:179], v195 offset:16384
	ds_read_b128 v[180:183], v195 offset:17408
	ds_read_b128 v[184:187], v195 offset:18432
	ds_read_b128 v[196:199], v195 offset:19456
	ds_read_b128 v[200:203], v195 offset:20480
	ds_read_b128 v[204:207], v195 offset:21504
	ds_read_b128 v[208:211], v195 offset:22528
	ds_read_b128 v[212:215], v195 offset:23552
	global_load_lds_dwordx4 v[216:217], off
	s_add_i32 m0, s86, 0x2000
	v_lshl_add_u64 v[218:219], s[84:85], 0, v[134:135]
	s_add_u32 s84, s84, s10
	s_addc_u32 s85, s85, s11
	s_add_i32 s86, s59, s39
	global_load_lds_dwordx4 v[218:219], off
	v_lshl_add_u64 v[224:225], s[84:85], 0, v[130:131]
	s_mov_b32 m0, s86
	v_lshl_add_u64 v[226:227], s[84:85], 0, v[134:135]
	global_load_lds_dwordx4 v[224:225], off
	s_add_i32 m0, s86, 0x2000
	v_lshl_add_u64 v[228:229], s[36:37], 0, v[128:129]
	global_load_lds_dwordx4 v[226:227], off
	s_mov_b32 m0, s40
	v_lshl_add_u64 v[230:231], s[36:37], 0, v[132:133]
	global_load_lds_dwordx4 v[228:229], off
	s_mov_b32 m0, s41
	s_nop 0
	global_load_lds_dwordx4 v[230:231], off
	s_waitcnt vmcnt(8)
	s_waitcnt lgkmcnt(0)
	s_setprio 1
	s_barrier
	v_mfma_f32_16x16x32_bf16 v[92:95], v[144:147], v[176:179], v[92:95]
	v_mfma_f32_16x16x32_bf16 v[88:91], v[152:155], v[176:179], v[88:91]
	v_mfma_f32_16x16x32_bf16 v[84:87], v[144:147], v[184:187], v[84:87]
	v_mfma_f32_16x16x32_bf16 v[80:83], v[152:155], v[184:187], v[80:83]
	v_mfma_f32_16x16x32_bf16 v[76:79], v[144:147], v[200:203], v[76:79]
	v_mfma_f32_16x16x32_bf16 v[72:75], v[152:155], v[200:203], v[72:75]
	v_mfma_f32_16x16x32_bf16 v[68:71], v[144:147], v[208:211], v[68:71]
	v_mfma_f32_16x16x32_bf16 v[64:67], v[152:155], v[208:211], v[64:67]
	v_mfma_f32_16x16x32_bf16 v[92:95], v[148:151], v[180:183], v[92:95]
	v_mfma_f32_16x16x32_bf16 v[88:91], v[156:159], v[180:183], v[88:91]
	v_mfma_f32_16x16x32_bf16 v[84:87], v[148:151], v[196:199], v[84:87]
	v_mfma_f32_16x16x32_bf16 v[80:83], v[156:159], v[196:199], v[80:83]
	v_mfma_f32_16x16x32_bf16 v[76:79], v[148:151], v[204:207], v[76:79]
	v_mfma_f32_16x16x32_bf16 v[72:75], v[156:159], v[204:207], v[72:75]
	v_mfma_f32_16x16x32_bf16 v[68:71], v[148:151], v[212:215], v[68:71]
	v_mfma_f32_16x16x32_bf16 v[64:67], v[156:159], v[212:215], v[64:67]
	v_mfma_f32_16x16x32_bf16 v[28:31], v[160:163], v[176:179], v[28:31]
	v_mfma_f32_16x16x32_bf16 v[24:27], v[168:171], v[176:179], v[24:27]
	v_mfma_f32_16x16x32_bf16 v[20:23], v[160:163], v[184:187], v[20:23]
	v_mfma_f32_16x16x32_bf16 v[16:19], v[168:171], v[184:187], v[16:19]
	v_mfma_f32_16x16x32_bf16 v[12:15], v[160:163], v[200:203], v[12:15]
	v_mfma_f32_16x16x32_bf16 v[8:11], v[168:171], v[200:203], v[8:11]
	v_mfma_f32_16x16x32_bf16 v[4:7], v[160:163], v[208:211], v[4:7]
	v_mfma_f32_16x16x32_bf16 v[0:3], v[168:171], v[208:211], v[0:3]
	v_mfma_f32_16x16x32_bf16 v[28:31], v[164:167], v[180:183], v[28:31]
	v_mfma_f32_16x16x32_bf16 v[24:27], v[172:175], v[180:183], v[24:27]
	v_mfma_f32_16x16x32_bf16 v[20:23], v[164:167], v[196:199], v[20:23]
	v_mfma_f32_16x16x32_bf16 v[16:19], v[172:175], v[196:199], v[16:19]
	v_mfma_f32_16x16x32_bf16 v[12:15], v[164:167], v[204:207], v[12:15]
	v_mfma_f32_16x16x32_bf16 v[8:11], v[172:175], v[204:207], v[8:11]
	v_mfma_f32_16x16x32_bf16 v[4:7], v[164:167], v[212:215], v[4:7]
	v_mfma_f32_16x16x32_bf16 v[0:3], v[172:175], v[212:215], v[0:3]
	s_barrier
	s_setprio 0
	s_add_i32 s84, 0, 0x18000
	s_add_i32 s85, 0, 0x1c000
	v_add_u32_e32 v156, s84, v189
	v_add_u32_e32 v172, s85, v189
	ds_read_b128 v[144:147], v156
	ds_read_b128 v[148:151], v156 offset:1024
	ds_read_b128 v[152:155], v156 offset:2048
	ds_read_b128 v[156:159], v156 offset:3072
	ds_read_b128 v[160:163], v172
	ds_read_b128 v[164:167], v172 offset:1024
	ds_read_b128 v[168:171], v172 offset:2048
	ds_read_b128 v[172:175], v172 offset:3072
	s_add_u32 s36, s36, s10
	s_addc_u32 s37, s37, s11
	s_mov_b32 m0, s42
	v_lshl_add_u64 v[232:233], s[36:37], 0, v[128:129]
	ds_read_b128 v[176:179], v195 offset:32768
	ds_read_b128 v[180:183], v195 offset:33792
	ds_read_b128 v[184:187], v195 offset:34816
	ds_read_b128 v[196:199], v195 offset:35840
	ds_read_b128 v[200:203], v195 offset:36864
	ds_read_b128 v[204:207], v195 offset:37888
	ds_read_b128 v[208:211], v195 offset:38912
	ds_read_b128 v[212:215], v195 offset:39936
	global_load_lds_dwordx4 v[232:233], off
	v_lshl_add_u64 v[232:233], s[36:37], 0, v[132:133]
	s_mov_b32 m0, s43
	s_nop 0
	global_load_lds_dwordx4 v[232:233], off
	s_waitcnt vmcnt(8)
	s_waitcnt lgkmcnt(0)
	s_setprio 1
	s_barrier
	v_mfma_f32_16x16x32_bf16 v[120:123], v[144:147], v[176:179], v[120:123]
	v_mfma_f32_16x16x32_bf16 v[124:127], v[152:155], v[176:179], v[124:127]
	v_mfma_f32_16x16x32_bf16 v[116:119], v[144:147], v[184:187], v[116:119]
	v_mfma_f32_16x16x32_bf16 v[112:115], v[152:155], v[184:187], v[112:115]
	v_mfma_f32_16x16x32_bf16 v[108:111], v[144:147], v[200:203], v[108:111]
	v_mfma_f32_16x16x32_bf16 v[104:107], v[152:155], v[200:203], v[104:107]
	v_mfma_f32_16x16x32_bf16 v[100:103], v[144:147], v[208:211], v[100:103]
	v_mfma_f32_16x16x32_bf16 v[96:99], v[152:155], v[208:211], v[96:99]
	v_mfma_f32_16x16x32_bf16 v[120:123], v[148:151], v[180:183], v[120:123]
	v_mfma_f32_16x16x32_bf16 v[124:127], v[156:159], v[180:183], v[124:127]
	v_mfma_f32_16x16x32_bf16 v[116:119], v[148:151], v[196:199], v[116:119]
	v_mfma_f32_16x16x32_bf16 v[112:115], v[156:159], v[196:199], v[112:115]
	v_mfma_f32_16x16x32_bf16 v[108:111], v[148:151], v[204:207], v[108:111]
	v_mfma_f32_16x16x32_bf16 v[104:107], v[156:159], v[204:207], v[104:107]
	v_mfma_f32_16x16x32_bf16 v[100:103], v[148:151], v[212:215], v[100:103]
	v_mfma_f32_16x16x32_bf16 v[96:99], v[156:159], v[212:215], v[96:99]
	v_mfma_f32_16x16x32_bf16 v[60:63], v[160:163], v[176:179], v[60:63]
	v_mfma_f32_16x16x32_bf16 v[56:59], v[168:171], v[176:179], v[56:59]
	v_mfma_f32_16x16x32_bf16 v[52:55], v[160:163], v[184:187], v[52:55]
	v_mfma_f32_16x16x32_bf16 v[48:51], v[168:171], v[184:187], v[48:51]
	v_mfma_f32_16x16x32_bf16 v[44:47], v[160:163], v[200:203], v[44:47]
	v_mfma_f32_16x16x32_bf16 v[40:43], v[168:171], v[200:203], v[40:43]
	v_mfma_f32_16x16x32_bf16 v[36:39], v[160:163], v[208:211], v[36:39]
	v_mfma_f32_16x16x32_bf16 v[32:35], v[168:171], v[208:211], v[32:35]
	v_mfma_f32_16x16x32_bf16 v[60:63], v[164:167], v[180:183], v[60:63]
	v_mfma_f32_16x16x32_bf16 v[56:59], v[172:175], v[180:183], v[56:59]
	v_mfma_f32_16x16x32_bf16 v[52:55], v[164:167], v[196:199], v[52:55]
	v_mfma_f32_16x16x32_bf16 v[48:51], v[172:175], v[196:199], v[48:51]
	v_mfma_f32_16x16x32_bf16 v[44:47], v[164:167], v[204:207], v[44:47]
	v_mfma_f32_16x16x32_bf16 v[40:43], v[172:175], v[204:207], v[40:43]
	v_mfma_f32_16x16x32_bf16 v[36:39], v[164:167], v[212:215], v[36:39]
	v_mfma_f32_16x16x32_bf16 v[32:35], v[172:175], v[212:215], v[32:35]
	s_barrier
	s_setprio 0
	s_add_i32 s36, s84, s39
	v_lshl_add_u64 v[216:217], v[216:217], 0, s[22:23]
	s_mov_b32 m0, s36
	ds_read_b128 v[176:179], v195 offset:49152
	ds_read_b128 v[180:183], v195 offset:50176
	ds_read_b128 v[184:187], v195 offset:51200
	ds_read_b128 v[196:199], v195 offset:52224
	ds_read_b128 v[200:203], v195 offset:53248
	ds_read_b128 v[204:207], v195 offset:54272
	ds_read_b128 v[208:211], v195 offset:55296
	ds_read_b128 v[212:215], v195 offset:56320
	global_load_lds_dwordx4 v[216:217], off
	v_lshl_add_u64 v[216:217], v[218:219], 0, s[22:23]
	s_add_i32 m0, s36, 0x2000
	s_add_i32 s36, s85, s39
	global_load_lds_dwordx4 v[216:217], off
	v_lshl_add_u64 v[216:217], v[224:225], 0, s[22:23]
	s_mov_b32 m0, s36
	s_nop 0
	global_load_lds_dwordx4 v[216:217], off
	v_lshl_add_u64 v[216:217], v[226:227], 0, s[22:23]
	s_add_i32 m0, s36, 0x2000
	s_nop 0
	global_load_lds_dwordx4 v[216:217], off
	v_lshl_add_u64 v[216:217], v[228:229], 0, s[22:23]
	s_mov_b32 m0, s45
	s_nop 0
	global_load_lds_dwordx4 v[216:217], off
	v_lshl_add_u64 v[216:217], v[230:231], 0, s[22:23]
	s_mov_b32 m0, s47
	s_nop 0
	global_load_lds_dwordx4 v[216:217], off
	s_waitcnt vmcnt(8)
	s_waitcnt lgkmcnt(0)
	s_setprio 1
	s_barrier
	v_mfma_f32_16x16x32_bf16 v[92:95], v[144:147], v[176:179], v[92:95]
	v_mfma_f32_16x16x32_bf16 v[88:91], v[152:155], v[176:179], v[88:91]
	v_mfma_f32_16x16x32_bf16 v[84:87], v[144:147], v[184:187], v[84:87]
	v_mfma_f32_16x16x32_bf16 v[80:83], v[152:155], v[184:187], v[80:83]
	v_mfma_f32_16x16x32_bf16 v[76:79], v[144:147], v[200:203], v[76:79]
	v_mfma_f32_16x16x32_bf16 v[72:75], v[152:155], v[200:203], v[72:75]
	v_mfma_f32_16x16x32_bf16 v[68:71], v[144:147], v[208:211], v[68:71]
	v_mfma_f32_16x16x32_bf16 v[64:67], v[152:155], v[208:211], v[64:67]
	v_mfma_f32_16x16x32_bf16 v[92:95], v[148:151], v[180:183], v[92:95]
	v_mfma_f32_16x16x32_bf16 v[88:91], v[156:159], v[180:183], v[88:91]
	v_mfma_f32_16x16x32_bf16 v[84:87], v[148:151], v[196:199], v[84:87]
	v_mfma_f32_16x16x32_bf16 v[80:83], v[156:159], v[196:199], v[80:83]
	v_mfma_f32_16x16x32_bf16 v[76:79], v[148:151], v[204:207], v[76:79]
	v_mfma_f32_16x16x32_bf16 v[72:75], v[156:159], v[204:207], v[72:75]
	v_mfma_f32_16x16x32_bf16 v[68:71], v[148:151], v[212:215], v[68:71]
	v_mfma_f32_16x16x32_bf16 v[64:67], v[156:159], v[212:215], v[64:67]
	v_mfma_f32_16x16x32_bf16 v[28:31], v[160:163], v[176:179], v[28:31]
	v_mfma_f32_16x16x32_bf16 v[24:27], v[168:171], v[176:179], v[24:27]
	v_mfma_f32_16x16x32_bf16 v[20:23], v[160:163], v[184:187], v[20:23]
	v_mfma_f32_16x16x32_bf16 v[16:19], v[168:171], v[184:187], v[16:19]
	v_mfma_f32_16x16x32_bf16 v[12:15], v[160:163], v[200:203], v[12:15]
	v_mfma_f32_16x16x32_bf16 v[8:11], v[168:171], v[200:203], v[8:11]
	v_mfma_f32_16x16x32_bf16 v[4:7], v[160:163], v[208:211], v[4:7]
	v_mfma_f32_16x16x32_bf16 v[0:3], v[168:171], v[208:211], v[0:3]
	v_mfma_f32_16x16x32_bf16 v[28:31], v[164:167], v[180:183], v[28:31]
	v_mfma_f32_16x16x32_bf16 v[24:27], v[172:175], v[180:183], v[24:27]
	v_mfma_f32_16x16x32_bf16 v[20:23], v[164:167], v[196:199], v[20:23]
	v_mfma_f32_16x16x32_bf16 v[16:19], v[172:175], v[196:199], v[16:19]
	v_mfma_f32_16x16x32_bf16 v[12:15], v[164:167], v[204:207], v[12:15]
	v_mfma_f32_16x16x32_bf16 v[8:11], v[172:175], v[204:207], v[8:11]
	v_mfma_f32_16x16x32_bf16 v[4:7], v[164:167], v[212:215], v[4:7]
	v_mfma_f32_16x16x32_bf16 v[0:3], v[172:175], v[212:215], v[0:3]
	s_barrier
	s_setprio 0
	s_add_u32 s34, s34, 0x100
	s_addc_u32 s35, s35, 0
	s_add_u32 s79, s79, 0x100
	s_addc_u32 s80, s80, 0
	s_cmp_ge_i32 s81, s54
	s_mov_b32 s36, s81
	s_cbranch_scc0 .LBB0_675

.LBB0_772:
	ds_read_b128 v[128:131], v183
	ds_read_b128 v[132:135], v183 offset:1024
	ds_read_b128 v[136:139], v183 offset:2048
	ds_read_b128 v[140:143], v183 offset:3072
	ds_read_b128 v[160:163], v185
	ds_read_b128 v[164:167], v185 offset:1024
	ds_read_b128 v[168:171], v185 offset:2048
	ds_read_b128 v[190:193], v185 offset:3072
	s_add_i32 s80, s8, 2
	s_add_u32 s81, s0, 0x80
	s_addc_u32 s9, s1, 0
	s_cmp_eq_u32 s57, s8
	s_cselect_b32 s8, s38, s81
	s_cselect_b32 s9, s39, s9
	s_cselect_b32 s85, s41, s11
	s_cselect_b32 s84, s40, s10
	v_lshl_add_u64 v[172:173], s[0:1], 0, v[152:153]
	s_add_i32 m0, s44, 0xc000
	ds_read_b128 v[194:197], v187
	ds_read_b128 v[198:201], v187 offset:1024
	ds_read_b128 v[202:205], v187 offset:2048
	ds_read_b128 v[206:209], v187 offset:3072
	ds_read_b128 v[210:213], v187 offset:4096
	ds_read_b128 v[214:217], v187 offset:5120
	ds_read_b128 v[224:227], v187 offset:6144
	ds_read_b128 v[228:231], v187 offset:7168
	global_load_lds_dwordx4 v[172:173], off
	v_lshl_add_u64 v[172:173], s[0:1], 0, v[154:155]
	s_add_i32 m0, s44, 0xe000
	s_nop 0
	global_load_lds_dwordx4 v[172:173], off
	s_waitcnt vmcnt(8)
	s_waitcnt lgkmcnt(0)
	s_setprio 1
	s_barrier
	v_mfma_f32_16x16x32_bf16 v[124:127], v[128:131], v[194:197], v[124:127]
	v_mfma_f32_16x16x32_bf16 v[120:123], v[136:139], v[194:197], v[120:123]
	v_mfma_f32_16x16x32_bf16 v[116:119], v[128:131], v[202:205], v[116:119]
	v_mfma_f32_16x16x32_bf16 v[112:115], v[136:139], v[202:205], v[112:115]
	v_mfma_f32_16x16x32_bf16 v[108:111], v[128:131], v[210:213], v[108:111]
	v_mfma_f32_16x16x32_bf16 v[104:107], v[136:139], v[210:213], v[104:107]
	v_mfma_f32_16x16x32_bf16 v[100:103], v[128:131], v[224:227], v[100:103]
	v_mfma_f32_16x16x32_bf16 v[96:99], v[136:139], v[224:227], v[96:99]
	v_mfma_f32_16x16x32_bf16 v[124:127], v[132:135], v[198:201], v[124:127]
	v_mfma_f32_16x16x32_bf16 v[120:123], v[140:143], v[198:201], v[120:123]
	v_mfma_f32_16x16x32_bf16 v[116:119], v[132:135], v[206:209], v[116:119]
	v_mfma_f32_16x16x32_bf16 v[112:115], v[140:143], v[206:209], v[112:115]
	v_mfma_f32_16x16x32_bf16 v[108:111], v[132:135], v[214:217], v[108:111]
	v_mfma_f32_16x16x32_bf16 v[104:107], v[140:143], v[214:217], v[104:107]
	v_mfma_f32_16x16x32_bf16 v[100:103], v[132:135], v[228:231], v[100:103]
	v_mfma_f32_16x16x32_bf16 v[96:99], v[140:143], v[228:231], v[96:99]
	v_mfma_f32_16x16x32_bf16 v[60:63], v[160:163], v[194:197], v[60:63]
	v_mfma_f32_16x16x32_bf16 v[56:59], v[168:171], v[194:197], v[56:59]
	v_mfma_f32_16x16x32_bf16 v[52:55], v[160:163], v[202:205], v[52:55]
	v_mfma_f32_16x16x32_bf16 v[48:51], v[168:171], v[202:205], v[48:51]
	v_mfma_f32_16x16x32_bf16 v[44:47], v[160:163], v[210:213], v[44:47]
	v_mfma_f32_16x16x32_bf16 v[40:43], v[168:171], v[210:213], v[40:43]
	v_mfma_f32_16x16x32_bf16 v[36:39], v[160:163], v[224:227], v[36:39]
	v_mfma_f32_16x16x32_bf16 v[32:35], v[168:171], v[224:227], v[32:35]
	v_mfma_f32_16x16x32_bf16 v[60:63], v[164:167], v[198:201], v[60:63]
	v_mfma_f32_16x16x32_bf16 v[56:59], v[190:193], v[198:201], v[56:59]
	v_mfma_f32_16x16x32_bf16 v[52:55], v[164:167], v[206:209], v[52:55]
	v_mfma_f32_16x16x32_bf16 v[48:51], v[190:193], v[206:209], v[48:51]
	v_mfma_f32_16x16x32_bf16 v[44:47], v[164:167], v[214:217], v[44:47]
	v_mfma_f32_16x16x32_bf16 v[40:43], v[190:193], v[214:217], v[40:43]
	v_mfma_f32_16x16x32_bf16 v[36:39], v[164:167], v[228:231], v[36:39]
	v_mfma_f32_16x16x32_bf16 v[32:35], v[190:193], v[228:231], v[32:35]
	s_barrier
	s_setprio 0
	s_add_i32 s81, s60, s43
	v_lshl_add_u64 v[172:173], s[84:85], 0, v[146:147]
	s_mov_b32 m0, s81
	ds_read_b128 v[194:197], v187 offset:16384
	ds_read_b128 v[198:201], v187 offset:17408
	ds_read_b128 v[202:205], v187 offset:18432
	ds_read_b128 v[206:209], v187 offset:19456
	ds_read_b128 v[210:213], v187 offset:20480
	ds_read_b128 v[214:217], v187 offset:21504
	ds_read_b128 v[224:227], v187 offset:22528
	ds_read_b128 v[228:231], v187 offset:23552
	global_load_lds_dwordx4 v[172:173], off
	s_add_i32 m0, s81, 0x2000
	v_lshl_add_u64 v[178:179], s[84:85], 0, v[150:151]
	s_add_u32 s84, s84, s14
	s_addc_u32 s85, s85, s15
	s_add_i32 s81, s61, s43
	global_load_lds_dwordx4 v[178:179], off
	v_lshl_add_u64 v[218:219], s[84:85], 0, v[146:147]
	s_mov_b32 m0, s81
	v_lshl_add_u64 v[232:233], s[84:85], 0, v[150:151]
	global_load_lds_dwordx4 v[218:219], off
	s_add_i32 m0, s81, 0x2000
	v_lshl_add_u64 v[234:235], s[8:9], 0, v[144:145]
	global_load_lds_dwordx4 v[232:233], off
	s_mov_b32 m0, s44
	v_lshl_add_u64 v[236:237], s[8:9], 0, v[148:149]
	global_load_lds_dwordx4 v[234:235], off
	s_mov_b32 m0, s45
	s_nop 0
	global_load_lds_dwordx4 v[236:237], off
	s_waitcnt vmcnt(8)
	s_waitcnt lgkmcnt(0)
	s_setprio 1
	s_barrier
	v_mfma_f32_16x16x32_bf16 v[92:95], v[128:131], v[194:197], v[92:95]
	v_mfma_f32_16x16x32_bf16 v[88:91], v[136:139], v[194:197], v[88:91]
	v_mfma_f32_16x16x32_bf16 v[84:87], v[128:131], v[202:205], v[84:87]
	v_mfma_f32_16x16x32_bf16 v[80:83], v[136:139], v[202:205], v[80:83]
	v_mfma_f32_16x16x32_bf16 v[76:79], v[128:131], v[210:213], v[76:79]
	v_mfma_f32_16x16x32_bf16 v[72:75], v[136:139], v[210:213], v[72:75]
	v_mfma_f32_16x16x32_bf16 v[68:71], v[128:131], v[224:227], v[68:71]
	v_mfma_f32_16x16x32_bf16 v[64:67], v[136:139], v[224:227], v[64:67]
	v_mfma_f32_16x16x32_bf16 v[92:95], v[132:135], v[198:201], v[92:95]
	v_mfma_f32_16x16x32_bf16 v[88:91], v[140:143], v[198:201], v[88:91]
	v_mfma_f32_16x16x32_bf16 v[84:87], v[132:135], v[206:209], v[84:87]
	v_mfma_f32_16x16x32_bf16 v[80:83], v[140:143], v[206:209], v[80:83]
	v_mfma_f32_16x16x32_bf16 v[76:79], v[132:135], v[214:217], v[76:79]
	v_mfma_f32_16x16x32_bf16 v[72:75], v[140:143], v[214:217], v[72:75]
	v_mfma_f32_16x16x32_bf16 v[68:71], v[132:135], v[228:231], v[68:71]
	v_mfma_f32_16x16x32_bf16 v[64:67], v[140:143], v[228:231], v[64:67]
	v_mfma_f32_16x16x32_bf16 v[28:31], v[160:163], v[194:197], v[28:31]
	v_mfma_f32_16x16x32_bf16 v[24:27], v[168:171], v[194:197], v[24:27]
	v_mfma_f32_16x16x32_bf16 v[20:23], v[160:163], v[202:205], v[20:23]
	v_mfma_f32_16x16x32_bf16 v[16:19], v[168:171], v[202:205], v[16:19]
	v_mfma_f32_16x16x32_bf16 v[12:15], v[160:163], v[210:213], v[12:15]
	v_mfma_f32_16x16x32_bf16 v[8:11], v[168:171], v[210:213], v[8:11]
	v_mfma_f32_16x16x32_bf16 v[4:7], v[160:163], v[224:227], v[4:7]
	v_mfma_f32_16x16x32_bf16 v[0:3], v[168:171], v[224:227], v[0:3]
	v_mfma_f32_16x16x32_bf16 v[28:31], v[164:167], v[198:201], v[28:31]
	v_mfma_f32_16x16x32_bf16 v[24:27], v[190:193], v[198:201], v[24:27]
	v_mfma_f32_16x16x32_bf16 v[20:23], v[164:167], v[206:209], v[20:23]
	v_mfma_f32_16x16x32_bf16 v[16:19], v[190:193], v[206:209], v[16:19]
	v_mfma_f32_16x16x32_bf16 v[12:15], v[164:167], v[214:217], v[12:15]
	v_mfma_f32_16x16x32_bf16 v[8:11], v[190:193], v[214:217], v[8:11]
	v_mfma_f32_16x16x32_bf16 v[4:7], v[164:167], v[228:231], v[4:7]
	v_mfma_f32_16x16x32_bf16 v[0:3], v[190:193], v[228:231], v[0:3]
	s_barrier
	s_setprio 0
	s_add_i32 s81, 0, 0x18000
	s_add_i32 s84, 0, 0x1c000
	v_add_u32_e32 v140, s81, v177
	v_add_u32_e32 v174, s84, v177
	ds_read_b128 v[128:131], v140
	ds_read_b128 v[132:135], v140 offset:1024
	ds_read_b128 v[136:139], v140 offset:2048
	ds_read_b128 v[140:143], v140 offset:3072
	ds_read_b128 v[160:163], v174
	ds_read_b128 v[164:167], v174 offset:1024
	ds_read_b128 v[168:171], v174 offset:2048
	ds_read_b128 v[190:193], v174 offset:3072
	s_add_u32 s8, s8, s14
	s_addc_u32 s9, s9, s15
	s_mov_b32 m0, s47
	v_lshl_add_u64 v[238:239], s[8:9], 0, v[144:145]
	ds_read_b128 v[194:197], v187 offset:32768
	ds_read_b128 v[198:201], v187 offset:33792
	ds_read_b128 v[202:205], v187 offset:34816
	ds_read_b128 v[206:209], v187 offset:35840
	ds_read_b128 v[210:213], v187 offset:36864
	ds_read_b128 v[214:217], v187 offset:37888
	ds_read_b128 v[224:227], v187 offset:38912
	ds_read_b128 v[228:231], v187 offset:39936
	global_load_lds_dwordx4 v[238:239], off
	v_lshl_add_u64 v[238:239], s[8:9], 0, v[148:149]
	s_mov_b32 m0, s48
	s_nop 0
	global_load_lds_dwordx4 v[238:239], off
	s_waitcnt vmcnt(8)
	s_waitcnt lgkmcnt(0)
	s_setprio 1
	s_barrier
	v_mfma_f32_16x16x32_bf16 v[124:127], v[128:131], v[194:197], v[124:127]
	v_mfma_f32_16x16x32_bf16 v[120:123], v[136:139], v[194:197], v[120:123]
	v_mfma_f32_16x16x32_bf16 v[116:119], v[128:131], v[202:205], v[116:119]
	v_mfma_f32_16x16x32_bf16 v[112:115], v[136:139], v[202:205], v[112:115]
	v_mfma_f32_16x16x32_bf16 v[108:111], v[128:131], v[210:213], v[108:111]
	v_mfma_f32_16x16x32_bf16 v[104:107], v[136:139], v[210:213], v[104:107]
	v_mfma_f32_16x16x32_bf16 v[100:103], v[128:131], v[224:227], v[100:103]
	v_mfma_f32_16x16x32_bf16 v[96:99], v[136:139], v[224:227], v[96:99]
	v_mfma_f32_16x16x32_bf16 v[124:127], v[132:135], v[198:201], v[124:127]
	v_mfma_f32_16x16x32_bf16 v[120:123], v[140:143], v[198:201], v[120:123]
	v_mfma_f32_16x16x32_bf16 v[116:119], v[132:135], v[206:209], v[116:119]
	v_mfma_f32_16x16x32_bf16 v[112:115], v[140:143], v[206:209], v[112:115]
	v_mfma_f32_16x16x32_bf16 v[108:111], v[132:135], v[214:217], v[108:111]
	v_mfma_f32_16x16x32_bf16 v[104:107], v[140:143], v[214:217], v[104:107]
	v_mfma_f32_16x16x32_bf16 v[100:103], v[132:135], v[228:231], v[100:103]
	v_mfma_f32_16x16x32_bf16 v[96:99], v[140:143], v[228:231], v[96:99]
	v_mfma_f32_16x16x32_bf16 v[60:63], v[160:163], v[194:197], v[60:63]
	v_mfma_f32_16x16x32_bf16 v[56:59], v[168:171], v[194:197], v[56:59]
	v_mfma_f32_16x16x32_bf16 v[52:55], v[160:163], v[202:205], v[52:55]
	v_mfma_f32_16x16x32_bf16 v[48:51], v[168:171], v[202:205], v[48:51]
	v_mfma_f32_16x16x32_bf16 v[44:47], v[160:163], v[210:213], v[44:47]
	v_mfma_f32_16x16x32_bf16 v[40:43], v[168:171], v[210:213], v[40:43]
	v_mfma_f32_16x16x32_bf16 v[36:39], v[160:163], v[224:227], v[36:39]
	v_mfma_f32_16x16x32_bf16 v[32:35], v[168:171], v[224:227], v[32:35]
	v_mfma_f32_16x16x32_bf16 v[60:63], v[164:167], v[198:201], v[60:63]
	v_mfma_f32_16x16x32_bf16 v[56:59], v[190:193], v[198:201], v[56:59]
	v_mfma_f32_16x16x32_bf16 v[52:55], v[164:167], v[206:209], v[52:55]
	v_mfma_f32_16x16x32_bf16 v[48:51], v[190:193], v[206:209], v[48:51]
	v_mfma_f32_16x16x32_bf16 v[44:47], v[164:167], v[214:217], v[44:47]
	v_mfma_f32_16x16x32_bf16 v[40:43], v[190:193], v[214:217], v[40:43]
	v_mfma_f32_16x16x32_bf16 v[36:39], v[164:167], v[228:231], v[36:39]
	v_mfma_f32_16x16x32_bf16 v[32:35], v[190:193], v[228:231], v[32:35]
	s_barrier
	s_setprio 0
	s_add_i32 s8, s81, s43
	v_lshl_add_u64 v[172:173], v[172:173], 0, s[28:29]
	s_mov_b32 m0, s8
	ds_read_b128 v[194:197], v187 offset:49152
	ds_read_b128 v[198:201], v187 offset:50176
	ds_read_b128 v[202:205], v187 offset:51200
	ds_read_b128 v[206:209], v187 offset:52224
	ds_read_b128 v[210:213], v187 offset:53248
	ds_read_b128 v[214:217], v187 offset:54272
	ds_read_b128 v[224:227], v187 offset:55296
	ds_read_b128 v[228:231], v187 offset:56320
	global_load_lds_dwordx4 v[172:173], off
	v_lshl_add_u64 v[172:173], v[178:179], 0, s[28:29]
	s_add_i32 m0, s8, 0x2000
	s_add_i32 s8, s84, s43
	global_load_lds_dwordx4 v[172:173], off
	v_lshl_add_u64 v[172:173], v[218:219], 0, s[28:29]
	s_mov_b32 m0, s8
	s_nop 0
	global_load_lds_dwordx4 v[172:173], off
	v_lshl_add_u64 v[172:173], v[232:233], 0, s[28:29]
	s_add_i32 m0, s8, 0x2000
	s_nop 0
	global_load_lds_dwordx4 v[172:173], off
	v_lshl_add_u64 v[172:173], v[234:235], 0, s[28:29]
	s_mov_b32 m0, s54
	s_nop 0
	global_load_lds_dwordx4 v[172:173], off
	v_lshl_add_u64 v[172:173], v[236:237], 0, s[28:29]
	s_mov_b32 m0, s55
	s_nop 0
	global_load_lds_dwordx4 v[172:173], off
	s_waitcnt vmcnt(8)
	s_waitcnt lgkmcnt(0)
	s_setprio 1
	s_barrier
	v_mfma_f32_16x16x32_bf16 v[92:95], v[128:131], v[194:197], v[92:95]
	v_mfma_f32_16x16x32_bf16 v[88:91], v[136:139], v[194:197], v[88:91]
	v_mfma_f32_16x16x32_bf16 v[84:87], v[128:131], v[202:205], v[84:87]
	v_mfma_f32_16x16x32_bf16 v[80:83], v[136:139], v[202:205], v[80:83]
	v_mfma_f32_16x16x32_bf16 v[76:79], v[128:131], v[210:213], v[76:79]
	v_mfma_f32_16x16x32_bf16 v[72:75], v[136:139], v[210:213], v[72:75]
	v_mfma_f32_16x16x32_bf16 v[68:71], v[128:131], v[224:227], v[68:71]
	v_mfma_f32_16x16x32_bf16 v[64:67], v[136:139], v[224:227], v[64:67]
	v_mfma_f32_16x16x32_bf16 v[92:95], v[132:135], v[198:201], v[92:95]
	v_mfma_f32_16x16x32_bf16 v[88:91], v[140:143], v[198:201], v[88:91]
	v_mfma_f32_16x16x32_bf16 v[84:87], v[132:135], v[206:209], v[84:87]
	v_mfma_f32_16x16x32_bf16 v[80:83], v[140:143], v[206:209], v[80:83]
	v_mfma_f32_16x16x32_bf16 v[76:79], v[132:135], v[214:217], v[76:79]
	v_mfma_f32_16x16x32_bf16 v[72:75], v[140:143], v[214:217], v[72:75]
	v_mfma_f32_16x16x32_bf16 v[68:71], v[132:135], v[228:231], v[68:71]
	v_mfma_f32_16x16x32_bf16 v[64:67], v[140:143], v[228:231], v[64:67]
	v_mfma_f32_16x16x32_bf16 v[28:31], v[160:163], v[194:197], v[28:31]
	v_mfma_f32_16x16x32_bf16 v[24:27], v[168:171], v[194:197], v[24:27]
	v_mfma_f32_16x16x32_bf16 v[20:23], v[160:163], v[202:205], v[20:23]
	v_mfma_f32_16x16x32_bf16 v[16:19], v[168:171], v[202:205], v[16:19]
	v_mfma_f32_16x16x32_bf16 v[12:15], v[160:163], v[210:213], v[12:15]
	v_mfma_f32_16x16x32_bf16 v[8:11], v[168:171], v[210:213], v[8:11]
	v_mfma_f32_16x16x32_bf16 v[4:7], v[160:163], v[224:227], v[4:7]
	v_mfma_f32_16x16x32_bf16 v[0:3], v[168:171], v[224:227], v[0:3]
	v_mfma_f32_16x16x32_bf16 v[28:31], v[164:167], v[198:201], v[28:31]
	v_mfma_f32_16x16x32_bf16 v[24:27], v[190:193], v[198:201], v[24:27]
	v_mfma_f32_16x16x32_bf16 v[20:23], v[164:167], v[206:209], v[20:23]
	v_mfma_f32_16x16x32_bf16 v[16:19], v[190:193], v[206:209], v[16:19]
	v_mfma_f32_16x16x32_bf16 v[12:15], v[164:167], v[214:217], v[12:15]
	v_mfma_f32_16x16x32_bf16 v[8:11], v[190:193], v[214:217], v[8:11]
	v_mfma_f32_16x16x32_bf16 v[4:7], v[164:167], v[228:231], v[4:7]
	v_mfma_f32_16x16x32_bf16 v[0:3], v[190:193], v[228:231], v[0:3]
	s_barrier
	s_setprio 0
	s_add_u32 s0, s0, 0x100
	s_addc_u32 s1, s1, 0
	s_add_u32 s10, s10, 0x100
	s_addc_u32 s11, s11, 0
	s_cmp_ge_i32 s80, s56
	s_mov_b32 s8, s80
	s_cbranch_scc0 .LBB0_772

.LBB0_775:
	v_lshl_add_u32 v202, s79, 8, v175
	v_ashrrev_i32_e32 v203, 31, v202
	v_lshl_add_u64 v[128:129], v[202:203], 3, s[20:21]
	global_load_dwordx2 v[128:129], v[128:129], off
	v_or_b32_e32 v200, 16, v202
	v_or_b32_e32 v198, 32, v202
	v_ashrrev_i32_e32 v201, 31, v200
	v_ashrrev_i32_e32 v199, 31, v198
	v_lshl_add_u64 v[130:131], v[200:201], 3, s[20:21]
	v_lshl_add_u64 v[132:133], v[198:199], 3, s[20:21]
	global_load_dwordx2 v[130:131], v[130:131], off
	s_nop 0
	global_load_dwordx2 v[132:133], v[132:133], off
	v_or_b32_e32 v196, 48, v202
	v_add_u32_e32 v194, 0x80, v202
	v_ashrrev_i32_e32 v197, 31, v196
	v_ashrrev_i32_e32 v195, 31, v194
	v_lshl_add_u64 v[134:135], v[196:197], 3, s[20:21]
	v_lshl_add_u64 v[136:137], v[194:195], 3, s[20:21]
	global_load_dwordx2 v[134:135], v[134:135], off
	s_nop 0
	global_load_dwordx2 v[136:137], v[136:137], off
	v_add_u32_e32 v192, 0x90, v202
	v_ashrrev_i32_e32 v193, 31, v192
	v_add_u32_e32 v206, 0xa0, v202
	v_ashrrev_i32_e32 v207, 31, v206
	v_add_u32_e32 v204, 0xb0, v202
	v_ashrrev_i32_e32 v205, 31, v204
	v_lshl_or_b32 v208, s78, 8, v181
	v_ashrrev_i32_e32 v209, 31, v208
	v_lshlrev_b32_e32 v252, 3, v192
	v_lshlrev_b32_e32 v253, 3, v206
	v_lshlrev_b32_e32 v254, 3, v204
	v_lshlrev_b32_e32 v255, 2, v208
	global_load_dword v252, v252, s[20:21]
	global_load_dword v253, v253, s[20:21]
	global_load_dword v254, v254, s[20:21]
	global_load_dword v252, v255, s[82:83]
	global_load_dword v253, v255, s[26:27]
	s_waitcnt vmcnt(0)
	v_pk_mul_f32 v[166:167], v[128:129], s[36:37] op_sel_hi:[1,0]
	s_nop 0
	v_fma_f32 v128, -v166, v166, v167
	v_max_f32_e32 v128, 0, v128
	v_add_f32_e32 v128, 0x3727c5ac, v128
	v_cmp_gt_f32_e32 vcc, s63, v128
	v_pk_mul_f32 v[162:163], v[130:131], s[36:37] op_sel_hi:[1,0]
	v_pk_mul_f32 v[160:161], v[132:133], s[36:37] op_sel_hi:[1,0]
	v_fma_f32 v129, -v162, v162, v163
	v_fma_f32 v130, -v160, v160, v161
	v_max_f32_e32 v129, 0, v129
	v_mul_f32_e32 v131, 0x4f800000, v128
	v_max_f32_e32 v130, 0, v130
	v_add_f32_e32 v129, 0x3727c5ac, v129
	v_cndmask_b32_e32 v128, v128, v131, vcc
	v_add_f32_e32 v130, 0x3727c5ac, v130
	v_mul_f32_e32 v131, 0x4f800000, v129
	v_sqrt_f32_e32 v133, v128
	v_cmp_gt_f32_e64 s[0:1], s63, v129
	v_mul_f32_e32 v132, 0x4f800000, v130
	v_cmp_gt_f32_e64 s[8:9], s63, v130
	v_cndmask_b32_e64 v129, v129, v131, s[0:1]
	v_sqrt_f32_e32 v131, v129
	v_cndmask_b32_e64 v130, v130, v132, s[8:9]
	v_sqrt_f32_e32 v132, v130
	v_add_u32_e32 v138, -1, v133
	v_add_u32_e32 v139, 1, v133
	v_fma_f32 v140, -v138, v133, v128
	v_fma_f32 v141, -v139, v133, v128
	v_add_u32_e32 v142, -1, v131
	v_cmp_ge_f32_e64 s[10:11], 0, v140
	v_add_u32_e32 v164, -1, v132
	v_add_u32_e32 v143, 1, v131
	v_cndmask_b32_e64 v133, v133, v138, s[10:11]
	v_fma_f32 v138, -v142, v131, v129
	v_cmp_lt_f32_e64 s[10:11], 0, v141
	v_fma_f32 v168, -v164, v132, v130
	v_add_u32_e32 v165, 1, v132
	v_cndmask_b32_e64 v133, v133, v139, s[10:11]
	v_cmp_ge_f32_e64 s[10:11], 0, v138
	v_fma_f32 v140, -v143, v131, v129
	v_fma_f32 v169, -v165, v132, v130
	v_cndmask_b32_e64 v131, v131, v142, s[10:11]
	v_cmp_ge_f32_e64 s[10:11], 0, v168
	v_mul_f32_e32 v138, 0x37800000, v133
	v_cndmask_b32_e32 v133, v133, v138, vcc
	v_cndmask_b32_e64 v132, v132, v164, s[10:11]
	v_cmp_lt_f32_e64 s[10:11], 0, v140
	v_cmp_class_f32_e32 vcc, v128, v189
	v_pk_mul_f32 v[170:171], v[136:137], s[36:37] op_sel_hi:[1,0]
	v_cndmask_b32_e64 v131, v131, v143, s[10:11]
	v_cmp_lt_f32_e64 s[10:11], 0, v169
	v_mul_f32_e32 v138, 0x37800000, v131
	v_cndmask_b32_e32 v128, v133, v128, vcc
	v_cndmask_b32_e64 v132, v132, v165, s[10:11]
	v_cndmask_b32_e64 v131, v131, v138, s[0:1]
	v_div_scale_f32 v133, s[0:1], v128, v128, 1.0
	v_mul_f32_e32 v139, 0x37800000, v132
	v_cmp_class_f32_e64 s[0:1], v129, v189
	v_cndmask_b32_e64 v132, v132, v139, s[8:9]
	v_div_scale_f32 v138, vcc, 1.0, v128, 1.0
	v_cndmask_b32_e64 v129, v131, v129, s[0:1]
	v_cmp_class_f32_e64 s[0:1], v130, v189
	v_rcp_f32_e32 v131, v133
	s_nop 0
	v_cndmask_b32_e64 v130, v132, v130, s[0:1]
	v_div_scale_f32 v132, s[0:1], v129, v129, 1.0
	v_div_scale_f32 v140, s[8:9], v130, v130, 1.0
	v_rcp_f32_e32 v141, v132
	v_rcp_f32_e32 v142, v140
	v_fma_f32 v143, -v133, v131, 1.0
	v_fmac_f32_e32 v131, v143, v131
	v_fma_f32 v143, -v132, v141, 1.0
	v_div_scale_f32 v139, s[0:1], 1.0, v129, 1.0
	v_fma_f32 v164, -v140, v142, 1.0
	v_mul_f32_e32 v165, v138, v131
	v_fmac_f32_e32 v141, v143, v141
	v_fmac_f32_e32 v142, v164, v142
	v_fma_f32 v143, -v133, v165, v138
	v_mul_f32_e32 v164, v139, v141
	v_fmac_f32_e32 v165, v143, v131
	v_fma_f32 v143, -v132, v164, v139
	v_fma_f32 v133, -v133, v165, v138
	v_fmac_f32_e32 v164, v143, v141
	v_div_fmas_f32 v131, v133, v131, v165
	v_fma_f32 v132, -v132, v164, v139
	s_mov_b64 vcc, s[0:1]
	v_div_fixup_f32 v184, v131, v128, 1.0
	v_div_fmas_f32 v128, v132, v141, v164
	v_div_fixup_f32 v176, v128, v129, 1.0
	v_lshl_add_u64 v[128:129], v[192:193], 3, s[20:21]
	global_load_dwordx2 v[128:129], v[128:129], off
	v_pk_mul_f32 v[164:165], v[134:135], s[36:37] op_sel_hi:[1,0]
	v_div_scale_f32 v131, vcc, 1.0, v130, 1.0
	v_fma_f32 v133, -v164, v164, v165
	v_max_f32_e32 v133, 0, v133
	v_add_f32_e32 v133, 0x3727c5ac, v133
	v_mul_f32_e32 v134, 0x4f800000, v133
	v_cmp_gt_f32_e64 s[0:1], s63, v133
	v_mul_f32_e32 v132, v131, v142
	v_fma_f32 v135, -v140, v132, v131
	v_cndmask_b32_e64 v133, v133, v134, s[0:1]
	v_sqrt_f32_e32 v134, v133
	v_fmac_f32_e32 v132, v135, v142
	v_fma_f32 v131, -v140, v132, v131
	v_div_fmas_f32 v131, v131, v142, v132
	v_add_u32_e32 v135, -1, v134
	v_fma_f32 v138, -v135, v134, v133
	v_cmp_ge_f32_e64 s[8:9], 0, v138
	v_add_u32_e32 v138, 1, v134
	v_div_fixup_f32 v174, v131, v130, 1.0
	v_cndmask_b32_e64 v135, v134, v135, s[8:9]
	v_fma_f32 v134, -v138, v134, v133
	v_cmp_lt_f32_e64 s[8:9], 0, v134
	s_nop 1
	v_cndmask_b32_e64 v134, v135, v138, s[8:9]
	v_mul_f32_e32 v135, 0x37800000, v134
	v_cndmask_b32_e64 v134, v134, v135, s[0:1]
	v_cmp_class_f32_e64 s[0:1], v133, v189
	s_nop 1
	v_cndmask_b32_e64 v133, v134, v133, s[0:1]
	v_div_scale_f32 v134, s[0:1], v133, v133, 1.0
	v_rcp_f32_e32 v135, v134
	v_div_scale_f32 v132, vcc, 1.0, v133, 1.0
	v_fma_f32 v130, -v134, v135, 1.0
	v_fmac_f32_e32 v135, v130, v135
	v_lshl_add_u64 v[130:131], v[206:207], 3, s[20:21]
	global_load_dwordx2 v[172:173], v[130:131], off
	v_lshl_add_u64 v[130:131], v[204:205], 3, s[20:21]
	global_load_dwordx2 v[210:211], v[130:131], off
	v_fma_f32 v130, -v170, v170, v171
	v_max_f32_e32 v130, 0, v130
	v_add_f32_e32 v130, 0x3727c5ac, v130
	v_mul_f32_e32 v131, 0x4f800000, v130
	v_cmp_gt_f32_e64 s[0:1], s63, v130
	v_mul_f32_e32 v138, v132, v135
	v_fma_f32 v136, -v134, v138, v132
	v_cndmask_b32_e64 v130, v130, v131, s[0:1]
	v_sqrt_f32_e32 v131, v130
	v_fmac_f32_e32 v138, v136, v135
	v_fma_f32 v132, -v134, v138, v132
	v_div_fmas_f32 v132, v132, v135, v138
	v_add_u32_e32 v134, -1, v131
	v_fma_f32 v136, -v134, v131, v130
	v_cmp_ge_f32_e64 s[8:9], 0, v136
	v_add_u32_e32 v136, 1, v131
	v_div_fixup_f32 v186, v132, v133, 1.0
	v_cndmask_b32_e64 v134, v131, v134, s[8:9]
	v_fma_f32 v131, -v136, v131, v130
	v_cmp_lt_f32_e64 s[8:9], 0, v131
	s_waitcnt vmcnt(0)
	v_pk_mul_f32 v[168:169], v[128:129], s[36:37] op_sel_hi:[1,0]
	v_cndmask_b32_e64 v131, v134, v136, s[8:9]
	v_mul_f32_e32 v134, 0x37800000, v131
	v_cndmask_b32_e64 v131, v131, v134, s[0:1]
	v_cmp_class_f32_e64 s[0:1], v130, v189
	v_fma_f32 v128, -v168, v168, v169
	v_max_f32_e32 v128, 0, v128
	v_cndmask_b32_e64 v130, v131, v130, s[0:1]
	v_div_scale_f32 v131, s[0:1], v130, v130, 1.0
	v_rcp_f32_e32 v134, v131
	v_add_f32_e32 v128, 0x3727c5ac, v128
	v_mul_f32_e32 v129, 0x4f800000, v128
	v_cmp_gt_f32_e64 s[0:1], s63, v128
	v_fma_f32 v132, -v131, v134, 1.0
	v_fmac_f32_e32 v134, v132, v134
	v_cndmask_b32_e64 v128, v128, v129, s[0:1]
	v_div_scale_f32 v132, vcc, 1.0, v130, 1.0
	v_sqrt_f32_e32 v129, v128
	v_mul_f32_e32 v133, v132, v134
	v_fma_f32 v135, -v131, v133, v132
	v_fmac_f32_e32 v133, v135, v134
	v_fma_f32 v131, -v131, v133, v132
	v_add_u32_e32 v132, -1, v129
	v_fma_f32 v135, -v132, v129, v128
	v_cmp_ge_f32_e64 s[8:9], 0, v135
	v_add_u32_e32 v135, 1, v129
	v_pk_mul_f32 v[178:179], v[172:173], s[36:37] op_sel_hi:[1,0]
	v_cndmask_b32_e64 v132, v129, v132, s[8:9]
	v_fma_f32 v129, -v135, v129, v128
	v_cmp_lt_f32_e64 s[8:9], 0, v129
	v_fma_f32 v172, -v178, v178, v179
	v_max_f32_e32 v172, 0, v172
	v_cndmask_b32_e64 v129, v132, v135, s[8:9]
	v_mul_f32_e32 v132, 0x37800000, v129
	v_cndmask_b32_e64 v129, v129, v132, s[0:1]
	v_cmp_class_f32_e64 s[0:1], v128, v189
	v_add_f32_e32 v172, 0x3727c5ac, v172
	v_mul_f32_e32 v173, 0x4f800000, v172
	v_cndmask_b32_e64 v180, v129, v128, s[0:1]
	v_div_scale_f32 v188, s[0:1], v180, v180, 1.0
	v_rcp_f32_e32 v190, v188
	v_div_fmas_f32 v128, v131, v134, v133
	v_lshlrev_b64 v[132:133], 2, v[208:209]
	v_div_fixup_f32 v182, v128, v130, 1.0
	v_fma_f32 v128, -v188, v190, 1.0
	v_lshl_add_u64 v[134:135], s[82:83], 0, v[132:133]
	v_fmac_f32_e32 v190, v128, v190
	global_load_dwordx4 v[128:131], v[134:135], off offset:16
	global_load_dwordx4 v[140:143], v[134:135], off
	v_lshl_add_u64 v[136:137], s[26:27], 0, v[132:133]
	global_load_dwordx4 v[132:135], v[136:137], off offset:16
	s_nop 0
	global_load_dwordx4 v[136:139], v[136:137], off
	v_cmp_gt_f32_e64 s[0:1], s63, v172
	v_div_scale_f32 v191, vcc, 1.0, v180, 1.0
	s_nop 0
	v_cndmask_b32_e64 v172, v172, v173, s[0:1]
	v_sqrt_f32_e32 v173, v172
	v_mul_f32_e32 v212, v191, v190
	v_fma_f32 v213, -v188, v212, v191
	v_fmac_f32_e32 v212, v213, v190
	v_fma_f32 v188, -v188, v212, v191
	v_add_u32_e32 v191, -1, v173
	v_fma_f32 v213, -v191, v173, v172
	v_cmp_ge_f32_e64 s[8:9], 0, v213
	v_add_u32_e32 v213, 1, v173
	s_waitcnt vmcnt(0)
	v_pk_fma_f32 v[120:121], v[166:167], v[128:129], v[120:121] op_sel_hi:[0,1,1] neg_lo:[1,0,0] neg_hi:[1,0,0]
	v_cndmask_b32_e64 v191, v173, v191, s[8:9]
	v_fma_f32 v173, -v213, v173, v172
	v_cmp_lt_f32_e64 s[8:9], 0, v173
	v_pk_fma_f32 v[124:125], v[166:167], v[140:141], v[124:125] op_sel_hi:[0,1,1] neg_lo:[1,0,0] neg_hi:[1,0,0]
	v_pk_fma_f32 v[126:127], v[166:167], v[142:143], v[126:127] op_sel_hi:[0,1,1] neg_lo:[1,0,0] neg_hi:[1,0,0]
	v_cndmask_b32_e64 v173, v191, v213, s[8:9]
	v_mul_f32_e32 v191, 0x37800000, v173
	v_cndmask_b32_e64 v173, v173, v191, s[0:1]
	v_cmp_class_f32_e64 s[0:1], v172, v189
	v_pk_fma_f32 v[126:127], v[184:185], v[126:127], v[138:139] op_sel_hi:[0,1,1]
	v_pk_fma_f32 v[124:125], v[184:185], v[124:125], v[136:137] op_sel_hi:[0,1,1]
	v_cndmask_b32_e64 v191, v173, v172, s[0:1]
	v_div_scale_f32 v213, s[0:1], v191, v191, 1.0
	v_rcp_f32_e32 v214, v213
	v_div_fmas_f32 v172, v188, v190, v212
	v_div_fixup_f32 v190, v172, v180, 1.0
	v_div_scale_f32 v180, vcc, 1.0, v191, 1.0
	v_fma_f32 v172, -v213, v214, 1.0
	v_fmac_f32_e32 v214, v172, v214
	v_pk_mul_f32 v[172:173], v[210:211], s[36:37] op_sel_hi:[1,0]
	v_mul_f32_e32 v188, v180, v214
	v_fma_f32 v210, -v172, v172, v173
	v_max_f32_e32 v210, 0, v210
	v_add_f32_e32 v210, 0x3727c5ac, v210
	v_mul_f32_e32 v211, 0x4f800000, v210
	v_cmp_gt_f32_e64 s[0:1], s63, v210
	v_fma_f32 v212, -v213, v188, v180
	v_fmac_f32_e32 v188, v212, v214
	v_cndmask_b32_e64 v210, v210, v211, s[0:1]
	v_sqrt_f32_e32 v211, v210
	v_fma_f32 v180, -v213, v188, v180
	v_pk_fma_f32 v[122:123], v[166:167], v[130:131], v[122:123] op_sel_hi:[0,1,1] neg_lo:[1,0,0] neg_hi:[1,0,0]
	v_pk_fma_f32 v[120:121], v[184:185], v[120:121], v[132:133] op_sel_hi:[0,1,1]
	v_add_u32_e32 v212, -1, v211
	v_fma_f32 v213, -v212, v211, v210
	v_cmp_ge_f32_e64 s[8:9], 0, v213
	v_add_u32_e32 v213, 1, v211
	v_pk_fma_f32 v[122:123], v[184:185], v[122:123], v[134:135] op_sel_hi:[0,1,1]
	v_cndmask_b32_e64 v212, v211, v212, s[8:9]
	v_fma_f32 v211, -v213, v211, v210
	v_cmp_lt_f32_e64 s[8:9], 0, v211
	v_max_f32_e32 v124, 0, v124
	v_max_f32_e32 v120, 0, v120
	v_cndmask_b32_e64 v211, v212, v213, s[8:9]
	v_max_f32_e32 v125, 0, v125
	v_max_f32_e32 v121, 0, v121
	v_max_f32_e32 v126, 0, v126
	v_max_f32_e32 v127, 0, v127
	v_mul_f32_e32 v212, 0x37800000, v211
	v_pk_mul_f32 v[124:125], v[124:125], v[124:125]
	v_pk_mul_f32 v[120:121], v[120:121], v[120:121]
	v_max_f32_e32 v122, 0, v122
	v_max_f32_e32 v123, 0, v123
	v_pk_mul_f32 v[126:127], v[126:127], v[126:127]
	v_pk_fma_f32 v[116:117], v[162:163], v[140:141], v[116:117] op_sel_hi:[0,1,1] neg_lo:[1,0,0] neg_hi:[1,0,0]
	v_pk_fma_f32 v[112:113], v[162:163], v[128:129], v[112:113] op_sel_hi:[0,1,1] neg_lo:[1,0,0] neg_hi:[1,0,0]
	v_cndmask_b32_e64 v211, v211, v212, s[0:1]
	v_cmp_class_f32_e64 s[0:1], v210, v189
	v_pk_mul_f32 v[122:123], v[122:123], v[122:123]
	v_cvt_pk_bf16_f32 v124, v124, v125
	v_cvt_pk_bf16_f32 v125, v126, v127
	v_cvt_pk_bf16_f32 v126, v120, v121
	v_lshlrev_b64 v[120:121], 14, v[202:203]
	v_pk_fma_f32 v[116:117], v[176:177], v[116:117], v[136:137] op_sel_hi:[0,1,1]
	v_pk_fma_f32 v[114:115], v[162:163], v[130:131], v[114:115] op_sel_hi:[0,1,1] neg_lo:[1,0,0] neg_hi:[1,0,0]
	v_pk_fma_f32 v[112:113], v[176:177], v[112:113], v[132:133] op_sel_hi:[0,1,1]
	v_cndmask_b32_e64 v210, v211, v210, s[0:1]
	v_cvt_pk_bf16_f32 v127, v122, v123
	v_lshl_add_u64 v[120:121], s[50:51], 0, v[120:121]
	v_lshlrev_b64 v[122:123], 1, v[208:209]
	v_pk_fma_f32 v[118:119], v[162:163], v[142:143], v[118:119] op_sel_hi:[0,1,1] neg_lo:[1,0,0] neg_hi:[1,0,0]
	v_pk_fma_f32 v[114:115], v[176:177], v[114:115], v[134:135] op_sel_hi:[0,1,1]
	v_max_f32_e32 v116, 0, v116
	v_max_f32_e32 v112, 0, v112
	v_max_f32_e32 v117, 0, v117
	v_max_f32_e32 v113, 0, v113
	v_div_scale_f32 v211, s[0:1], v210, v210, 1.0
	v_lshl_add_u64 v[120:121], v[120:121], 0, v[122:123]
	v_pk_fma_f32 v[118:119], v[176:177], v[118:119], v[138:139] op_sel_hi:[0,1,1]
	v_pk_mul_f32 v[116:117], v[116:117], v[116:117]
	v_pk_mul_f32 v[112:113], v[112:113], v[112:113]
	v_max_f32_e32 v114, 0, v114
	v_max_f32_e32 v115, 0, v115
	v_pk_fma_f32 v[108:109], v[160:161], v[140:141], v[108:109] op_sel_hi:[0,1,1] neg_lo:[1,0,0] neg_hi:[1,0,0]
	v_pk_fma_f32 v[104:105], v[160:161], v[128:129], v[104:105] op_sel_hi:[0,1,1] neg_lo:[1,0,0] neg_hi:[1,0,0]
	v_rcp_f32_e32 v212, v211
	global_store_dwordx4 v[120:121], v[124:127], off
	v_max_f32_e32 v118, 0, v118
	v_max_f32_e32 v119, 0, v119
	v_pk_mul_f32 v[124:125], v[114:115], v[114:115]
	v_cvt_pk_bf16_f32 v114, v116, v117
	v_cvt_pk_bf16_f32 v116, v112, v113
	v_lshlrev_b64 v[112:113], 14, v[200:201]
	v_pk_fma_f32 v[108:109], v[174:175], v[108:109], v[136:137] op_sel_hi:[0,1,1]
	v_pk_fma_f32 v[106:107], v[160:161], v[130:131], v[106:107] op_sel_hi:[0,1,1] neg_lo:[1,0,0] neg_hi:[1,0,0]
	v_pk_fma_f32 v[104:105], v[174:175], v[104:105], v[132:133] op_sel_hi:[0,1,1]
	v_pk_mul_f32 v[118:119], v[118:119], v[118:119]
	v_lshl_add_u64 v[112:113], s[50:51], 0, v[112:113]
	v_pk_fma_f32 v[110:111], v[160:161], v[142:143], v[110:111] op_sel_hi:[0,1,1] neg_lo:[1,0,0] neg_hi:[1,0,0]
	v_pk_fma_f32 v[106:107], v[174:175], v[106:107], v[134:135] op_sel_hi:[0,1,1]
	v_max_f32_e32 v108, 0, v108
	v_max_f32_e32 v104, 0, v104
	v_max_f32_e32 v109, 0, v109
	v_max_f32_e32 v105, 0, v105
	v_cvt_pk_bf16_f32 v115, v118, v119
	v_cvt_pk_bf16_f32 v117, v124, v125
	v_lshl_add_u64 v[112:113], v[112:113], 0, v[122:123]
	v_pk_fma_f32 v[110:111], v[174:175], v[110:111], v[138:139] op_sel_hi:[0,1,1]
	v_pk_mul_f32 v[108:109], v[108:109], v[108:109]
	v_pk_mul_f32 v[104:105], v[104:105], v[104:105]
	v_max_f32_e32 v106, 0, v106
	v_max_f32_e32 v107, 0, v107
	v_pk_fma_f32 v[100:101], v[164:165], v[140:141], v[100:101] op_sel_hi:[0,1,1] neg_lo:[1,0,0] neg_hi:[1,0,0]
	v_pk_fma_f32 v[96:97], v[164:165], v[128:129], v[96:97] op_sel_hi:[0,1,1] neg_lo:[1,0,0] neg_hi:[1,0,0]
	v_div_fmas_f32 v180, v180, v214, v188
	global_store_dwordx4 v[112:113], v[114:117], off
	v_max_f32_e32 v110, 0, v110
	v_max_f32_e32 v111, 0, v111
	v_pk_mul_f32 v[114:115], v[106:107], v[106:107]
	v_cvt_pk_bf16_f32 v106, v108, v109
	v_cvt_pk_bf16_f32 v108, v104, v105
	v_lshlrev_b64 v[104:105], 14, v[198:199]
	v_pk_fma_f32 v[100:101], v[186:187], v[100:101], v[136:137] op_sel_hi:[0,1,1]
	v_pk_fma_f32 v[98:99], v[164:165], v[130:131], v[98:99] op_sel_hi:[0,1,1] neg_lo:[1,0,0] neg_hi:[1,0,0]
	v_pk_fma_f32 v[96:97], v[186:187], v[96:97], v[132:133] op_sel_hi:[0,1,1]
	v_div_fixup_f32 v188, v180, v191, 1.0
	v_fma_f32 v180, -v211, v212, 1.0
	v_pk_mul_f32 v[110:111], v[110:111], v[110:111]
	v_lshl_add_u64 v[104:105], s[50:51], 0, v[104:105]
	v_pk_fma_f32 v[102:103], v[164:165], v[142:143], v[102:103] op_sel_hi:[0,1,1] neg_lo:[1,0,0] neg_hi:[1,0,0]
	v_pk_fma_f32 v[98:99], v[186:187], v[98:99], v[134:135] op_sel_hi:[0,1,1]
	v_max_f32_e32 v100, 0, v100
	v_max_f32_e32 v96, 0, v96
	v_max_f32_e32 v101, 0, v101
	v_max_f32_e32 v97, 0, v97
	v_fmac_f32_e32 v212, v180, v212
	v_div_scale_f32 v180, vcc, 1.0, v210, 1.0
	v_cvt_pk_bf16_f32 v107, v110, v111
	v_cvt_pk_bf16_f32 v109, v114, v115
	v_lshl_add_u64 v[104:105], v[104:105], 0, v[122:123]
	v_pk_fma_f32 v[102:103], v[186:187], v[102:103], v[138:139] op_sel_hi:[0,1,1]
	v_pk_mul_f32 v[100:101], v[100:101], v[100:101]
	v_pk_mul_f32 v[96:97], v[96:97], v[96:97]
	v_max_f32_e32 v98, 0, v98
	v_max_f32_e32 v99, 0, v99
	v_pk_fma_f32 v[92:93], v[170:171], v[140:141], v[92:93] op_sel_hi:[0,1,1] neg_lo:[1,0,0] neg_hi:[1,0,0]
	v_pk_fma_f32 v[88:89], v[170:171], v[128:129], v[88:89] op_sel_hi:[0,1,1] neg_lo:[1,0,0] neg_hi:[1,0,0]
	v_mul_f32_e32 v191, v180, v212
	global_store_dwordx4 v[104:105], v[106:109], off
	v_max_f32_e32 v102, 0, v102
	v_max_f32_e32 v103, 0, v103
	v_pk_mul_f32 v[106:107], v[98:99], v[98:99]
	v_cvt_pk_bf16_f32 v98, v100, v101
	v_cvt_pk_bf16_f32 v100, v96, v97
	v_lshlrev_b64 v[96:97], 14, v[196:197]
	v_pk_fma_f32 v[92:93], v[182:183], v[92:93], v[136:137] op_sel_hi:[0,1,1]
	v_pk_fma_f32 v[90:91], v[170:171], v[130:131], v[90:91] op_sel_hi:[0,1,1] neg_lo:[1,0,0] neg_hi:[1,0,0]
	v_pk_fma_f32 v[88:89], v[182:183], v[88:89], v[132:133] op_sel_hi:[0,1,1]
	v_fma_f32 v213, -v211, v191, v180
	v_pk_mul_f32 v[102:103], v[102:103], v[102:103]
	v_lshl_add_u64 v[96:97], s[50:51], 0, v[96:97]
	v_pk_fma_f32 v[94:95], v[170:171], v[142:143], v[94:95] op_sel_hi:[0,1,1] neg_lo:[1,0,0] neg_hi:[1,0,0]
	v_pk_fma_f32 v[90:91], v[182:183], v[90:91], v[134:135] op_sel_hi:[0,1,1]
	v_max_f32_e32 v92, 0, v92
	v_max_f32_e32 v88, 0, v88
	v_max_f32_e32 v93, 0, v93
	v_max_f32_e32 v89, 0, v89
	v_fmac_f32_e32 v191, v213, v212
	v_cvt_pk_bf16_f32 v99, v102, v103
	v_cvt_pk_bf16_f32 v101, v106, v107
	v_lshl_add_u64 v[96:97], v[96:97], 0, v[122:123]
	v_pk_fma_f32 v[94:95], v[182:183], v[94:95], v[138:139] op_sel_hi:[0,1,1]
	v_pk_mul_f32 v[92:93], v[92:93], v[92:93]
	v_pk_mul_f32 v[88:89], v[88:89], v[88:89]
	v_max_f32_e32 v90, 0, v90
	v_max_f32_e32 v91, 0, v91
	v_pk_fma_f32 v[84:85], v[168:169], v[140:141], v[84:85] op_sel_hi:[0,1,1] neg_lo:[1,0,0] neg_hi:[1,0,0]
	v_pk_fma_f32 v[80:81], v[168:169], v[128:129], v[80:81] op_sel_hi:[0,1,1] neg_lo:[1,0,0] neg_hi:[1,0,0]
	global_store_dwordx4 v[96:97], v[98:101], off
	v_max_f32_e32 v94, 0, v94
	v_max_f32_e32 v95, 0, v95
	v_pk_mul_f32 v[98:99], v[90:91], v[90:91]
	v_cvt_pk_bf16_f32 v90, v92, v93
	v_cvt_pk_bf16_f32 v92, v88, v89
	v_lshlrev_b64 v[88:89], 14, v[194:195]
	v_pk_fma_f32 v[84:85], v[84:85], v[190:191], v[136:137] op_sel_hi:[1,0,1]
	v_pk_fma_f32 v[82:83], v[168:169], v[130:131], v[82:83] op_sel_hi:[0,1,1] neg_lo:[1,0,0] neg_hi:[1,0,0]
	v_pk_fma_f32 v[80:81], v[190:191], v[80:81], v[132:133] op_sel_hi:[0,1,1]
	v_pk_mul_f32 v[94:95], v[94:95], v[94:95]
	v_lshl_add_u64 v[88:89], s[50:51], 0, v[88:89]
	v_pk_fma_f32 v[86:87], v[168:169], v[142:143], v[86:87] op_sel_hi:[0,1,1] neg_lo:[1,0,0] neg_hi:[1,0,0]
	v_pk_fma_f32 v[82:83], v[190:191], v[82:83], v[134:135] op_sel_hi:[0,1,1]
	v_max_f32_e32 v84, 0, v84
	v_max_f32_e32 v80, 0, v80
	v_max_f32_e32 v85, 0, v85
	v_max_f32_e32 v81, 0, v81
	v_cvt_pk_bf16_f32 v91, v94, v95
	v_cvt_pk_bf16_f32 v93, v98, v99
	v_lshl_add_u64 v[88:89], v[88:89], 0, v[122:123]
	v_pk_fma_f32 v[86:87], v[86:87], v[190:191], v[138:139] op_sel_hi:[1,0,1]
	v_pk_mul_f32 v[84:85], v[84:85], v[84:85]
	v_pk_mul_f32 v[80:81], v[80:81], v[80:81]
	v_max_f32_e32 v82, 0, v82
	v_max_f32_e32 v83, 0, v83
	global_store_dwordx4 v[88:89], v[90:93], off
	v_max_f32_e32 v86, 0, v86
	v_max_f32_e32 v87, 0, v87
	v_pk_mul_f32 v[90:91], v[82:83], v[82:83]
	v_cvt_pk_bf16_f32 v82, v84, v85
	v_cvt_pk_bf16_f32 v84, v80, v81
	v_lshlrev_b64 v[80:81], 14, v[192:193]
	v_pk_fma_f32 v[76:77], v[178:179], v[140:141], v[76:77] op_sel_hi:[0,1,1] neg_lo:[1,0,0] neg_hi:[1,0,0]
	v_pk_fma_f32 v[72:73], v[178:179], v[128:129], v[72:73] op_sel_hi:[0,1,1] neg_lo:[1,0,0] neg_hi:[1,0,0]
	v_pk_mul_f32 v[86:87], v[86:87], v[86:87]
	v_lshl_add_u64 v[80:81], s[50:51], 0, v[80:81]
	v_pk_fma_f32 v[78:79], v[178:179], v[142:143], v[78:79] op_sel_hi:[0,1,1] neg_lo:[1,0,0] neg_hi:[1,0,0]
	v_pk_fma_f32 v[76:77], v[76:77], v[188:189], v[136:137] op_sel_hi:[1,0,1]
	v_pk_fma_f32 v[72:73], v[72:73], v[188:189], v[132:133] op_sel_hi:[1,0,1]
	v_cvt_pk_bf16_f32 v83, v86, v87
	v_cvt_pk_bf16_f32 v85, v90, v91
	v_lshl_add_u64 v[80:81], v[80:81], 0, v[122:123]
	v_pk_fma_f32 v[78:79], v[78:79], v[188:189], v[138:139] op_sel_hi:[1,0,1]
	v_pk_fma_f32 v[74:75], v[178:179], v[130:131], v[74:75] op_sel_hi:[0,1,1] neg_lo:[1,0,0] neg_hi:[1,0,0]
	v_max_f32_e32 v76, 0, v76
	v_max_f32_e32 v72, 0, v72
	v_max_f32_e32 v77, 0, v77
	v_max_f32_e32 v73, 0, v73
	global_store_dwordx4 v[80:81], v[82:85], off
	v_pk_fma_f32 v[74:75], v[74:75], v[188:189], v[134:135] op_sel_hi:[1,0,1]
	v_pk_mul_f32 v[76:77], v[76:77], v[76:77]
	v_pk_mul_f32 v[82:83], v[72:73], v[72:73]
	v_max_f32_e32 v72, 0, v78
	v_max_f32_e32 v73, 0, v79
	v_max_f32_e32 v74, 0, v74
	v_max_f32_e32 v75, 0, v75
	v_pk_mul_f32 v[78:79], v[72:73], v[72:73]
	v_cvt_pk_bf16_f32 v72, v76, v77
	v_lshlrev_b64 v[76:77], 14, v[206:207]
	v_fma_f32 v180, -v211, v191, v180
	v_pk_mul_f32 v[84:85], v[74:75], v[74:75]
	v_lshl_add_u64 v[76:77], s[50:51], 0, v[76:77]
	v_div_fmas_f32 v180, v180, v212, v191
	v_cvt_pk_bf16_f32 v73, v78, v79
	v_cvt_pk_bf16_f32 v74, v82, v83
	v_cvt_pk_bf16_f32 v75, v84, v85
	v_lshl_add_u64 v[82:83], v[76:77], 0, v[122:123]
	v_div_fixup_f32 v180, v180, v210, 1.0
	global_store_dwordx4 v[82:83], v[72:75], off
	v_pk_fma_f32 v[68:69], v[140:141], v[172:173], v[68:69] op_sel_hi:[1,0,1] neg_lo:[1,0,0] neg_hi:[1,0,0]
	v_pk_fma_f32 v[64:65], v[172:173], v[128:129], v[64:65] op_sel_hi:[0,1,1] neg_lo:[1,0,0] neg_hi:[1,0,0]
	v_xor_b32_e32 v73, 0x80000000, v143
	v_xor_b32_e32 v72, 0x80000000, v142
	v_pk_fma_f32 v[70:71], v[72:73], v[172:173], v[70:71] op_sel_hi:[1,0,1]
	v_pk_fma_f32 v[68:69], v[68:69], v[180:181], v[136:137] op_sel_hi:[1,0,1]
	v_pk_fma_f32 v[64:65], v[64:65], v[180:181], v[132:133] op_sel_hi:[1,0,1]
	v_pk_fma_f32 v[70:71], v[70:71], v[180:181], v[138:139] op_sel_hi:[1,0,1]
	v_pk_fma_f32 v[66:67], v[172:173], v[130:131], v[66:67] op_sel_hi:[0,1,1] neg_lo:[1,0,0] neg_hi:[1,0,0]
	v_max_f32_e32 v68, 0, v68
	v_max_f32_e32 v64, 0, v64
	v_max_f32_e32 v69, 0, v69
	v_max_f32_e32 v65, 0, v65
	v_pk_fma_f32 v[66:67], v[66:67], v[180:181], v[134:135] op_sel_hi:[1,0,1]
	v_pk_mul_f32 v[68:69], v[68:69], v[68:69]
	v_pk_mul_f32 v[72:73], v[64:65], v[64:65]
	v_max_f32_e32 v64, 0, v70
	v_max_f32_e32 v65, 0, v71
	v_max_f32_e32 v66, 0, v66
	v_max_f32_e32 v67, 0, v67
	v_pk_mul_f32 v[70:71], v[64:65], v[64:65]
	v_cvt_pk_bf16_f32 v64, v68, v69
	v_lshlrev_b64 v[68:69], 14, v[204:205]
	v_pk_mul_f32 v[74:75], v[66:67], v[66:67]
	v_lshl_add_u64 v[68:69], s[50:51], 0, v[68:69]
	v_cvt_pk_bf16_f32 v65, v70, v71
	v_cvt_pk_bf16_f32 v66, v72, v73
	v_cvt_pk_bf16_f32 v67, v74, v75
	v_lshl_add_u64 v[84:85], v[68:69], 0, v[122:123]
	global_store_dwordx4 v[84:85], v[64:67], off
	s_and_b64 vcc, exec, s[6:7]
	s_mov_b64 s[0:1], -1
	v_or_b32_e32 v64, 0x80, v208
	v_ashrrev_i32_e32 v65, 31, v64
	v_lshlrev_b64 v[64:65], 2, v[64:65]
	v_lshl_add_u64 v[66:67], s[82:83], 0, v[64:65]
	v_lshl_add_u64 v[64:65], s[26:27], 0, v[64:65]
	global_load_dwordx4 v[72:75], v[66:67], off
	global_load_dwordx4 v[76:79], v[64:65], off
	global_load_dwordx4 v[68:71], v[66:67], off offset:16
	s_nop 0
	global_load_dwordx4 v[64:67], v[64:65], off offset:16
	s_waitcnt vmcnt(0)
	v_pk_fma_f32 v[56:57], v[166:167], v[68:69], v[56:57] op_sel_hi:[0,1,1] neg_lo:[1,0,0] neg_hi:[1,0,0]
	v_pk_fma_f32 v[60:61], v[166:167], v[72:73], v[60:61] op_sel_hi:[0,1,1] neg_lo:[1,0,0] neg_hi:[1,0,0]
	v_pk_fma_f32 v[62:63], v[166:167], v[74:75], v[62:63] op_sel_hi:[0,1,1] neg_lo:[1,0,0] neg_hi:[1,0,0]
	v_pk_fma_f32 v[58:59], v[166:167], v[70:71], v[58:59] op_sel_hi:[0,1,1] neg_lo:[1,0,0] neg_hi:[1,0,0]
	v_pk_fma_f32 v[56:57], v[184:185], v[56:57], v[64:65] op_sel_hi:[0,1,1]
	v_pk_fma_f32 v[62:63], v[184:185], v[62:63], v[78:79] op_sel_hi:[0,1,1]
	v_pk_fma_f32 v[60:61], v[184:185], v[60:61], v[76:77] op_sel_hi:[0,1,1]
	v_pk_fma_f32 v[58:59], v[184:185], v[58:59], v[66:67] op_sel_hi:[0,1,1]
	v_max_f32_e32 v56, 0, v56
	v_max_f32_e32 v57, 0, v57
	v_max_f32_e32 v60, 0, v60
	v_max_f32_e32 v61, 0, v61
	v_pk_mul_f32 v[86:87], v[56:57], v[56:57]
	v_max_f32_e32 v56, 0, v62
	v_max_f32_e32 v58, 0, v58
	v_max_f32_e32 v57, 0, v63
	v_max_f32_e32 v59, 0, v59
	v_pk_fma_f32 v[48:49], v[162:163], v[68:69], v[48:49] op_sel_hi:[0,1,1] neg_lo:[1,0,0] neg_hi:[1,0,0]
	v_pk_mul_f32 v[60:61], v[60:61], v[60:61]
	v_pk_mul_f32 v[62:63], v[56:57], v[56:57]
	v_pk_mul_f32 v[90:91], v[58:59], v[58:59]
	v_pk_fma_f32 v[52:53], v[162:163], v[72:73], v[52:53] op_sel_hi:[0,1,1] neg_lo:[1,0,0] neg_hi:[1,0,0]
	v_pk_fma_f32 v[54:55], v[162:163], v[74:75], v[54:55] op_sel_hi:[0,1,1] neg_lo:[1,0,0] neg_hi:[1,0,0]
	v_pk_fma_f32 v[50:51], v[162:163], v[70:71], v[50:51] op_sel_hi:[0,1,1] neg_lo:[1,0,0] neg_hi:[1,0,0]
	v_pk_fma_f32 v[48:49], v[176:177], v[48:49], v[64:65] op_sel_hi:[0,1,1]
	v_cvt_pk_bf16_f32 v56, v60, v61
	v_cvt_pk_bf16_f32 v57, v62, v63
	v_cvt_pk_bf16_f32 v58, v86, v87
	v_cvt_pk_bf16_f32 v59, v90, v91
	v_pk_fma_f32 v[54:55], v[176:177], v[54:55], v[78:79] op_sel_hi:[0,1,1]
	v_pk_fma_f32 v[52:53], v[176:177], v[52:53], v[76:77] op_sel_hi:[0,1,1]
	v_pk_fma_f32 v[50:51], v[176:177], v[50:51], v[66:67] op_sel_hi:[0,1,1]
	v_max_f32_e32 v48, 0, v48
	v_max_f32_e32 v49, 0, v49
	global_store_dwordx4 v[120:121], v[56:59], off offset:256
	v_max_f32_e32 v52, 0, v52
	v_max_f32_e32 v53, 0, v53
	v_pk_mul_f32 v[56:57], v[48:49], v[48:49]
	v_max_f32_e32 v48, 0, v54
	v_max_f32_e32 v50, 0, v50
	v_max_f32_e32 v49, 0, v55
	v_max_f32_e32 v51, 0, v51
	v_pk_fma_f32 v[40:41], v[160:161], v[68:69], v[40:41] op_sel_hi:[0,1,1] neg_lo:[1,0,0] neg_hi:[1,0,0]
	v_pk_mul_f32 v[52:53], v[52:53], v[52:53]
	v_pk_mul_f32 v[54:55], v[48:49], v[48:49]
	v_pk_mul_f32 v[58:59], v[50:51], v[50:51]
	v_pk_fma_f32 v[44:45], v[160:161], v[72:73], v[44:45] op_sel_hi:[0,1,1] neg_lo:[1,0,0] neg_hi:[1,0,0]
	v_pk_fma_f32 v[46:47], v[160:161], v[74:75], v[46:47] op_sel_hi:[0,1,1] neg_lo:[1,0,0] neg_hi:[1,0,0]
	v_pk_fma_f32 v[42:43], v[160:161], v[70:71], v[42:43] op_sel_hi:[0,1,1] neg_lo:[1,0,0] neg_hi:[1,0,0]
	v_pk_fma_f32 v[40:41], v[174:175], v[40:41], v[64:65] op_sel_hi:[0,1,1]
	v_cvt_pk_bf16_f32 v48, v52, v53
	v_cvt_pk_bf16_f32 v49, v54, v55
	v_cvt_pk_bf16_f32 v50, v56, v57
	v_cvt_pk_bf16_f32 v51, v58, v59
	v_pk_fma_f32 v[46:47], v[174:175], v[46:47], v[78:79] op_sel_hi:[0,1,1]
	v_pk_fma_f32 v[44:45], v[174:175], v[44:45], v[76:77] op_sel_hi:[0,1,1]
	v_pk_fma_f32 v[42:43], v[174:175], v[42:43], v[66:67] op_sel_hi:[0,1,1]
	v_max_f32_e32 v40, 0, v40
	v_max_f32_e32 v41, 0, v41
	global_store_dwordx4 v[112:113], v[48:51], off offset:256
	v_max_f32_e32 v44, 0, v44
	v_max_f32_e32 v45, 0, v45
	v_pk_mul_f32 v[48:49], v[40:41], v[40:41]
	v_max_f32_e32 v40, 0, v46
	v_max_f32_e32 v42, 0, v42
	v_max_f32_e32 v41, 0, v47
	v_max_f32_e32 v43, 0, v43
	v_pk_fma_f32 v[32:33], v[164:165], v[68:69], v[32:33] op_sel_hi:[0,1,1] neg_lo:[1,0,0] neg_hi:[1,0,0]
	v_pk_mul_f32 v[44:45], v[44:45], v[44:45]
	v_pk_mul_f32 v[46:47], v[40:41], v[40:41]
	v_pk_mul_f32 v[50:51], v[42:43], v[42:43]
	v_pk_fma_f32 v[36:37], v[164:165], v[72:73], v[36:37] op_sel_hi:[0,1,1] neg_lo:[1,0,0] neg_hi:[1,0,0]
	v_pk_fma_f32 v[38:39], v[164:165], v[74:75], v[38:39] op_sel_hi:[0,1,1] neg_lo:[1,0,0] neg_hi:[1,0,0]
	v_pk_fma_f32 v[34:35], v[164:165], v[70:71], v[34:35] op_sel_hi:[0,1,1] neg_lo:[1,0,0] neg_hi:[1,0,0]
	v_pk_fma_f32 v[32:33], v[186:187], v[32:33], v[64:65] op_sel_hi:[0,1,1]
	v_cvt_pk_bf16_f32 v40, v44, v45
	v_cvt_pk_bf16_f32 v41, v46, v47
	v_cvt_pk_bf16_f32 v42, v48, v49
	v_cvt_pk_bf16_f32 v43, v50, v51
	v_pk_fma_f32 v[38:39], v[186:187], v[38:39], v[78:79] op_sel_hi:[0,1,1]
	v_pk_fma_f32 v[36:37], v[186:187], v[36:37], v[76:77] op_sel_hi:[0,1,1]
	v_pk_fma_f32 v[34:35], v[186:187], v[34:35], v[66:67] op_sel_hi:[0,1,1]
	v_max_f32_e32 v32, 0, v32
	v_max_f32_e32 v33, 0, v33
	global_store_dwordx4 v[104:105], v[40:43], off offset:256
	v_max_f32_e32 v36, 0, v36
	v_max_f32_e32 v37, 0, v37
	v_pk_mul_f32 v[40:41], v[32:33], v[32:33]
	v_max_f32_e32 v32, 0, v38
	v_max_f32_e32 v34, 0, v34
	v_max_f32_e32 v33, 0, v39
	v_max_f32_e32 v35, 0, v35
	v_pk_fma_f32 v[24:25], v[170:171], v[68:69], v[24:25] op_sel_hi:[0,1,1] neg_lo:[1,0,0] neg_hi:[1,0,0]
	v_pk_mul_f32 v[36:37], v[36:37], v[36:37]
	v_pk_mul_f32 v[38:39], v[32:33], v[32:33]
	v_pk_mul_f32 v[42:43], v[34:35], v[34:35]
	v_pk_fma_f32 v[28:29], v[170:171], v[72:73], v[28:29] op_sel_hi:[0,1,1] neg_lo:[1,0,0] neg_hi:[1,0,0]
	v_pk_fma_f32 v[30:31], v[170:171], v[74:75], v[30:31] op_sel_hi:[0,1,1] neg_lo:[1,0,0] neg_hi:[1,0,0]
	v_pk_fma_f32 v[26:27], v[170:171], v[70:71], v[26:27] op_sel_hi:[0,1,1] neg_lo:[1,0,0] neg_hi:[1,0,0]
	v_pk_fma_f32 v[24:25], v[182:183], v[24:25], v[64:65] op_sel_hi:[0,1,1]
	v_cvt_pk_bf16_f32 v32, v36, v37
	v_cvt_pk_bf16_f32 v33, v38, v39
	v_cvt_pk_bf16_f32 v34, v40, v41
	v_cvt_pk_bf16_f32 v35, v42, v43
	v_pk_fma_f32 v[30:31], v[182:183], v[30:31], v[78:79] op_sel_hi:[0,1,1]
	v_pk_fma_f32 v[28:29], v[182:183], v[28:29], v[76:77] op_sel_hi:[0,1,1]
	v_pk_fma_f32 v[26:27], v[182:183], v[26:27], v[66:67] op_sel_hi:[0,1,1]
	v_max_f32_e32 v24, 0, v24
	v_max_f32_e32 v25, 0, v25
	global_store_dwordx4 v[96:97], v[32:35], off offset:256
	v_max_f32_e32 v28, 0, v28
	v_max_f32_e32 v29, 0, v29
	v_pk_mul_f32 v[32:33], v[24:25], v[24:25]
	v_max_f32_e32 v24, 0, v30
	v_max_f32_e32 v26, 0, v26
	v_max_f32_e32 v25, 0, v31
	v_max_f32_e32 v27, 0, v27
	v_pk_fma_f32 v[16:17], v[168:169], v[68:69], v[16:17] op_sel_hi:[0,1,1] neg_lo:[1,0,0] neg_hi:[1,0,0]
	v_pk_mul_f32 v[28:29], v[28:29], v[28:29]
	v_pk_mul_f32 v[30:31], v[24:25], v[24:25]
	v_pk_mul_f32 v[34:35], v[26:27], v[26:27]
	v_pk_fma_f32 v[20:21], v[168:169], v[72:73], v[20:21] op_sel_hi:[0,1,1] neg_lo:[1,0,0] neg_hi:[1,0,0]
	v_pk_fma_f32 v[22:23], v[168:169], v[74:75], v[22:23] op_sel_hi:[0,1,1] neg_lo:[1,0,0] neg_hi:[1,0,0]
	v_pk_fma_f32 v[18:19], v[168:169], v[70:71], v[18:19] op_sel_hi:[0,1,1] neg_lo:[1,0,0] neg_hi:[1,0,0]
	v_pk_fma_f32 v[16:17], v[190:191], v[16:17], v[64:65] op_sel_hi:[0,1,1]
	v_cvt_pk_bf16_f32 v24, v28, v29
	v_cvt_pk_bf16_f32 v25, v30, v31
	v_cvt_pk_bf16_f32 v26, v32, v33
	v_cvt_pk_bf16_f32 v27, v34, v35
	v_pk_fma_f32 v[22:23], v[190:191], v[22:23], v[78:79] op_sel_hi:[0,1,1]
	v_pk_fma_f32 v[20:21], v[190:191], v[20:21], v[76:77] op_sel_hi:[0,1,1]
	v_pk_fma_f32 v[18:19], v[190:191], v[18:19], v[66:67] op_sel_hi:[0,1,1]
	v_max_f32_e32 v16, 0, v16
	v_max_f32_e32 v17, 0, v17
	global_store_dwordx4 v[88:89], v[24:27], off offset:256
	v_max_f32_e32 v20, 0, v20
	v_max_f32_e32 v21, 0, v21
	v_pk_mul_f32 v[24:25], v[16:17], v[16:17]
	v_max_f32_e32 v16, 0, v22
	v_max_f32_e32 v18, 0, v18
	v_max_f32_e32 v17, 0, v23
	v_max_f32_e32 v19, 0, v19
	v_pk_fma_f32 v[8:9], v[178:179], v[68:69], v[8:9] op_sel_hi:[0,1,1] neg_lo:[1,0,0] neg_hi:[1,0,0]
	v_pk_mul_f32 v[20:21], v[20:21], v[20:21]
	v_pk_mul_f32 v[22:23], v[16:17], v[16:17]
	v_pk_mul_f32 v[26:27], v[18:19], v[18:19]
	v_pk_fma_f32 v[12:13], v[178:179], v[72:73], v[12:13] op_sel_hi:[0,1,1] neg_lo:[1,0,0] neg_hi:[1,0,0]
	v_pk_fma_f32 v[14:15], v[178:179], v[74:75], v[14:15] op_sel_hi:[0,1,1] neg_lo:[1,0,0] neg_hi:[1,0,0]
	v_pk_fma_f32 v[10:11], v[178:179], v[70:71], v[10:11] op_sel_hi:[0,1,1] neg_lo:[1,0,0] neg_hi:[1,0,0]
	v_pk_fma_f32 v[8:9], v[188:189], v[8:9], v[64:65] op_sel_hi:[0,1,1]
	v_cvt_pk_bf16_f32 v16, v20, v21
	v_cvt_pk_bf16_f32 v17, v22, v23
	v_cvt_pk_bf16_f32 v18, v24, v25
	v_cvt_pk_bf16_f32 v19, v26, v27
	v_pk_fma_f32 v[14:15], v[188:189], v[14:15], v[78:79] op_sel_hi:[0,1,1]
	v_pk_fma_f32 v[12:13], v[188:189], v[12:13], v[76:77] op_sel_hi:[0,1,1]
	v_pk_fma_f32 v[10:11], v[188:189], v[10:11], v[66:67] op_sel_hi:[0,1,1]
	v_max_f32_e32 v8, 0, v8
	v_max_f32_e32 v9, 0, v9
	global_store_dwordx4 v[80:81], v[16:19], off offset:256
	v_max_f32_e32 v12, 0, v12
	v_max_f32_e32 v13, 0, v13
	v_pk_mul_f32 v[16:17], v[8:9], v[8:9]
	v_max_f32_e32 v8, 0, v14
	v_max_f32_e32 v10, 0, v10
	v_max_f32_e32 v9, 0, v15
	v_max_f32_e32 v11, 0, v11
	v_pk_fma_f32 v[0:1], v[172:173], v[68:69], v[0:1] op_sel_hi:[0,1,1] neg_lo:[1,0,0] neg_hi:[1,0,0]
	v_pk_mul_f32 v[12:13], v[12:13], v[12:13]
	v_pk_mul_f32 v[14:15], v[8:9], v[8:9]
	v_pk_mul_f32 v[18:19], v[10:11], v[10:11]
	v_pk_fma_f32 v[4:5], v[172:173], v[72:73], v[4:5] op_sel_hi:[0,1,1] neg_lo:[1,0,0] neg_hi:[1,0,0]
	v_pk_fma_f32 v[6:7], v[172:173], v[74:75], v[6:7] op_sel_hi:[0,1,1] neg_lo:[1,0,0] neg_hi:[1,0,0]
	v_pk_fma_f32 v[2:3], v[172:173], v[70:71], v[2:3] op_sel_hi:[0,1,1] neg_lo:[1,0,0] neg_hi:[1,0,0]
	v_pk_fma_f32 v[0:1], v[180:181], v[0:1], v[64:65] op_sel_hi:[0,1,1]
	v_cvt_pk_bf16_f32 v8, v12, v13
	v_cvt_pk_bf16_f32 v9, v14, v15
	v_cvt_pk_bf16_f32 v10, v16, v17
	v_cvt_pk_bf16_f32 v11, v18, v19
	v_pk_fma_f32 v[6:7], v[180:181], v[6:7], v[78:79] op_sel_hi:[0,1,1]
	v_pk_fma_f32 v[4:5], v[180:181], v[4:5], v[76:77] op_sel_hi:[0,1,1]
	v_pk_fma_f32 v[2:3], v[180:181], v[2:3], v[66:67] op_sel_hi:[0,1,1]
	v_max_f32_e32 v0, 0, v0
	v_max_f32_e32 v1, 0, v1
	global_store_dwordx4 v[82:83], v[8:11], off offset:256
	v_max_f32_e32 v4, 0, v4
	v_max_f32_e32 v5, 0, v5
	v_pk_mul_f32 v[8:9], v[0:1], v[0:1]
	v_max_f32_e32 v0, 0, v6
	v_max_f32_e32 v2, 0, v2
	v_max_f32_e32 v1, 0, v7
	v_max_f32_e32 v3, 0, v3
	v_pk_mul_f32 v[4:5], v[4:5], v[4:5]
	v_pk_mul_f32 v[6:7], v[0:1], v[0:1]
	v_pk_mul_f32 v[10:11], v[2:3], v[2:3]
	v_cvt_pk_bf16_f32 v0, v4, v5
	v_cvt_pk_bf16_f32 v1, v6, v7
	v_cvt_pk_bf16_f32 v2, v8, v9
	v_cvt_pk_bf16_f32 v3, v10, v11
	global_store_dwordx4 v[84:85], v[0:3], off offset:256
	s_cbranch_vccnz .LBB0_759
	s_andn2_b64 vcc, exec, s[24:25]
	s_cbranch_vccnz .LBB0_758
	s_barrier
	s_branch .LBB0_758

.LBB0_855:
	ds_read_b128 v[128:131], v229
	ds_read_b128 v[132:135], v229 offset:1024
	ds_read_b128 v[136:139], v229 offset:2048
	ds_read_b128 v[140:143], v229 offset:3072
	ds_read_b128 v[160:163], v230
	ds_read_b128 v[164:167], v230 offset:1024
	ds_read_b128 v[168:171], v230 offset:2048
	ds_read_b128 v[172:175], v230 offset:3072
	s_add_i32 s85, s42, 2
	s_add_u32 s86, s0, 0x80
	s_addc_u32 s43, s1, 0
	s_cmp_eq_u32 s60, s42
	s_cselect_b32 s42, s38, s86
	s_cselect_b32 s43, s39, s43
	s_cselect_b32 s87, s41, s45
	s_cselect_b32 s86, s40, s44
	v_lshl_add_u64 v[208:209], s[0:1], 0, v[152:153]
	s_add_i32 m0, s48, 0xc000
	ds_read_b128 v[176:179], v231
	ds_read_b128 v[180:183], v231 offset:1024
	ds_read_b128 v[184:187], v231 offset:2048
	ds_read_b128 v[188:191], v231 offset:3072
	ds_read_b128 v[192:195], v231 offset:4096
	ds_read_b128 v[196:199], v231 offset:5120
	ds_read_b128 v[200:203], v231 offset:6144
	ds_read_b128 v[204:207], v231 offset:7168
	global_load_lds_dwordx4 v[208:209], off
	v_lshl_add_u64 v[208:209], s[0:1], 0, v[154:155]
	s_add_i32 m0, s48, 0xe000
	s_nop 0
	global_load_lds_dwordx4 v[208:209], off
	s_waitcnt vmcnt(8)
	s_waitcnt lgkmcnt(0)
	s_setprio 1
	s_barrier
	v_mfma_f32_16x16x32_bf16 v[124:127], v[128:131], v[176:179], v[124:127]
	v_mfma_f32_16x16x32_bf16 v[120:123], v[136:139], v[176:179], v[120:123]
	v_mfma_f32_16x16x32_bf16 v[116:119], v[128:131], v[184:187], v[116:119]
	v_mfma_f32_16x16x32_bf16 v[112:115], v[136:139], v[184:187], v[112:115]
	v_mfma_f32_16x16x32_bf16 v[108:111], v[128:131], v[192:195], v[108:111]
	v_mfma_f32_16x16x32_bf16 v[104:107], v[136:139], v[192:195], v[104:107]
	v_mfma_f32_16x16x32_bf16 v[100:103], v[128:131], v[200:203], v[100:103]
	v_mfma_f32_16x16x32_bf16 v[96:99], v[136:139], v[200:203], v[96:99]
	v_mfma_f32_16x16x32_bf16 v[124:127], v[132:135], v[180:183], v[124:127]
	v_mfma_f32_16x16x32_bf16 v[120:123], v[140:143], v[180:183], v[120:123]
	v_mfma_f32_16x16x32_bf16 v[116:119], v[132:135], v[188:191], v[116:119]
	v_mfma_f32_16x16x32_bf16 v[112:115], v[140:143], v[188:191], v[112:115]
	v_mfma_f32_16x16x32_bf16 v[108:111], v[132:135], v[196:199], v[108:111]
	v_mfma_f32_16x16x32_bf16 v[104:107], v[140:143], v[196:199], v[104:107]
	v_mfma_f32_16x16x32_bf16 v[100:103], v[132:135], v[204:207], v[100:103]
	v_mfma_f32_16x16x32_bf16 v[96:99], v[140:143], v[204:207], v[96:99]
	v_mfma_f32_16x16x32_bf16 v[60:63], v[160:163], v[176:179], v[60:63]
	v_mfma_f32_16x16x32_bf16 v[56:59], v[168:171], v[176:179], v[56:59]
	v_mfma_f32_16x16x32_bf16 v[52:55], v[160:163], v[184:187], v[52:55]
	v_mfma_f32_16x16x32_bf16 v[48:51], v[168:171], v[184:187], v[48:51]
	v_mfma_f32_16x16x32_bf16 v[44:47], v[160:163], v[192:195], v[44:47]
	v_mfma_f32_16x16x32_bf16 v[40:43], v[168:171], v[192:195], v[40:43]
	v_mfma_f32_16x16x32_bf16 v[36:39], v[160:163], v[200:203], v[36:39]
	v_mfma_f32_16x16x32_bf16 v[32:35], v[168:171], v[200:203], v[32:35]
	v_mfma_f32_16x16x32_bf16 v[60:63], v[164:167], v[180:183], v[60:63]
	v_mfma_f32_16x16x32_bf16 v[56:59], v[172:175], v[180:183], v[56:59]
	v_mfma_f32_16x16x32_bf16 v[52:55], v[164:167], v[188:191], v[52:55]
	v_mfma_f32_16x16x32_bf16 v[48:51], v[172:175], v[188:191], v[48:51]
	v_mfma_f32_16x16x32_bf16 v[44:47], v[164:167], v[196:199], v[44:47]
	v_mfma_f32_16x16x32_bf16 v[40:43], v[172:175], v[196:199], v[40:43]
	v_mfma_f32_16x16x32_bf16 v[36:39], v[164:167], v[204:207], v[36:39]
	v_mfma_f32_16x16x32_bf16 v[32:35], v[172:175], v[204:207], v[32:35]
	s_barrier
	s_setprio 0
	s_add_i32 s88, s76, s47
	v_lshl_add_u64 v[208:209], s[86:87], 0, v[146:147]
	s_mov_b32 m0, s88
	ds_read_b128 v[176:179], v231 offset:16384
	ds_read_b128 v[180:183], v231 offset:17408
	ds_read_b128 v[184:187], v231 offset:18432
	ds_read_b128 v[188:191], v231 offset:19456
	ds_read_b128 v[192:195], v231 offset:20480
	ds_read_b128 v[196:199], v231 offset:21504
	ds_read_b128 v[200:203], v231 offset:22528
	ds_read_b128 v[204:207], v231 offset:23552
	global_load_lds_dwordx4 v[208:209], off
	s_add_i32 m0, s88, 0x2000
	v_lshl_add_u64 v[210:211], s[86:87], 0, v[150:151]
	s_add_u32 s86, s86, s10
	s_addc_u32 s87, s87, s11
	s_add_i32 s88, s77, s47
	global_load_lds_dwordx4 v[210:211], off
	v_lshl_add_u64 v[212:213], s[86:87], 0, v[146:147]
	s_mov_b32 m0, s88
	v_lshl_add_u64 v[214:215], s[86:87], 0, v[150:151]
	global_load_lds_dwordx4 v[212:213], off
	s_add_i32 m0, s88, 0x2000
	v_lshl_add_u64 v[216:217], s[42:43], 0, v[144:145]
	global_load_lds_dwordx4 v[214:215], off
	s_mov_b32 m0, s48
	v_lshl_add_u64 v[218:219], s[42:43], 0, v[148:149]
	global_load_lds_dwordx4 v[216:217], off
	s_mov_b32 m0, s49
	s_nop 0
	global_load_lds_dwordx4 v[218:219], off
	s_waitcnt vmcnt(8)
	s_waitcnt lgkmcnt(0)
	s_setprio 1
	s_barrier
	v_mfma_f32_16x16x32_bf16 v[92:95], v[128:131], v[176:179], v[92:95]
	v_mfma_f32_16x16x32_bf16 v[88:91], v[136:139], v[176:179], v[88:91]
	v_mfma_f32_16x16x32_bf16 v[84:87], v[128:131], v[184:187], v[84:87]
	v_mfma_f32_16x16x32_bf16 v[80:83], v[136:139], v[184:187], v[80:83]
	v_mfma_f32_16x16x32_bf16 v[76:79], v[128:131], v[192:195], v[76:79]
	v_mfma_f32_16x16x32_bf16 v[72:75], v[136:139], v[192:195], v[72:75]
	v_mfma_f32_16x16x32_bf16 v[68:71], v[128:131], v[200:203], v[68:71]
	v_mfma_f32_16x16x32_bf16 v[64:67], v[136:139], v[200:203], v[64:67]
	v_mfma_f32_16x16x32_bf16 v[92:95], v[132:135], v[180:183], v[92:95]
	v_mfma_f32_16x16x32_bf16 v[88:91], v[140:143], v[180:183], v[88:91]
	v_mfma_f32_16x16x32_bf16 v[84:87], v[132:135], v[188:191], v[84:87]
	v_mfma_f32_16x16x32_bf16 v[80:83], v[140:143], v[188:191], v[80:83]
	v_mfma_f32_16x16x32_bf16 v[76:79], v[132:135], v[196:199], v[76:79]
	v_mfma_f32_16x16x32_bf16 v[72:75], v[140:143], v[196:199], v[72:75]
	v_mfma_f32_16x16x32_bf16 v[68:71], v[132:135], v[204:207], v[68:71]
	v_mfma_f32_16x16x32_bf16 v[64:67], v[140:143], v[204:207], v[64:67]
	v_mfma_f32_16x16x32_bf16 v[28:31], v[160:163], v[176:179], v[28:31]
	v_mfma_f32_16x16x32_bf16 v[24:27], v[168:171], v[176:179], v[24:27]
	v_mfma_f32_16x16x32_bf16 v[20:23], v[160:163], v[184:187], v[20:23]
	v_mfma_f32_16x16x32_bf16 v[16:19], v[168:171], v[184:187], v[16:19]
	v_mfma_f32_16x16x32_bf16 v[12:15], v[160:163], v[192:195], v[12:15]
	v_mfma_f32_16x16x32_bf16 v[8:11], v[168:171], v[192:195], v[8:11]
	v_mfma_f32_16x16x32_bf16 v[4:7], v[160:163], v[200:203], v[4:7]
	v_mfma_f32_16x16x32_bf16 v[0:3], v[168:171], v[200:203], v[0:3]
	v_mfma_f32_16x16x32_bf16 v[28:31], v[164:167], v[180:183], v[28:31]
	v_mfma_f32_16x16x32_bf16 v[24:27], v[172:175], v[180:183], v[24:27]
	v_mfma_f32_16x16x32_bf16 v[20:23], v[164:167], v[188:191], v[20:23]
	v_mfma_f32_16x16x32_bf16 v[16:19], v[172:175], v[188:191], v[16:19]
	v_mfma_f32_16x16x32_bf16 v[12:15], v[164:167], v[196:199], v[12:15]
	v_mfma_f32_16x16x32_bf16 v[8:11], v[172:175], v[196:199], v[8:11]
	v_mfma_f32_16x16x32_bf16 v[4:7], v[164:167], v[204:207], v[4:7]
	v_mfma_f32_16x16x32_bf16 v[0:3], v[172:175], v[204:207], v[0:3]
	s_barrier
	s_setprio 0
	s_add_i32 s86, 0, 0x18000
	s_add_i32 s87, 0, 0x1c000
	v_add_u32_e32 v140, s86, v225
	v_add_u32_e32 v172, s87, v225
	ds_read_b128 v[128:131], v140
	ds_read_b128 v[132:135], v140 offset:1024
	ds_read_b128 v[136:139], v140 offset:2048
	ds_read_b128 v[140:143], v140 offset:3072
	ds_read_b128 v[160:163], v172
	ds_read_b128 v[164:167], v172 offset:1024
	ds_read_b128 v[168:171], v172 offset:2048
	ds_read_b128 v[172:175], v172 offset:3072
	s_add_u32 s42, s42, s10
	s_addc_u32 s43, s43, s11
	s_mov_b32 m0, s54
	v_lshl_add_u64 v[234:235], s[42:43], 0, v[144:145]
	ds_read_b128 v[176:179], v231 offset:32768
	ds_read_b128 v[180:183], v231 offset:33792
	ds_read_b128 v[184:187], v231 offset:34816
	ds_read_b128 v[188:191], v231 offset:35840
	ds_read_b128 v[192:195], v231 offset:36864
	ds_read_b128 v[196:199], v231 offset:37888
	ds_read_b128 v[200:203], v231 offset:38912
	ds_read_b128 v[204:207], v231 offset:39936
	global_load_lds_dwordx4 v[234:235], off
	v_lshl_add_u64 v[234:235], s[42:43], 0, v[148:149]
	s_mov_b32 m0, s55
	s_nop 0
	global_load_lds_dwordx4 v[234:235], off
	s_waitcnt vmcnt(8)
	s_waitcnt lgkmcnt(0)
	s_setprio 1
	s_barrier
	v_mfma_f32_16x16x32_bf16 v[124:127], v[128:131], v[176:179], v[124:127]
	v_mfma_f32_16x16x32_bf16 v[120:123], v[136:139], v[176:179], v[120:123]
	v_mfma_f32_16x16x32_bf16 v[116:119], v[128:131], v[184:187], v[116:119]
	v_mfma_f32_16x16x32_bf16 v[112:115], v[136:139], v[184:187], v[112:115]
	v_mfma_f32_16x16x32_bf16 v[108:111], v[128:131], v[192:195], v[108:111]
	v_mfma_f32_16x16x32_bf16 v[104:107], v[136:139], v[192:195], v[104:107]
	v_mfma_f32_16x16x32_bf16 v[100:103], v[128:131], v[200:203], v[100:103]
	v_mfma_f32_16x16x32_bf16 v[96:99], v[136:139], v[200:203], v[96:99]
	v_mfma_f32_16x16x32_bf16 v[124:127], v[132:135], v[180:183], v[124:127]
	v_mfma_f32_16x16x32_bf16 v[120:123], v[140:143], v[180:183], v[120:123]
	v_mfma_f32_16x16x32_bf16 v[116:119], v[132:135], v[188:191], v[116:119]
	v_mfma_f32_16x16x32_bf16 v[112:115], v[140:143], v[188:191], v[112:115]
	v_mfma_f32_16x16x32_bf16 v[108:111], v[132:135], v[196:199], v[108:111]
	v_mfma_f32_16x16x32_bf16 v[104:107], v[140:143], v[196:199], v[104:107]
	v_mfma_f32_16x16x32_bf16 v[100:103], v[132:135], v[204:207], v[100:103]
	v_mfma_f32_16x16x32_bf16 v[96:99], v[140:143], v[204:207], v[96:99]
	v_mfma_f32_16x16x32_bf16 v[60:63], v[160:163], v[176:179], v[60:63]
	v_mfma_f32_16x16x32_bf16 v[56:59], v[168:171], v[176:179], v[56:59]
	v_mfma_f32_16x16x32_bf16 v[52:55], v[160:163], v[184:187], v[52:55]
	v_mfma_f32_16x16x32_bf16 v[48:51], v[168:171], v[184:187], v[48:51]
	v_mfma_f32_16x16x32_bf16 v[44:47], v[160:163], v[192:195], v[44:47]
	v_mfma_f32_16x16x32_bf16 v[40:43], v[168:171], v[192:195], v[40:43]
	v_mfma_f32_16x16x32_bf16 v[36:39], v[160:163], v[200:203], v[36:39]
	v_mfma_f32_16x16x32_bf16 v[32:35], v[168:171], v[200:203], v[32:35]
	v_mfma_f32_16x16x32_bf16 v[60:63], v[164:167], v[180:183], v[60:63]
	v_mfma_f32_16x16x32_bf16 v[56:59], v[172:175], v[180:183], v[56:59]
	v_mfma_f32_16x16x32_bf16 v[52:55], v[164:167], v[188:191], v[52:55]
	v_mfma_f32_16x16x32_bf16 v[48:51], v[172:175], v[188:191], v[48:51]
	v_mfma_f32_16x16x32_bf16 v[44:47], v[164:167], v[196:199], v[44:47]
	v_mfma_f32_16x16x32_bf16 v[40:43], v[172:175], v[196:199], v[40:43]
	v_mfma_f32_16x16x32_bf16 v[36:39], v[164:167], v[204:207], v[36:39]
	v_mfma_f32_16x16x32_bf16 v[32:35], v[172:175], v[204:207], v[32:35]
	s_barrier
	s_setprio 0
	s_add_i32 s42, s86, s47
	v_lshl_add_u64 v[208:209], v[208:209], 0, s[26:27]
	s_mov_b32 m0, s42
	ds_read_b128 v[176:179], v231 offset:49152
	ds_read_b128 v[180:183], v231 offset:50176
	ds_read_b128 v[184:187], v231 offset:51200
	ds_read_b128 v[188:191], v231 offset:52224
	ds_read_b128 v[192:195], v231 offset:53248
	ds_read_b128 v[196:199], v231 offset:54272
	ds_read_b128 v[200:203], v231 offset:55296
	ds_read_b128 v[204:207], v231 offset:56320
	global_load_lds_dwordx4 v[208:209], off
	v_lshl_add_u64 v[208:209], v[210:211], 0, s[26:27]
	s_add_i32 m0, s42, 0x2000
	s_add_i32 s42, s87, s47
	global_load_lds_dwordx4 v[208:209], off
	v_lshl_add_u64 v[208:209], v[212:213], 0, s[26:27]
	s_mov_b32 m0, s42
	s_nop 0
	global_load_lds_dwordx4 v[208:209], off
	v_lshl_add_u64 v[208:209], v[214:215], 0, s[26:27]
	s_add_i32 m0, s42, 0x2000
	s_nop 0
	global_load_lds_dwordx4 v[208:209], off
	v_lshl_add_u64 v[208:209], v[216:217], 0, s[26:27]
	s_mov_b32 m0, s57
	s_nop 0
	global_load_lds_dwordx4 v[208:209], off
	v_lshl_add_u64 v[208:209], v[218:219], 0, s[26:27]
	s_mov_b32 m0, s58
	s_nop 0
	global_load_lds_dwordx4 v[208:209], off
	s_waitcnt vmcnt(8)
	s_waitcnt lgkmcnt(0)
	s_setprio 1
	s_barrier
	v_mfma_f32_16x16x32_bf16 v[92:95], v[128:131], v[176:179], v[92:95]
	v_mfma_f32_16x16x32_bf16 v[88:91], v[136:139], v[176:179], v[88:91]
	v_mfma_f32_16x16x32_bf16 v[84:87], v[128:131], v[184:187], v[84:87]
	v_mfma_f32_16x16x32_bf16 v[80:83], v[136:139], v[184:187], v[80:83]
	v_mfma_f32_16x16x32_bf16 v[76:79], v[128:131], v[192:195], v[76:79]
	v_mfma_f32_16x16x32_bf16 v[72:75], v[136:139], v[192:195], v[72:75]
	v_mfma_f32_16x16x32_bf16 v[68:71], v[128:131], v[200:203], v[68:71]
	v_mfma_f32_16x16x32_bf16 v[64:67], v[136:139], v[200:203], v[64:67]
	v_mfma_f32_16x16x32_bf16 v[92:95], v[132:135], v[180:183], v[92:95]
	v_mfma_f32_16x16x32_bf16 v[88:91], v[140:143], v[180:183], v[88:91]
	v_mfma_f32_16x16x32_bf16 v[84:87], v[132:135], v[188:191], v[84:87]
	v_mfma_f32_16x16x32_bf16 v[80:83], v[140:143], v[188:191], v[80:83]
	v_mfma_f32_16x16x32_bf16 v[76:79], v[132:135], v[196:199], v[76:79]
	v_mfma_f32_16x16x32_bf16 v[72:75], v[140:143], v[196:199], v[72:75]
	v_mfma_f32_16x16x32_bf16 v[68:71], v[132:135], v[204:207], v[68:71]
	v_mfma_f32_16x16x32_bf16 v[64:67], v[140:143], v[204:207], v[64:67]
	v_mfma_f32_16x16x32_bf16 v[28:31], v[160:163], v[176:179], v[28:31]
	v_mfma_f32_16x16x32_bf16 v[24:27], v[168:171], v[176:179], v[24:27]
	v_mfma_f32_16x16x32_bf16 v[20:23], v[160:163], v[184:187], v[20:23]
	v_mfma_f32_16x16x32_bf16 v[16:19], v[168:171], v[184:187], v[16:19]
	v_mfma_f32_16x16x32_bf16 v[12:15], v[160:163], v[192:195], v[12:15]
	v_mfma_f32_16x16x32_bf16 v[8:11], v[168:171], v[192:195], v[8:11]
	v_mfma_f32_16x16x32_bf16 v[4:7], v[160:163], v[200:203], v[4:7]
	v_mfma_f32_16x16x32_bf16 v[0:3], v[168:171], v[200:203], v[0:3]
	v_mfma_f32_16x16x32_bf16 v[28:31], v[164:167], v[180:183], v[28:31]
	v_mfma_f32_16x16x32_bf16 v[24:27], v[172:175], v[180:183], v[24:27]
	v_mfma_f32_16x16x32_bf16 v[20:23], v[164:167], v[188:191], v[20:23]
	v_mfma_f32_16x16x32_bf16 v[16:19], v[172:175], v[188:191], v[16:19]
	v_mfma_f32_16x16x32_bf16 v[12:15], v[164:167], v[196:199], v[12:15]
	v_mfma_f32_16x16x32_bf16 v[8:11], v[172:175], v[196:199], v[8:11]
	v_mfma_f32_16x16x32_bf16 v[4:7], v[164:167], v[204:207], v[4:7]
	v_mfma_f32_16x16x32_bf16 v[0:3], v[172:175], v[204:207], v[0:3]
	s_barrier
	s_setprio 0
	s_add_u32 s0, s0, 0x100
	s_addc_u32 s1, s1, 0
	s_add_u32 s44, s44, 0x100
	s_addc_u32 s45, s45, 0
	s_cmp_ge_i32 s85, s59
	s_mov_b32 s42, s85
	s_cbranch_scc0 .LBB0_855

.LBB0_956:
	ds_read_b128 v[150:153], v169
	ds_read_b128 v[154:157], v169 offset:1024
	ds_read_b128 v[158:161], v169 offset:2048
	ds_read_b128 v[174:177], v169 offset:3072
	ds_read_b128 v[178:181], v170
	ds_read_b128 v[182:185], v170 offset:1024
	ds_read_b128 v[186:189], v170 offset:2048
	ds_read_b128 v[190:193], v170 offset:3072
	s_add_i32 s95, s10, 2
	s_add_u32 s96, s0, 0x80
	s_addc_u32 s11, s1, 0
	s_cmp_eq_u32 s81, s10
	s_cselect_b32 s10, s48, s96
	s_cselect_b32 s11, s49, s11
	s_cselect_b32 s97, s55, s45
	s_cselect_b32 s96, s54, s44
	v_lshl_add_u64 v[218:219], s[0:1], 0, v[142:143]
	s_add_i32 m0, s58, 0xc000
	ds_read_b128 v[194:197], v171
	ds_read_b128 v[198:201], v171 offset:1024
	ds_read_b128 v[202:205], v171 offset:2048
	ds_read_b128 v[206:209], v171 offset:3072
	ds_read_b128 v[210:213], v171 offset:4096
	ds_read_b128 v[214:217], v171 offset:5120
	ds_read_b128 v[222:225], v171 offset:6144
	ds_read_b128 v[226:229], v171 offset:7168
	global_load_lds_dwordx4 v[218:219], off
	v_lshl_add_u64 v[218:219], s[0:1], 0, v[144:145]
	s_add_i32 m0, s58, 0xe000
	s_nop 0
	global_load_lds_dwordx4 v[218:219], off
	s_waitcnt vmcnt(8)
	s_waitcnt lgkmcnt(0)
	s_setprio 1
	s_barrier
	v_mfma_f32_16x16x32_bf16 v[120:123], v[150:153], v[194:197], v[120:123]
	v_mfma_f32_16x16x32_bf16 v[124:127], v[158:161], v[194:197], v[124:127]
	v_mfma_f32_16x16x32_bf16 v[108:111], v[150:153], v[202:205], v[108:111]
	v_mfma_f32_16x16x32_bf16 v[104:107], v[158:161], v[202:205], v[104:107]
	v_mfma_f32_16x16x32_bf16 v[92:95], v[150:153], v[210:213], v[92:95]
	v_mfma_f32_16x16x32_bf16 v[88:91], v[158:161], v[210:213], v[88:91]
	v_mfma_f32_16x16x32_bf16 v[76:79], v[150:153], v[222:225], v[76:79]
	v_mfma_f32_16x16x32_bf16 v[72:75], v[158:161], v[222:225], v[72:75]
	v_mfma_f32_16x16x32_bf16 v[120:123], v[154:157], v[198:201], v[120:123]
	v_mfma_f32_16x16x32_bf16 v[124:127], v[174:177], v[198:201], v[124:127]
	v_mfma_f32_16x16x32_bf16 v[108:111], v[154:157], v[206:209], v[108:111]
	v_mfma_f32_16x16x32_bf16 v[104:107], v[174:177], v[206:209], v[104:107]
	v_mfma_f32_16x16x32_bf16 v[92:95], v[154:157], v[214:217], v[92:95]
	v_mfma_f32_16x16x32_bf16 v[88:91], v[174:177], v[214:217], v[88:91]
	v_mfma_f32_16x16x32_bf16 v[76:79], v[154:157], v[226:229], v[76:79]
	v_mfma_f32_16x16x32_bf16 v[72:75], v[174:177], v[226:229], v[72:75]
	v_mfma_f32_16x16x32_bf16 v[116:119], v[178:181], v[194:197], v[116:119]
	v_mfma_f32_16x16x32_bf16 v[112:115], v[186:189], v[194:197], v[112:115]
	v_mfma_f32_16x16x32_bf16 v[100:103], v[178:181], v[202:205], v[100:103]
	v_mfma_f32_16x16x32_bf16 v[96:99], v[186:189], v[202:205], v[96:99]
	v_mfma_f32_16x16x32_bf16 v[84:87], v[178:181], v[210:213], v[84:87]
	v_mfma_f32_16x16x32_bf16 v[80:83], v[186:189], v[210:213], v[80:83]
	v_mfma_f32_16x16x32_bf16 v[68:71], v[178:181], v[222:225], v[68:71]
	v_mfma_f32_16x16x32_bf16 v[64:67], v[186:189], v[222:225], v[64:67]
	v_mfma_f32_16x16x32_bf16 v[116:119], v[182:185], v[198:201], v[116:119]
	v_mfma_f32_16x16x32_bf16 v[112:115], v[190:193], v[198:201], v[112:115]
	v_mfma_f32_16x16x32_bf16 v[100:103], v[182:185], v[206:209], v[100:103]
	v_mfma_f32_16x16x32_bf16 v[96:99], v[190:193], v[206:209], v[96:99]
	v_mfma_f32_16x16x32_bf16 v[84:87], v[182:185], v[214:217], v[84:87]
	v_mfma_f32_16x16x32_bf16 v[80:83], v[190:193], v[214:217], v[80:83]
	v_mfma_f32_16x16x32_bf16 v[68:71], v[182:185], v[226:229], v[68:71]
	v_mfma_f32_16x16x32_bf16 v[64:67], v[190:193], v[226:229], v[64:67]
	s_barrier
	s_setprio 0
	s_add_i32 vcc_lo, s84, s57
	v_lshl_add_u64 v[218:219], s[96:97], 0, v[130:131]
	s_mov_b32 m0, vcc_lo
	ds_read_b128 v[194:197], v171 offset:16384
	ds_read_b128 v[198:201], v171 offset:17408
	ds_read_b128 v[202:205], v171 offset:18432
	ds_read_b128 v[206:209], v171 offset:19456
	ds_read_b128 v[210:213], v171 offset:20480
	ds_read_b128 v[214:217], v171 offset:21504
	ds_read_b128 v[222:225], v171 offset:22528
	ds_read_b128 v[226:229], v171 offset:23552
	global_load_lds_dwordx4 v[218:219], off
	s_add_i32 m0, vcc_lo, 0x2000
	v_lshl_add_u64 v[230:231], s[96:97], 0, v[134:135]
	s_add_u32 s96, s96, s22
	s_addc_u32 s97, s97, s23
	s_add_i32 vcc_lo, s85, s57
	global_load_lds_dwordx4 v[230:231], off
	v_lshl_add_u64 v[232:233], s[96:97], 0, v[130:131]
	s_mov_b32 m0, vcc_lo
	v_lshl_add_u64 v[234:235], s[96:97], 0, v[134:135]
	global_load_lds_dwordx4 v[232:233], off
	s_add_i32 m0, vcc_lo, 0x2000
	v_lshl_add_u64 v[236:237], s[10:11], 0, v[128:129]
	global_load_lds_dwordx4 v[234:235], off
	s_mov_b32 m0, s58
	v_lshl_add_u64 v[238:239], s[10:11], 0, v[132:133]
	global_load_lds_dwordx4 v[236:237], off
	s_mov_b32 m0, s59
	s_nop 0
	global_load_lds_dwordx4 v[238:239], off
	s_waitcnt vmcnt(8)
	s_waitcnt lgkmcnt(0)
	s_setprio 1
	s_barrier
	v_mfma_f32_16x16x32_bf16 v[60:63], v[150:153], v[194:197], v[60:63]
	v_mfma_f32_16x16x32_bf16 v[56:59], v[158:161], v[194:197], v[56:59]
	v_mfma_f32_16x16x32_bf16 v[44:47], v[150:153], v[202:205], v[44:47]
	v_mfma_f32_16x16x32_bf16 v[40:43], v[158:161], v[202:205], v[40:43]
	v_mfma_f32_16x16x32_bf16 v[28:31], v[150:153], v[210:213], v[28:31]
	v_mfma_f32_16x16x32_bf16 v[24:27], v[158:161], v[210:213], v[24:27]
	v_mfma_f32_16x16x32_bf16 v[12:15], v[150:153], v[222:225], v[12:15]
	v_mfma_f32_16x16x32_bf16 v[8:11], v[158:161], v[222:225], v[8:11]
	v_mfma_f32_16x16x32_bf16 v[60:63], v[154:157], v[198:201], v[60:63]
	v_mfma_f32_16x16x32_bf16 v[56:59], v[174:177], v[198:201], v[56:59]
	v_mfma_f32_16x16x32_bf16 v[44:47], v[154:157], v[206:209], v[44:47]
	v_mfma_f32_16x16x32_bf16 v[40:43], v[174:177], v[206:209], v[40:43]
	v_mfma_f32_16x16x32_bf16 v[28:31], v[154:157], v[214:217], v[28:31]
	v_mfma_f32_16x16x32_bf16 v[24:27], v[174:177], v[214:217], v[24:27]
	v_mfma_f32_16x16x32_bf16 v[12:15], v[154:157], v[226:229], v[12:15]
	v_mfma_f32_16x16x32_bf16 v[8:11], v[174:177], v[226:229], v[8:11]
	v_mfma_f32_16x16x32_bf16 v[52:55], v[178:181], v[194:197], v[52:55]
	v_mfma_f32_16x16x32_bf16 v[48:51], v[186:189], v[194:197], v[48:51]
	v_mfma_f32_16x16x32_bf16 v[36:39], v[178:181], v[202:205], v[36:39]
	v_mfma_f32_16x16x32_bf16 v[32:35], v[186:189], v[202:205], v[32:35]
	v_mfma_f32_16x16x32_bf16 v[20:23], v[178:181], v[210:213], v[20:23]
	v_mfma_f32_16x16x32_bf16 v[16:19], v[186:189], v[210:213], v[16:19]
	v_mfma_f32_16x16x32_bf16 v[4:7], v[178:181], v[222:225], v[4:7]
	v_mfma_f32_16x16x32_bf16 v[0:3], v[186:189], v[222:225], v[0:3]
	v_mfma_f32_16x16x32_bf16 v[52:55], v[182:185], v[198:201], v[52:55]
	v_mfma_f32_16x16x32_bf16 v[48:51], v[190:193], v[198:201], v[48:51]
	v_mfma_f32_16x16x32_bf16 v[36:39], v[182:185], v[206:209], v[36:39]
	v_mfma_f32_16x16x32_bf16 v[32:35], v[190:193], v[206:209], v[32:35]
	v_mfma_f32_16x16x32_bf16 v[20:23], v[182:185], v[214:217], v[20:23]
	v_mfma_f32_16x16x32_bf16 v[16:19], v[190:193], v[214:217], v[16:19]
	v_mfma_f32_16x16x32_bf16 v[4:7], v[182:185], v[226:229], v[4:7]
	v_mfma_f32_16x16x32_bf16 v[0:3], v[190:193], v[226:229], v[0:3]
	s_barrier
	s_setprio 0
	s_add_i32 s96, 0, 0x18000
	v_add_u32_e32 v173, s96, v164
	s_add_i32 s97, 0, 0x1c000
	ds_read_b128 v[150:153], v173
	ds_read_b128 v[154:157], v173 offset:1024
	ds_read_b128 v[158:161], v173 offset:2048
	ds_read_b128 v[174:177], v173 offset:3072
	v_add_u32_e32 v173, s97, v164
	ds_read_b128 v[178:181], v173
	ds_read_b128 v[182:185], v173 offset:1024
	ds_read_b128 v[186:189], v173 offset:2048
	ds_read_b128 v[190:193], v173 offset:3072
	s_add_u32 s10, s10, s22
	s_addc_u32 s11, s11, s23
	s_mov_b32 m0, s60
	v_lshl_add_u64 v[240:241], s[10:11], 0, v[128:129]
	ds_read_b128 v[194:197], v171 offset:32768
	ds_read_b128 v[198:201], v171 offset:33792
	ds_read_b128 v[202:205], v171 offset:34816
	ds_read_b128 v[206:209], v171 offset:35840
	ds_read_b128 v[210:213], v171 offset:36864
	ds_read_b128 v[214:217], v171 offset:37888
	ds_read_b128 v[222:225], v171 offset:38912
	ds_read_b128 v[226:229], v171 offset:39936
	global_load_lds_dwordx4 v[240:241], off
	v_lshl_add_u64 v[240:241], s[10:11], 0, v[132:133]
	s_mov_b32 m0, s61
	s_nop 0
	global_load_lds_dwordx4 v[240:241], off
	s_waitcnt vmcnt(8)
	s_waitcnt lgkmcnt(0)
	s_setprio 1
	s_barrier
	v_mfma_f32_16x16x32_bf16 v[120:123], v[150:153], v[194:197], v[120:123]
	v_mfma_f32_16x16x32_bf16 v[124:127], v[158:161], v[194:197], v[124:127]
	v_mfma_f32_16x16x32_bf16 v[108:111], v[150:153], v[202:205], v[108:111]
	v_mfma_f32_16x16x32_bf16 v[104:107], v[158:161], v[202:205], v[104:107]
	v_mfma_f32_16x16x32_bf16 v[92:95], v[150:153], v[210:213], v[92:95]
	v_mfma_f32_16x16x32_bf16 v[88:91], v[158:161], v[210:213], v[88:91]
	v_mfma_f32_16x16x32_bf16 v[76:79], v[150:153], v[222:225], v[76:79]
	v_mfma_f32_16x16x32_bf16 v[72:75], v[158:161], v[222:225], v[72:75]
	v_mfma_f32_16x16x32_bf16 v[120:123], v[154:157], v[198:201], v[120:123]
	v_mfma_f32_16x16x32_bf16 v[124:127], v[174:177], v[198:201], v[124:127]
	v_mfma_f32_16x16x32_bf16 v[108:111], v[154:157], v[206:209], v[108:111]
	v_mfma_f32_16x16x32_bf16 v[104:107], v[174:177], v[206:209], v[104:107]
	v_mfma_f32_16x16x32_bf16 v[92:95], v[154:157], v[214:217], v[92:95]
	v_mfma_f32_16x16x32_bf16 v[88:91], v[174:177], v[214:217], v[88:91]
	v_mfma_f32_16x16x32_bf16 v[76:79], v[154:157], v[226:229], v[76:79]
	v_mfma_f32_16x16x32_bf16 v[72:75], v[174:177], v[226:229], v[72:75]
	v_mfma_f32_16x16x32_bf16 v[116:119], v[178:181], v[194:197], v[116:119]
	v_mfma_f32_16x16x32_bf16 v[112:115], v[186:189], v[194:197], v[112:115]
	v_mfma_f32_16x16x32_bf16 v[100:103], v[178:181], v[202:205], v[100:103]
	v_mfma_f32_16x16x32_bf16 v[96:99], v[186:189], v[202:205], v[96:99]
	v_mfma_f32_16x16x32_bf16 v[84:87], v[178:181], v[210:213], v[84:87]
	v_mfma_f32_16x16x32_bf16 v[80:83], v[186:189], v[210:213], v[80:83]
	v_mfma_f32_16x16x32_bf16 v[68:71], v[178:181], v[222:225], v[68:71]
	v_mfma_f32_16x16x32_bf16 v[64:67], v[186:189], v[222:225], v[64:67]
	v_mfma_f32_16x16x32_bf16 v[116:119], v[182:185], v[198:201], v[116:119]
	v_mfma_f32_16x16x32_bf16 v[112:115], v[190:193], v[198:201], v[112:115]
	v_mfma_f32_16x16x32_bf16 v[100:103], v[182:185], v[206:209], v[100:103]
	v_mfma_f32_16x16x32_bf16 v[96:99], v[190:193], v[206:209], v[96:99]
	v_mfma_f32_16x16x32_bf16 v[84:87], v[182:185], v[214:217], v[84:87]
	v_mfma_f32_16x16x32_bf16 v[80:83], v[190:193], v[214:217], v[80:83]
	v_mfma_f32_16x16x32_bf16 v[68:71], v[182:185], v[226:229], v[68:71]
	v_mfma_f32_16x16x32_bf16 v[64:67], v[190:193], v[226:229], v[64:67]
	s_barrier
	s_setprio 0
	s_add_i32 s10, s96, s57
	v_lshl_add_u64 v[218:219], v[218:219], 0, s[34:35]
	s_mov_b32 m0, s10
	ds_read_b128 v[194:197], v171 offset:49152
	ds_read_b128 v[198:201], v171 offset:50176
	ds_read_b128 v[202:205], v171 offset:51200
	ds_read_b128 v[206:209], v171 offset:52224
	ds_read_b128 v[210:213], v171 offset:53248
	ds_read_b128 v[214:217], v171 offset:54272
	ds_read_b128 v[222:225], v171 offset:55296
	ds_read_b128 v[226:229], v171 offset:56320
	global_load_lds_dwordx4 v[218:219], off
	v_lshl_add_u64 v[218:219], v[230:231], 0, s[34:35]
	s_add_i32 m0, s10, 0x2000
	s_add_i32 s10, s97, s57
	global_load_lds_dwordx4 v[218:219], off
	v_lshl_add_u64 v[218:219], v[232:233], 0, s[34:35]
	s_mov_b32 m0, s10
	s_nop 0
	global_load_lds_dwordx4 v[218:219], off
	v_lshl_add_u64 v[218:219], v[234:235], 0, s[34:35]
	s_add_i32 m0, s10, 0x2000
	s_nop 0
	global_load_lds_dwordx4 v[218:219], off
	v_lshl_add_u64 v[218:219], v[236:237], 0, s[34:35]
	s_mov_b32 m0, s63
	s_nop 0
	global_load_lds_dwordx4 v[218:219], off
	v_lshl_add_u64 v[218:219], v[238:239], 0, s[34:35]
	s_mov_b32 m0, s79
	s_nop 0
	global_load_lds_dwordx4 v[218:219], off
	s_waitcnt vmcnt(8)
	s_waitcnt lgkmcnt(0)
	s_setprio 1
	s_barrier
	v_mfma_f32_16x16x32_bf16 v[60:63], v[150:153], v[194:197], v[60:63]
	v_mfma_f32_16x16x32_bf16 v[56:59], v[158:161], v[194:197], v[56:59]
	v_mfma_f32_16x16x32_bf16 v[44:47], v[150:153], v[202:205], v[44:47]
	v_mfma_f32_16x16x32_bf16 v[40:43], v[158:161], v[202:205], v[40:43]
	v_mfma_f32_16x16x32_bf16 v[28:31], v[150:153], v[210:213], v[28:31]
	v_mfma_f32_16x16x32_bf16 v[24:27], v[158:161], v[210:213], v[24:27]
	v_mfma_f32_16x16x32_bf16 v[12:15], v[150:153], v[222:225], v[12:15]
	v_mfma_f32_16x16x32_bf16 v[8:11], v[158:161], v[222:225], v[8:11]
	v_mfma_f32_16x16x32_bf16 v[60:63], v[154:157], v[198:201], v[60:63]
	v_mfma_f32_16x16x32_bf16 v[56:59], v[174:177], v[198:201], v[56:59]
	v_mfma_f32_16x16x32_bf16 v[44:47], v[154:157], v[206:209], v[44:47]
	v_mfma_f32_16x16x32_bf16 v[40:43], v[174:177], v[206:209], v[40:43]
	v_mfma_f32_16x16x32_bf16 v[28:31], v[154:157], v[214:217], v[28:31]
	v_mfma_f32_16x16x32_bf16 v[24:27], v[174:177], v[214:217], v[24:27]
	v_mfma_f32_16x16x32_bf16 v[12:15], v[154:157], v[226:229], v[12:15]
	v_mfma_f32_16x16x32_bf16 v[8:11], v[174:177], v[226:229], v[8:11]
	v_mfma_f32_16x16x32_bf16 v[52:55], v[178:181], v[194:197], v[52:55]
	v_mfma_f32_16x16x32_bf16 v[48:51], v[186:189], v[194:197], v[48:51]
	v_mfma_f32_16x16x32_bf16 v[36:39], v[178:181], v[202:205], v[36:39]
	v_mfma_f32_16x16x32_bf16 v[32:35], v[186:189], v[202:205], v[32:35]
	v_mfma_f32_16x16x32_bf16 v[20:23], v[178:181], v[210:213], v[20:23]
	v_mfma_f32_16x16x32_bf16 v[16:19], v[186:189], v[210:213], v[16:19]
	v_mfma_f32_16x16x32_bf16 v[4:7], v[178:181], v[222:225], v[4:7]
	v_mfma_f32_16x16x32_bf16 v[0:3], v[186:189], v[222:225], v[0:3]
	v_mfma_f32_16x16x32_bf16 v[52:55], v[182:185], v[198:201], v[52:55]
	v_mfma_f32_16x16x32_bf16 v[48:51], v[190:193], v[198:201], v[48:51]
	v_mfma_f32_16x16x32_bf16 v[36:39], v[182:185], v[206:209], v[36:39]
	v_mfma_f32_16x16x32_bf16 v[32:35], v[190:193], v[206:209], v[32:35]
	v_mfma_f32_16x16x32_bf16 v[20:23], v[182:185], v[214:217], v[20:23]
	v_mfma_f32_16x16x32_bf16 v[16:19], v[190:193], v[214:217], v[16:19]
	v_mfma_f32_16x16x32_bf16 v[4:7], v[182:185], v[226:229], v[4:7]
	v_mfma_f32_16x16x32_bf16 v[0:3], v[190:193], v[226:229], v[0:3]
	s_barrier
	s_setprio 0
	s_add_u32 s0, s0, 0x100
	s_addc_u32 s1, s1, 0
	s_add_u32 s44, s44, 0x100
	s_addc_u32 s45, s45, 0
	s_cmp_ge_i32 s95, s80
	s_mov_b32 s10, s95
	s_cbranch_scc0 .LBB0_956

.LBB0_1073:
	ds_read_b128 v[158:161], v152
	ds_read_b128 v[164:167], v152 offset:1024
	ds_read_b128 v[168:171], v152 offset:2048
	ds_read_b128 v[172:175], v152 offset:3072
	ds_read_b128 v[176:179], v153
	ds_read_b128 v[180:183], v153 offset:1024
	ds_read_b128 v[184:187], v153 offset:2048
	ds_read_b128 v[188:191], v153 offset:3072
	s_add_i32 s88, s42, 2
	s_add_u32 s89, s0, 0x80
	s_addc_u32 s43, s1, 0
	s_cmp_eq_u32 s63, s42
	s_cselect_b32 s42, s38, s89
	s_cselect_b32 s43, s39, s43
	s_cselect_b32 s91, s41, s45
	s_cselect_b32 s90, s40, s44
	v_lshl_add_u64 v[148:149], s[0:1], 0, v[138:139]
	s_add_i32 m0, s54, 0xc000
	ds_read_b128 v[192:195], v154
	ds_read_b128 v[196:199], v154 offset:1024
	ds_read_b128 v[200:203], v154 offset:2048
	ds_read_b128 v[204:207], v154 offset:3072
	ds_read_b128 v[208:211], v154 offset:4096
	ds_read_b128 v[212:215], v154 offset:5120
	ds_read_b128 v[216:219], v154 offset:6144
	ds_read_b128 v[222:225], v154 offset:7168
	global_load_lds_dwordx4 v[148:149], off
	v_lshl_add_u64 v[148:149], s[0:1], 0, v[140:141]
	s_add_i32 m0, s54, 0xe000
	s_nop 0
	global_load_lds_dwordx4 v[148:149], off
	s_waitcnt vmcnt(8)
	s_waitcnt lgkmcnt(0)
	s_setprio 1
	s_barrier
	v_mfma_f32_16x16x32_bf16 v[120:123], v[158:161], v[192:195], v[120:123]
	v_mfma_f32_16x16x32_bf16 v[124:127], v[168:171], v[192:195], v[124:127]
	v_mfma_f32_16x16x32_bf16 v[108:111], v[158:161], v[200:203], v[108:111]
	v_mfma_f32_16x16x32_bf16 v[104:107], v[168:171], v[200:203], v[104:107]
	v_mfma_f32_16x16x32_bf16 v[92:95], v[158:161], v[208:211], v[92:95]
	v_mfma_f32_16x16x32_bf16 v[88:91], v[168:171], v[208:211], v[88:91]
	v_mfma_f32_16x16x32_bf16 v[76:79], v[158:161], v[216:219], v[76:79]
	v_mfma_f32_16x16x32_bf16 v[72:75], v[168:171], v[216:219], v[72:75]
	v_mfma_f32_16x16x32_bf16 v[120:123], v[164:167], v[196:199], v[120:123]
	v_mfma_f32_16x16x32_bf16 v[124:127], v[172:175], v[196:199], v[124:127]
	v_mfma_f32_16x16x32_bf16 v[108:111], v[164:167], v[204:207], v[108:111]
	v_mfma_f32_16x16x32_bf16 v[104:107], v[172:175], v[204:207], v[104:107]
	v_mfma_f32_16x16x32_bf16 v[92:95], v[164:167], v[212:215], v[92:95]
	v_mfma_f32_16x16x32_bf16 v[88:91], v[172:175], v[212:215], v[88:91]
	v_mfma_f32_16x16x32_bf16 v[76:79], v[164:167], v[222:225], v[76:79]
	v_mfma_f32_16x16x32_bf16 v[72:75], v[172:175], v[222:225], v[72:75]
	v_mfma_f32_16x16x32_bf16 v[116:119], v[176:179], v[192:195], v[116:119]
	v_mfma_f32_16x16x32_bf16 v[112:115], v[184:187], v[192:195], v[112:115]
	v_mfma_f32_16x16x32_bf16 v[100:103], v[176:179], v[200:203], v[100:103]
	v_mfma_f32_16x16x32_bf16 v[96:99], v[184:187], v[200:203], v[96:99]
	v_mfma_f32_16x16x32_bf16 v[84:87], v[176:179], v[208:211], v[84:87]
	v_mfma_f32_16x16x32_bf16 v[80:83], v[184:187], v[208:211], v[80:83]
	v_mfma_f32_16x16x32_bf16 v[68:71], v[176:179], v[216:219], v[68:71]
	v_mfma_f32_16x16x32_bf16 v[64:67], v[184:187], v[216:219], v[64:67]
	v_mfma_f32_16x16x32_bf16 v[116:119], v[180:183], v[196:199], v[116:119]
	v_mfma_f32_16x16x32_bf16 v[112:115], v[188:191], v[196:199], v[112:115]
	v_mfma_f32_16x16x32_bf16 v[100:103], v[180:183], v[204:207], v[100:103]
	v_mfma_f32_16x16x32_bf16 v[96:99], v[188:191], v[204:207], v[96:99]
	v_mfma_f32_16x16x32_bf16 v[84:87], v[180:183], v[212:215], v[84:87]
	v_mfma_f32_16x16x32_bf16 v[80:83], v[188:191], v[212:215], v[80:83]
	v_mfma_f32_16x16x32_bf16 v[68:71], v[180:183], v[222:225], v[68:71]
	v_mfma_f32_16x16x32_bf16 v[64:67], v[188:191], v[222:225], v[64:67]
	s_barrier
	s_setprio 0
	s_add_i32 s89, s81, s49
	v_lshl_add_u64 v[148:149], s[90:91], 0, v[130:131]
	s_mov_b32 m0, s89
	ds_read_b128 v[192:195], v154 offset:16384
	ds_read_b128 v[196:199], v154 offset:17408
	ds_read_b128 v[200:203], v154 offset:18432
	ds_read_b128 v[204:207], v154 offset:19456
	ds_read_b128 v[208:211], v154 offset:20480
	ds_read_b128 v[212:215], v154 offset:21504
	ds_read_b128 v[216:219], v154 offset:22528
	ds_read_b128 v[222:225], v154 offset:23552
	global_load_lds_dwordx4 v[148:149], off
	s_add_i32 m0, s89, 0x2000
	v_lshl_add_u64 v[226:227], s[90:91], 0, v[134:135]
	s_add_u32 s90, s90, s10
	s_addc_u32 s91, s91, s11
	s_add_i32 s89, s82, s49
	global_load_lds_dwordx4 v[226:227], off
	v_lshl_add_u64 v[228:229], s[90:91], 0, v[130:131]
	s_mov_b32 m0, s89
	v_lshl_add_u64 v[230:231], s[90:91], 0, v[134:135]
	global_load_lds_dwordx4 v[228:229], off
	s_add_i32 m0, s89, 0x2000
	v_lshl_add_u64 v[232:233], s[42:43], 0, v[128:129]
	global_load_lds_dwordx4 v[230:231], off
	s_mov_b32 m0, s54
	v_lshl_add_u64 v[234:235], s[42:43], 0, v[132:133]
	global_load_lds_dwordx4 v[232:233], off
	s_mov_b32 m0, s55
	s_nop 0
	global_load_lds_dwordx4 v[234:235], off
	s_waitcnt vmcnt(8)
	s_waitcnt lgkmcnt(0)
	s_setprio 1
	s_barrier
	v_mfma_f32_16x16x32_bf16 v[60:63], v[158:161], v[192:195], v[60:63]
	v_mfma_f32_16x16x32_bf16 v[56:59], v[168:171], v[192:195], v[56:59]
	v_mfma_f32_16x16x32_bf16 v[44:47], v[158:161], v[200:203], v[44:47]
	v_mfma_f32_16x16x32_bf16 v[40:43], v[168:171], v[200:203], v[40:43]
	v_mfma_f32_16x16x32_bf16 v[28:31], v[158:161], v[208:211], v[28:31]
	v_mfma_f32_16x16x32_bf16 v[24:27], v[168:171], v[208:211], v[24:27]
	v_mfma_f32_16x16x32_bf16 v[12:15], v[158:161], v[216:219], v[12:15]
	v_mfma_f32_16x16x32_bf16 v[8:11], v[168:171], v[216:219], v[8:11]
	v_mfma_f32_16x16x32_bf16 v[60:63], v[164:167], v[196:199], v[60:63]
	v_mfma_f32_16x16x32_bf16 v[56:59], v[172:175], v[196:199], v[56:59]
	v_mfma_f32_16x16x32_bf16 v[44:47], v[164:167], v[204:207], v[44:47]
	v_mfma_f32_16x16x32_bf16 v[40:43], v[172:175], v[204:207], v[40:43]
	v_mfma_f32_16x16x32_bf16 v[28:31], v[164:167], v[212:215], v[28:31]
	v_mfma_f32_16x16x32_bf16 v[24:27], v[172:175], v[212:215], v[24:27]
	v_mfma_f32_16x16x32_bf16 v[12:15], v[164:167], v[222:225], v[12:15]
	v_mfma_f32_16x16x32_bf16 v[8:11], v[172:175], v[222:225], v[8:11]
	v_mfma_f32_16x16x32_bf16 v[52:55], v[176:179], v[192:195], v[52:55]
	v_mfma_f32_16x16x32_bf16 v[48:51], v[184:187], v[192:195], v[48:51]
	v_mfma_f32_16x16x32_bf16 v[36:39], v[176:179], v[200:203], v[36:39]
	v_mfma_f32_16x16x32_bf16 v[32:35], v[184:187], v[200:203], v[32:35]
	v_mfma_f32_16x16x32_bf16 v[20:23], v[176:179], v[208:211], v[20:23]
	v_mfma_f32_16x16x32_bf16 v[16:19], v[184:187], v[208:211], v[16:19]
	v_mfma_f32_16x16x32_bf16 v[4:7], v[176:179], v[216:219], v[4:7]
	v_mfma_f32_16x16x32_bf16 v[0:3], v[184:187], v[216:219], v[0:3]
	v_mfma_f32_16x16x32_bf16 v[52:55], v[180:183], v[196:199], v[52:55]
	v_mfma_f32_16x16x32_bf16 v[48:51], v[188:191], v[196:199], v[48:51]
	v_mfma_f32_16x16x32_bf16 v[36:39], v[180:183], v[204:207], v[36:39]
	v_mfma_f32_16x16x32_bf16 v[32:35], v[188:191], v[204:207], v[32:35]
	v_mfma_f32_16x16x32_bf16 v[20:23], v[180:183], v[212:215], v[20:23]
	v_mfma_f32_16x16x32_bf16 v[16:19], v[188:191], v[212:215], v[16:19]
	v_mfma_f32_16x16x32_bf16 v[4:7], v[180:183], v[222:225], v[4:7]
	v_mfma_f32_16x16x32_bf16 v[0:3], v[188:191], v[222:225], v[0:3]
	s_barrier
	s_setprio 0
	s_add_i32 s89, 0, 0x18000
	v_add_u32_e32 v136, s89, v151
	s_add_i32 s90, 0, 0x1c000
	ds_read_b128 v[158:161], v136
	ds_read_b128 v[164:167], v136 offset:1024
	ds_read_b128 v[168:171], v136 offset:2048
	ds_read_b128 v[172:175], v136 offset:3072
	v_add_u32_e32 v136, s90, v151
	ds_read_b128 v[176:179], v136
	ds_read_b128 v[180:183], v136 offset:1024
	ds_read_b128 v[184:187], v136 offset:2048
	ds_read_b128 v[188:191], v136 offset:3072
	s_add_u32 s42, s42, s10
	s_addc_u32 s43, s43, s11
	s_mov_b32 m0, s56
	v_lshl_add_u64 v[236:237], s[42:43], 0, v[128:129]
	ds_read_b128 v[192:195], v154 offset:32768
	ds_read_b128 v[196:199], v154 offset:33792
	ds_read_b128 v[200:203], v154 offset:34816
	ds_read_b128 v[204:207], v154 offset:35840
	ds_read_b128 v[208:211], v154 offset:36864
	ds_read_b128 v[212:215], v154 offset:37888
	ds_read_b128 v[216:219], v154 offset:38912
	ds_read_b128 v[222:225], v154 offset:39936
	global_load_lds_dwordx4 v[236:237], off
	v_lshl_add_u64 v[236:237], s[42:43], 0, v[132:133]
	s_mov_b32 m0, s57
	s_nop 0
	global_load_lds_dwordx4 v[236:237], off
	s_waitcnt vmcnt(8)
	s_waitcnt lgkmcnt(0)
	s_setprio 1
	s_barrier
	v_mfma_f32_16x16x32_bf16 v[120:123], v[158:161], v[192:195], v[120:123]
	v_mfma_f32_16x16x32_bf16 v[124:127], v[168:171], v[192:195], v[124:127]
	v_mfma_f32_16x16x32_bf16 v[108:111], v[158:161], v[200:203], v[108:111]
	v_mfma_f32_16x16x32_bf16 v[104:107], v[168:171], v[200:203], v[104:107]
	v_mfma_f32_16x16x32_bf16 v[92:95], v[158:161], v[208:211], v[92:95]
	v_mfma_f32_16x16x32_bf16 v[88:91], v[168:171], v[208:211], v[88:91]
	v_mfma_f32_16x16x32_bf16 v[76:79], v[158:161], v[216:219], v[76:79]
	v_mfma_f32_16x16x32_bf16 v[72:75], v[168:171], v[216:219], v[72:75]
	v_mfma_f32_16x16x32_bf16 v[120:123], v[164:167], v[196:199], v[120:123]
	v_mfma_f32_16x16x32_bf16 v[124:127], v[172:175], v[196:199], v[124:127]
	v_mfma_f32_16x16x32_bf16 v[108:111], v[164:167], v[204:207], v[108:111]
	v_mfma_f32_16x16x32_bf16 v[104:107], v[172:175], v[204:207], v[104:107]
	v_mfma_f32_16x16x32_bf16 v[92:95], v[164:167], v[212:215], v[92:95]
	v_mfma_f32_16x16x32_bf16 v[88:91], v[172:175], v[212:215], v[88:91]
	v_mfma_f32_16x16x32_bf16 v[76:79], v[164:167], v[222:225], v[76:79]
	v_mfma_f32_16x16x32_bf16 v[72:75], v[172:175], v[222:225], v[72:75]
	v_mfma_f32_16x16x32_bf16 v[116:119], v[176:179], v[192:195], v[116:119]
	v_mfma_f32_16x16x32_bf16 v[112:115], v[184:187], v[192:195], v[112:115]
	v_mfma_f32_16x16x32_bf16 v[100:103], v[176:179], v[200:203], v[100:103]
	v_mfma_f32_16x16x32_bf16 v[96:99], v[184:187], v[200:203], v[96:99]
	v_mfma_f32_16x16x32_bf16 v[84:87], v[176:179], v[208:211], v[84:87]
	v_mfma_f32_16x16x32_bf16 v[80:83], v[184:187], v[208:211], v[80:83]
	v_mfma_f32_16x16x32_bf16 v[68:71], v[176:179], v[216:219], v[68:71]
	v_mfma_f32_16x16x32_bf16 v[64:67], v[184:187], v[216:219], v[64:67]
	v_mfma_f32_16x16x32_bf16 v[116:119], v[180:183], v[196:199], v[116:119]
	v_mfma_f32_16x16x32_bf16 v[112:115], v[188:191], v[196:199], v[112:115]
	v_mfma_f32_16x16x32_bf16 v[100:103], v[180:183], v[204:207], v[100:103]
	v_mfma_f32_16x16x32_bf16 v[96:99], v[188:191], v[204:207], v[96:99]
	v_mfma_f32_16x16x32_bf16 v[84:87], v[180:183], v[212:215], v[84:87]
	v_mfma_f32_16x16x32_bf16 v[80:83], v[188:191], v[212:215], v[80:83]
	v_mfma_f32_16x16x32_bf16 v[68:71], v[180:183], v[222:225], v[68:71]
	v_mfma_f32_16x16x32_bf16 v[64:67], v[188:191], v[222:225], v[64:67]
	s_barrier
	s_setprio 0
	s_add_i32 s42, s89, s49
	v_lshl_add_u64 v[148:149], v[148:149], 0, s[30:31]
	s_mov_b32 m0, s42
	ds_read_b128 v[192:195], v154 offset:49152
	ds_read_b128 v[196:199], v154 offset:50176
	ds_read_b128 v[200:203], v154 offset:51200
	ds_read_b128 v[204:207], v154 offset:52224
	ds_read_b128 v[208:211], v154 offset:53248
	ds_read_b128 v[212:215], v154 offset:54272
	ds_read_b128 v[216:219], v154 offset:55296
	ds_read_b128 v[222:225], v154 offset:56320
	global_load_lds_dwordx4 v[148:149], off
	v_lshl_add_u64 v[148:149], v[226:227], 0, s[30:31]
	s_add_i32 m0, s42, 0x2000
	s_add_i32 s42, s90, s49
	global_load_lds_dwordx4 v[148:149], off
	v_lshl_add_u64 v[148:149], v[228:229], 0, s[30:31]
	s_mov_b32 m0, s42
	s_nop 0
	global_load_lds_dwordx4 v[148:149], off
	v_lshl_add_u64 v[148:149], v[230:231], 0, s[30:31]
	s_add_i32 m0, s42, 0x2000
	s_nop 0
	global_load_lds_dwordx4 v[148:149], off
	v_lshl_add_u64 v[148:149], v[232:233], 0, s[30:31]
	s_mov_b32 m0, s59
	s_nop 0
	global_load_lds_dwordx4 v[148:149], off
	v_lshl_add_u64 v[148:149], v[234:235], 0, s[30:31]
	s_mov_b32 m0, s60
	s_nop 0
	global_load_lds_dwordx4 v[148:149], off
	s_waitcnt vmcnt(8)
	s_waitcnt lgkmcnt(0)
	s_setprio 1
	s_barrier
	v_mfma_f32_16x16x32_bf16 v[60:63], v[158:161], v[192:195], v[60:63]
	v_mfma_f32_16x16x32_bf16 v[56:59], v[168:171], v[192:195], v[56:59]
	v_mfma_f32_16x16x32_bf16 v[44:47], v[158:161], v[200:203], v[44:47]
	v_mfma_f32_16x16x32_bf16 v[40:43], v[168:171], v[200:203], v[40:43]
	v_mfma_f32_16x16x32_bf16 v[28:31], v[158:161], v[208:211], v[28:31]
	v_mfma_f32_16x16x32_bf16 v[24:27], v[168:171], v[208:211], v[24:27]
	v_mfma_f32_16x16x32_bf16 v[12:15], v[158:161], v[216:219], v[12:15]
	v_mfma_f32_16x16x32_bf16 v[8:11], v[168:171], v[216:219], v[8:11]
	v_mfma_f32_16x16x32_bf16 v[60:63], v[164:167], v[196:199], v[60:63]
	v_mfma_f32_16x16x32_bf16 v[56:59], v[172:175], v[196:199], v[56:59]
	v_mfma_f32_16x16x32_bf16 v[44:47], v[164:167], v[204:207], v[44:47]
	v_mfma_f32_16x16x32_bf16 v[40:43], v[172:175], v[204:207], v[40:43]
	v_mfma_f32_16x16x32_bf16 v[28:31], v[164:167], v[212:215], v[28:31]
	v_mfma_f32_16x16x32_bf16 v[24:27], v[172:175], v[212:215], v[24:27]
	v_mfma_f32_16x16x32_bf16 v[12:15], v[164:167], v[222:225], v[12:15]
	v_mfma_f32_16x16x32_bf16 v[8:11], v[172:175], v[222:225], v[8:11]
	v_mfma_f32_16x16x32_bf16 v[52:55], v[176:179], v[192:195], v[52:55]
	v_mfma_f32_16x16x32_bf16 v[48:51], v[184:187], v[192:195], v[48:51]
	v_mfma_f32_16x16x32_bf16 v[36:39], v[176:179], v[200:203], v[36:39]
	v_mfma_f32_16x16x32_bf16 v[32:35], v[184:187], v[200:203], v[32:35]
	v_mfma_f32_16x16x32_bf16 v[20:23], v[176:179], v[208:211], v[20:23]
	v_mfma_f32_16x16x32_bf16 v[16:19], v[184:187], v[208:211], v[16:19]
	v_mfma_f32_16x16x32_bf16 v[4:7], v[176:179], v[216:219], v[4:7]
	v_mfma_f32_16x16x32_bf16 v[0:3], v[184:187], v[216:219], v[0:3]
	v_mfma_f32_16x16x32_bf16 v[52:55], v[180:183], v[196:199], v[52:55]
	v_mfma_f32_16x16x32_bf16 v[48:51], v[188:191], v[196:199], v[48:51]
	v_mfma_f32_16x16x32_bf16 v[36:39], v[180:183], v[204:207], v[36:39]
	v_mfma_f32_16x16x32_bf16 v[32:35], v[188:191], v[204:207], v[32:35]
	v_mfma_f32_16x16x32_bf16 v[20:23], v[180:183], v[212:215], v[20:23]
	v_mfma_f32_16x16x32_bf16 v[16:19], v[188:191], v[212:215], v[16:19]
	v_mfma_f32_16x16x32_bf16 v[4:7], v[180:183], v[222:225], v[4:7]
	v_mfma_f32_16x16x32_bf16 v[0:3], v[188:191], v[222:225], v[0:3]
	s_barrier
	s_setprio 0
	s_add_u32 s0, s0, 0x100
	s_addc_u32 s1, s1, 0
	s_add_u32 s44, s44, 0x100
	s_addc_u32 s45, s45, 0
	s_cmp_ge_i32 s88, s61
	s_mov_b32 s42, s88
	s_cbranch_scc0 .LBB0_1073

.LBB0_1096:
	ds_read_b128 v[146:149], v157
	ds_read_b128 v[150:153], v157 offset:1024
	ds_read_b128 v[164:167], v157 offset:2048
	ds_read_b128 v[168:171], v157 offset:3072
	ds_read_b128 v[172:175], v158
	ds_read_b128 v[176:179], v158 offset:1024
	ds_read_b128 v[180:183], v158 offset:2048
	ds_read_b128 v[184:187], v158 offset:3072
	s_add_i32 s44, s8, 2
	s_add_u32 s45, s0, 0x80
	s_addc_u32 s9, s1, 0
	s_cmp_eq_u32 s77, s8
	s_cselect_b32 s8, s40, s45
	s_cselect_b32 s9, s41, s9
	s_cselect_b32 s93, s43, s11
	s_cselect_b32 s92, s42, s10
	v_lshl_add_u64 v[222:223], s[0:1], 0, v[138:139]
	s_add_i32 m0, s55, 0xc000
	ds_read_b128 v[188:191], v159
	ds_read_b128 v[192:195], v159 offset:1024
	ds_read_b128 v[196:199], v159 offset:2048
	ds_read_b128 v[200:203], v159 offset:3072
	ds_read_b128 v[204:207], v159 offset:4096
	ds_read_b128 v[208:211], v159 offset:5120
	ds_read_b128 v[212:215], v159 offset:6144
	ds_read_b128 v[216:219], v159 offset:7168
	global_load_lds_dwordx4 v[222:223], off
	v_lshl_add_u64 v[222:223], s[0:1], 0, v[140:141]
	s_add_i32 m0, s55, 0xe000
	s_nop 0
	global_load_lds_dwordx4 v[222:223], off
	s_waitcnt vmcnt(8)
	s_waitcnt lgkmcnt(0)
	s_setprio 1
	s_barrier
	v_mfma_f32_16x16x32_bf16 v[120:123], v[146:149], v[188:191], v[120:123]
	v_mfma_f32_16x16x32_bf16 v[124:127], v[164:167], v[188:191], v[124:127]
	v_mfma_f32_16x16x32_bf16 v[108:111], v[146:149], v[196:199], v[108:111]
	v_mfma_f32_16x16x32_bf16 v[104:107], v[164:167], v[196:199], v[104:107]
	v_mfma_f32_16x16x32_bf16 v[92:95], v[146:149], v[204:207], v[92:95]
	v_mfma_f32_16x16x32_bf16 v[88:91], v[164:167], v[204:207], v[88:91]
	v_mfma_f32_16x16x32_bf16 v[76:79], v[146:149], v[212:215], v[76:79]
	v_mfma_f32_16x16x32_bf16 v[72:75], v[164:167], v[212:215], v[72:75]
	v_mfma_f32_16x16x32_bf16 v[120:123], v[150:153], v[192:195], v[120:123]
	v_mfma_f32_16x16x32_bf16 v[124:127], v[168:171], v[192:195], v[124:127]
	v_mfma_f32_16x16x32_bf16 v[108:111], v[150:153], v[200:203], v[108:111]
	v_mfma_f32_16x16x32_bf16 v[104:107], v[168:171], v[200:203], v[104:107]
	v_mfma_f32_16x16x32_bf16 v[92:95], v[150:153], v[208:211], v[92:95]
	v_mfma_f32_16x16x32_bf16 v[88:91], v[168:171], v[208:211], v[88:91]
	v_mfma_f32_16x16x32_bf16 v[76:79], v[150:153], v[216:219], v[76:79]
	v_mfma_f32_16x16x32_bf16 v[72:75], v[168:171], v[216:219], v[72:75]
	v_mfma_f32_16x16x32_bf16 v[116:119], v[172:175], v[188:191], v[116:119]
	v_mfma_f32_16x16x32_bf16 v[112:115], v[180:183], v[188:191], v[112:115]
	v_mfma_f32_16x16x32_bf16 v[100:103], v[172:175], v[196:199], v[100:103]
	v_mfma_f32_16x16x32_bf16 v[96:99], v[180:183], v[196:199], v[96:99]
	v_mfma_f32_16x16x32_bf16 v[84:87], v[172:175], v[204:207], v[84:87]
	v_mfma_f32_16x16x32_bf16 v[80:83], v[180:183], v[204:207], v[80:83]
	v_mfma_f32_16x16x32_bf16 v[68:71], v[172:175], v[212:215], v[68:71]
	v_mfma_f32_16x16x32_bf16 v[64:67], v[180:183], v[212:215], v[64:67]
	v_mfma_f32_16x16x32_bf16 v[116:119], v[176:179], v[192:195], v[116:119]
	v_mfma_f32_16x16x32_bf16 v[112:115], v[184:187], v[192:195], v[112:115]
	v_mfma_f32_16x16x32_bf16 v[100:103], v[176:179], v[200:203], v[100:103]
	v_mfma_f32_16x16x32_bf16 v[96:99], v[184:187], v[200:203], v[96:99]
	v_mfma_f32_16x16x32_bf16 v[84:87], v[176:179], v[208:211], v[84:87]
	v_mfma_f32_16x16x32_bf16 v[80:83], v[184:187], v[208:211], v[80:83]
	v_mfma_f32_16x16x32_bf16 v[68:71], v[176:179], v[216:219], v[68:71]
	v_mfma_f32_16x16x32_bf16 v[64:67], v[184:187], v[216:219], v[64:67]
	s_barrier
	s_setprio 0
	s_add_i32 s45, s82, s54
	v_lshl_add_u64 v[222:223], s[92:93], 0, v[130:131]
	s_mov_b32 m0, s45
	ds_read_b128 v[188:191], v159 offset:16384
	ds_read_b128 v[192:195], v159 offset:17408
	ds_read_b128 v[196:199], v159 offset:18432
	ds_read_b128 v[200:203], v159 offset:19456
	ds_read_b128 v[204:207], v159 offset:20480
	ds_read_b128 v[208:211], v159 offset:21504
	ds_read_b128 v[212:215], v159 offset:22528
	ds_read_b128 v[216:219], v159 offset:23552
	global_load_lds_dwordx4 v[222:223], off
	s_add_i32 m0, s45, 0x2000
	v_lshl_add_u64 v[224:225], s[92:93], 0, v[134:135]
	s_add_u32 s92, s92, s26
	s_addc_u32 s93, s93, s27
	s_add_i32 s45, s83, s54
	global_load_lds_dwordx4 v[224:225], off
	v_lshl_add_u64 v[226:227], s[92:93], 0, v[130:131]
	s_mov_b32 m0, s45
	v_lshl_add_u64 v[228:229], s[92:93], 0, v[134:135]
	global_load_lds_dwordx4 v[226:227], off
	s_add_i32 m0, s45, 0x2000
	v_lshl_add_u64 v[230:231], s[8:9], 0, v[128:129]
	global_load_lds_dwordx4 v[228:229], off
	s_mov_b32 m0, s55
	v_lshl_add_u64 v[232:233], s[8:9], 0, v[132:133]
	global_load_lds_dwordx4 v[230:231], off
	s_mov_b32 m0, s56
	s_nop 0
	global_load_lds_dwordx4 v[232:233], off
	s_waitcnt vmcnt(8)
	s_waitcnt lgkmcnt(0)
	s_setprio 1
	s_barrier
	v_mfma_f32_16x16x32_bf16 v[60:63], v[146:149], v[188:191], v[60:63]
	v_mfma_f32_16x16x32_bf16 v[56:59], v[164:167], v[188:191], v[56:59]
	v_mfma_f32_16x16x32_bf16 v[44:47], v[146:149], v[196:199], v[44:47]
	v_mfma_f32_16x16x32_bf16 v[40:43], v[164:167], v[196:199], v[40:43]
	v_mfma_f32_16x16x32_bf16 v[28:31], v[146:149], v[204:207], v[28:31]
	v_mfma_f32_16x16x32_bf16 v[24:27], v[164:167], v[204:207], v[24:27]
	v_mfma_f32_16x16x32_bf16 v[12:15], v[146:149], v[212:215], v[12:15]
	v_mfma_f32_16x16x32_bf16 v[8:11], v[164:167], v[212:215], v[8:11]
	v_mfma_f32_16x16x32_bf16 v[60:63], v[150:153], v[192:195], v[60:63]
	v_mfma_f32_16x16x32_bf16 v[56:59], v[168:171], v[192:195], v[56:59]
	v_mfma_f32_16x16x32_bf16 v[44:47], v[150:153], v[200:203], v[44:47]
	v_mfma_f32_16x16x32_bf16 v[40:43], v[168:171], v[200:203], v[40:43]
	v_mfma_f32_16x16x32_bf16 v[28:31], v[150:153], v[208:211], v[28:31]
	v_mfma_f32_16x16x32_bf16 v[24:27], v[168:171], v[208:211], v[24:27]
	v_mfma_f32_16x16x32_bf16 v[12:15], v[150:153], v[216:219], v[12:15]
	v_mfma_f32_16x16x32_bf16 v[8:11], v[168:171], v[216:219], v[8:11]
	v_mfma_f32_16x16x32_bf16 v[52:55], v[172:175], v[188:191], v[52:55]
	v_mfma_f32_16x16x32_bf16 v[48:51], v[180:183], v[188:191], v[48:51]
	v_mfma_f32_16x16x32_bf16 v[36:39], v[172:175], v[196:199], v[36:39]
	v_mfma_f32_16x16x32_bf16 v[32:35], v[180:183], v[196:199], v[32:35]
	v_mfma_f32_16x16x32_bf16 v[20:23], v[172:175], v[204:207], v[20:23]
	v_mfma_f32_16x16x32_bf16 v[16:19], v[180:183], v[204:207], v[16:19]
	v_mfma_f32_16x16x32_bf16 v[4:7], v[172:175], v[212:215], v[4:7]
	v_mfma_f32_16x16x32_bf16 v[0:3], v[180:183], v[212:215], v[0:3]
	v_mfma_f32_16x16x32_bf16 v[52:55], v[176:179], v[192:195], v[52:55]
	v_mfma_f32_16x16x32_bf16 v[48:51], v[184:187], v[192:195], v[48:51]
	v_mfma_f32_16x16x32_bf16 v[36:39], v[176:179], v[200:203], v[36:39]
	v_mfma_f32_16x16x32_bf16 v[32:35], v[184:187], v[200:203], v[32:35]
	v_mfma_f32_16x16x32_bf16 v[20:23], v[176:179], v[208:211], v[20:23]
	v_mfma_f32_16x16x32_bf16 v[16:19], v[184:187], v[208:211], v[16:19]
	v_mfma_f32_16x16x32_bf16 v[4:7], v[176:179], v[216:219], v[4:7]
	v_mfma_f32_16x16x32_bf16 v[0:3], v[184:187], v[216:219], v[0:3]
	s_barrier
	s_setprio 0
	s_add_i32 s45, 0, 0x18000
	v_add_u32_e32 v136, s45, v155
	s_add_i32 s92, 0, 0x1c000
	ds_read_b128 v[146:149], v136
	ds_read_b128 v[150:153], v136 offset:1024
	ds_read_b128 v[164:167], v136 offset:2048
	ds_read_b128 v[168:171], v136 offset:3072
	v_add_u32_e32 v136, s92, v155
	ds_read_b128 v[172:175], v136
	ds_read_b128 v[176:179], v136 offset:1024
	ds_read_b128 v[180:183], v136 offset:2048
	ds_read_b128 v[184:187], v136 offset:3072
	s_add_u32 s8, s8, s26
	s_addc_u32 s9, s9, s27
	s_mov_b32 m0, s57
	v_lshl_add_u64 v[234:235], s[8:9], 0, v[128:129]
	ds_read_b128 v[188:191], v159 offset:32768
	ds_read_b128 v[192:195], v159 offset:33792
	ds_read_b128 v[196:199], v159 offset:34816
	ds_read_b128 v[200:203], v159 offset:35840
	ds_read_b128 v[204:207], v159 offset:36864
	ds_read_b128 v[208:211], v159 offset:37888
	ds_read_b128 v[212:215], v159 offset:38912
	ds_read_b128 v[216:219], v159 offset:39936
	global_load_lds_dwordx4 v[234:235], off
	v_lshl_add_u64 v[234:235], s[8:9], 0, v[132:133]
	s_mov_b32 m0, s58
	s_nop 0
	global_load_lds_dwordx4 v[234:235], off
	s_waitcnt vmcnt(8)
	s_waitcnt lgkmcnt(0)
	s_setprio 1
	s_barrier
	v_mfma_f32_16x16x32_bf16 v[120:123], v[146:149], v[188:191], v[120:123]
	v_mfma_f32_16x16x32_bf16 v[124:127], v[164:167], v[188:191], v[124:127]
	v_mfma_f32_16x16x32_bf16 v[108:111], v[146:149], v[196:199], v[108:111]
	v_mfma_f32_16x16x32_bf16 v[104:107], v[164:167], v[196:199], v[104:107]
	v_mfma_f32_16x16x32_bf16 v[92:95], v[146:149], v[204:207], v[92:95]
	v_mfma_f32_16x16x32_bf16 v[88:91], v[164:167], v[204:207], v[88:91]
	v_mfma_f32_16x16x32_bf16 v[76:79], v[146:149], v[212:215], v[76:79]
	v_mfma_f32_16x16x32_bf16 v[72:75], v[164:167], v[212:215], v[72:75]
	v_mfma_f32_16x16x32_bf16 v[120:123], v[150:153], v[192:195], v[120:123]
	v_mfma_f32_16x16x32_bf16 v[124:127], v[168:171], v[192:195], v[124:127]
	v_mfma_f32_16x16x32_bf16 v[108:111], v[150:153], v[200:203], v[108:111]
	v_mfma_f32_16x16x32_bf16 v[104:107], v[168:171], v[200:203], v[104:107]
	v_mfma_f32_16x16x32_bf16 v[92:95], v[150:153], v[208:211], v[92:95]
	v_mfma_f32_16x16x32_bf16 v[88:91], v[168:171], v[208:211], v[88:91]
	v_mfma_f32_16x16x32_bf16 v[76:79], v[150:153], v[216:219], v[76:79]
	v_mfma_f32_16x16x32_bf16 v[72:75], v[168:171], v[216:219], v[72:75]
	v_mfma_f32_16x16x32_bf16 v[116:119], v[172:175], v[188:191], v[116:119]
	v_mfma_f32_16x16x32_bf16 v[112:115], v[180:183], v[188:191], v[112:115]
	v_mfma_f32_16x16x32_bf16 v[100:103], v[172:175], v[196:199], v[100:103]
	v_mfma_f32_16x16x32_bf16 v[96:99], v[180:183], v[196:199], v[96:99]
	v_mfma_f32_16x16x32_bf16 v[84:87], v[172:175], v[204:207], v[84:87]
	v_mfma_f32_16x16x32_bf16 v[80:83], v[180:183], v[204:207], v[80:83]
	v_mfma_f32_16x16x32_bf16 v[68:71], v[172:175], v[212:215], v[68:71]
	v_mfma_f32_16x16x32_bf16 v[64:67], v[180:183], v[212:215], v[64:67]
	v_mfma_f32_16x16x32_bf16 v[116:119], v[176:179], v[192:195], v[116:119]
	v_mfma_f32_16x16x32_bf16 v[112:115], v[184:187], v[192:195], v[112:115]
	v_mfma_f32_16x16x32_bf16 v[100:103], v[176:179], v[200:203], v[100:103]
	v_mfma_f32_16x16x32_bf16 v[96:99], v[184:187], v[200:203], v[96:99]
	v_mfma_f32_16x16x32_bf16 v[84:87], v[176:179], v[208:211], v[84:87]
	v_mfma_f32_16x16x32_bf16 v[80:83], v[184:187], v[208:211], v[80:83]
	v_mfma_f32_16x16x32_bf16 v[68:71], v[176:179], v[216:219], v[68:71]
	v_mfma_f32_16x16x32_bf16 v[64:67], v[184:187], v[216:219], v[64:67]
	s_barrier
	s_setprio 0
	s_add_i32 s8, s45, s54
	v_lshl_add_u64 v[222:223], v[222:223], 0, s[34:35]
	s_mov_b32 m0, s8
	ds_read_b128 v[188:191], v159 offset:49152
	ds_read_b128 v[192:195], v159 offset:50176
	ds_read_b128 v[196:199], v159 offset:51200
	ds_read_b128 v[200:203], v159 offset:52224
	ds_read_b128 v[204:207], v159 offset:53248
	ds_read_b128 v[208:211], v159 offset:54272
	ds_read_b128 v[212:215], v159 offset:55296
	ds_read_b128 v[216:219], v159 offset:56320
	global_load_lds_dwordx4 v[222:223], off
	v_lshl_add_u64 v[222:223], v[224:225], 0, s[34:35]
	s_add_i32 m0, s8, 0x2000
	s_add_i32 s8, s92, s54
	global_load_lds_dwordx4 v[222:223], off
	v_lshl_add_u64 v[222:223], v[226:227], 0, s[34:35]
	s_mov_b32 m0, s8
	s_nop 0
	global_load_lds_dwordx4 v[222:223], off
	v_lshl_add_u64 v[222:223], v[228:229], 0, s[34:35]
	s_add_i32 m0, s8, 0x2000
	s_nop 0
	global_load_lds_dwordx4 v[222:223], off
	v_lshl_add_u64 v[222:223], v[230:231], 0, s[34:35]
	s_mov_b32 m0, s61
	s_nop 0
	global_load_lds_dwordx4 v[222:223], off
	v_lshl_add_u64 v[222:223], v[232:233], 0, s[34:35]
	s_mov_b32 m0, s62
	s_nop 0
	global_load_lds_dwordx4 v[222:223], off
	s_waitcnt vmcnt(8)
	s_waitcnt lgkmcnt(0)
	s_setprio 1
	s_barrier
	v_mfma_f32_16x16x32_bf16 v[60:63], v[146:149], v[188:191], v[60:63]
	v_mfma_f32_16x16x32_bf16 v[56:59], v[164:167], v[188:191], v[56:59]
	v_mfma_f32_16x16x32_bf16 v[44:47], v[146:149], v[196:199], v[44:47]
	v_mfma_f32_16x16x32_bf16 v[40:43], v[164:167], v[196:199], v[40:43]
	v_mfma_f32_16x16x32_bf16 v[28:31], v[146:149], v[204:207], v[28:31]
	v_mfma_f32_16x16x32_bf16 v[24:27], v[164:167], v[204:207], v[24:27]
	v_mfma_f32_16x16x32_bf16 v[12:15], v[146:149], v[212:215], v[12:15]
	v_mfma_f32_16x16x32_bf16 v[8:11], v[164:167], v[212:215], v[8:11]
	v_mfma_f32_16x16x32_bf16 v[60:63], v[150:153], v[192:195], v[60:63]
	v_mfma_f32_16x16x32_bf16 v[56:59], v[168:171], v[192:195], v[56:59]
	v_mfma_f32_16x16x32_bf16 v[44:47], v[150:153], v[200:203], v[44:47]
	v_mfma_f32_16x16x32_bf16 v[40:43], v[168:171], v[200:203], v[40:43]
	v_mfma_f32_16x16x32_bf16 v[28:31], v[150:153], v[208:211], v[28:31]
	v_mfma_f32_16x16x32_bf16 v[24:27], v[168:171], v[208:211], v[24:27]
	v_mfma_f32_16x16x32_bf16 v[12:15], v[150:153], v[216:219], v[12:15]
	v_mfma_f32_16x16x32_bf16 v[8:11], v[168:171], v[216:219], v[8:11]
	v_mfma_f32_16x16x32_bf16 v[52:55], v[172:175], v[188:191], v[52:55]
	v_mfma_f32_16x16x32_bf16 v[48:51], v[180:183], v[188:191], v[48:51]
	v_mfma_f32_16x16x32_bf16 v[36:39], v[172:175], v[196:199], v[36:39]
	v_mfma_f32_16x16x32_bf16 v[32:35], v[180:183], v[196:199], v[32:35]
	v_mfma_f32_16x16x32_bf16 v[20:23], v[172:175], v[204:207], v[20:23]
	v_mfma_f32_16x16x32_bf16 v[16:19], v[180:183], v[204:207], v[16:19]
	v_mfma_f32_16x16x32_bf16 v[4:7], v[172:175], v[212:215], v[4:7]
	v_mfma_f32_16x16x32_bf16 v[0:3], v[180:183], v[212:215], v[0:3]
	v_mfma_f32_16x16x32_bf16 v[52:55], v[176:179], v[192:195], v[52:55]
	v_mfma_f32_16x16x32_bf16 v[48:51], v[184:187], v[192:195], v[48:51]
	v_mfma_f32_16x16x32_bf16 v[36:39], v[176:179], v[200:203], v[36:39]
	v_mfma_f32_16x16x32_bf16 v[32:35], v[184:187], v[200:203], v[32:35]
	v_mfma_f32_16x16x32_bf16 v[20:23], v[176:179], v[208:211], v[20:23]
	v_mfma_f32_16x16x32_bf16 v[16:19], v[184:187], v[208:211], v[16:19]
	v_mfma_f32_16x16x32_bf16 v[4:7], v[176:179], v[216:219], v[4:7]
	v_mfma_f32_16x16x32_bf16 v[0:3], v[184:187], v[216:219], v[0:3]
	s_barrier
	s_setprio 0
	s_add_u32 s0, s0, 0x100
	s_addc_u32 s1, s1, 0
	s_add_u32 s10, s10, 0x100
	s_addc_u32 s11, s11, 0
	s_cmp_ge_i32 s44, s63
	s_mov_b32 s8, s44
	s_cbranch_scc0 .LBB0_1096

.LBB0_1292:
	ds_read_b128 v[128:131], v226
	ds_read_b128 v[132:135], v226 offset:1024
	ds_read_b128 v[136:139], v226 offset:2048
	ds_read_b128 v[140:143], v226 offset:3072
	ds_read_b128 v[160:163], v227
	ds_read_b128 v[164:167], v227 offset:1024
	ds_read_b128 v[168:171], v227 offset:2048
	ds_read_b128 v[172:175], v227 offset:3072
	s_add_i32 s80, s40, 2
	s_add_u32 s81, s0, 0x80
	s_addc_u32 s41, s1, 0
	s_cmp_eq_u32 s57, s40
	s_cselect_b32 s40, s36, s81
	s_cselect_b32 s41, s37, s41
	s_cselect_b32 s83, s39, s43
	s_cselect_b32 s82, s38, s42
	v_lshl_add_u64 v[208:209], s[0:1], 0, v[152:153]
	s_add_i32 m0, s45, 0xc000
	ds_read_b128 v[176:179], v228
	ds_read_b128 v[180:183], v228 offset:1024
	ds_read_b128 v[184:187], v228 offset:2048
	ds_read_b128 v[188:191], v228 offset:3072
	ds_read_b128 v[192:195], v228 offset:4096
	ds_read_b128 v[196:199], v228 offset:5120
	ds_read_b128 v[200:203], v228 offset:6144
	ds_read_b128 v[204:207], v228 offset:7168
	global_load_lds_dwordx4 v[208:209], off
	v_lshl_add_u64 v[208:209], s[0:1], 0, v[154:155]
	s_add_i32 m0, s45, 0xe000
	s_nop 0
	global_load_lds_dwordx4 v[208:209], off
	s_waitcnt vmcnt(8)
	s_waitcnt lgkmcnt(0)
	s_setprio 1
	s_barrier
	v_mfma_f32_16x16x32_bf16 v[124:127], v[128:131], v[176:179], v[124:127]
	v_mfma_f32_16x16x32_bf16 v[120:123], v[136:139], v[176:179], v[120:123]
	v_mfma_f32_16x16x32_bf16 v[116:119], v[128:131], v[184:187], v[116:119]
	v_mfma_f32_16x16x32_bf16 v[112:115], v[136:139], v[184:187], v[112:115]
	v_mfma_f32_16x16x32_bf16 v[108:111], v[128:131], v[192:195], v[108:111]
	v_mfma_f32_16x16x32_bf16 v[104:107], v[136:139], v[192:195], v[104:107]
	v_mfma_f32_16x16x32_bf16 v[100:103], v[128:131], v[200:203], v[100:103]
	v_mfma_f32_16x16x32_bf16 v[96:99], v[136:139], v[200:203], v[96:99]
	v_mfma_f32_16x16x32_bf16 v[124:127], v[132:135], v[180:183], v[124:127]
	v_mfma_f32_16x16x32_bf16 v[120:123], v[140:143], v[180:183], v[120:123]
	v_mfma_f32_16x16x32_bf16 v[116:119], v[132:135], v[188:191], v[116:119]
	v_mfma_f32_16x16x32_bf16 v[112:115], v[140:143], v[188:191], v[112:115]
	v_mfma_f32_16x16x32_bf16 v[108:111], v[132:135], v[196:199], v[108:111]
	v_mfma_f32_16x16x32_bf16 v[104:107], v[140:143], v[196:199], v[104:107]
	v_mfma_f32_16x16x32_bf16 v[100:103], v[132:135], v[204:207], v[100:103]
	v_mfma_f32_16x16x32_bf16 v[96:99], v[140:143], v[204:207], v[96:99]
	v_mfma_f32_16x16x32_bf16 v[60:63], v[160:163], v[176:179], v[60:63]
	v_mfma_f32_16x16x32_bf16 v[56:59], v[168:171], v[176:179], v[56:59]
	v_mfma_f32_16x16x32_bf16 v[52:55], v[160:163], v[184:187], v[52:55]
	v_mfma_f32_16x16x32_bf16 v[48:51], v[168:171], v[184:187], v[48:51]
	v_mfma_f32_16x16x32_bf16 v[44:47], v[160:163], v[192:195], v[44:47]
	v_mfma_f32_16x16x32_bf16 v[40:43], v[168:171], v[192:195], v[40:43]
	v_mfma_f32_16x16x32_bf16 v[36:39], v[160:163], v[200:203], v[36:39]
	v_mfma_f32_16x16x32_bf16 v[32:35], v[168:171], v[200:203], v[32:35]
	v_mfma_f32_16x16x32_bf16 v[60:63], v[164:167], v[180:183], v[60:63]
	v_mfma_f32_16x16x32_bf16 v[56:59], v[172:175], v[180:183], v[56:59]
	v_mfma_f32_16x16x32_bf16 v[52:55], v[164:167], v[188:191], v[52:55]
	v_mfma_f32_16x16x32_bf16 v[48:51], v[172:175], v[188:191], v[48:51]
	v_mfma_f32_16x16x32_bf16 v[44:47], v[164:167], v[196:199], v[44:47]
	v_mfma_f32_16x16x32_bf16 v[40:43], v[172:175], v[196:199], v[40:43]
	v_mfma_f32_16x16x32_bf16 v[36:39], v[164:167], v[204:207], v[36:39]
	v_mfma_f32_16x16x32_bf16 v[32:35], v[172:175], v[204:207], v[32:35]
	s_barrier
	s_setprio 0
	s_add_i32 s81, s61, s44
	v_lshl_add_u64 v[208:209], s[82:83], 0, v[146:147]
	s_mov_b32 m0, s81
	ds_read_b128 v[176:179], v228 offset:16384
	ds_read_b128 v[180:183], v228 offset:17408
	ds_read_b128 v[184:187], v228 offset:18432
	ds_read_b128 v[188:191], v228 offset:19456
	ds_read_b128 v[192:195], v228 offset:20480
	ds_read_b128 v[196:199], v228 offset:21504
	ds_read_b128 v[200:203], v228 offset:22528
	ds_read_b128 v[204:207], v228 offset:23552
	global_load_lds_dwordx4 v[208:209], off
	s_add_i32 m0, s81, 0x2000
	v_lshl_add_u64 v[210:211], s[82:83], 0, v[150:151]
	s_add_u32 s82, s82, s10
	s_addc_u32 s83, s83, s11
	s_add_i32 s81, s62, s44
	global_load_lds_dwordx4 v[210:211], off
	v_lshl_add_u64 v[212:213], s[82:83], 0, v[146:147]
	s_mov_b32 m0, s81
	v_lshl_add_u64 v[214:215], s[82:83], 0, v[150:151]
	global_load_lds_dwordx4 v[212:213], off
	s_add_i32 m0, s81, 0x2000
	v_lshl_add_u64 v[216:217], s[40:41], 0, v[144:145]
	global_load_lds_dwordx4 v[214:215], off
	s_mov_b32 m0, s45
	v_lshl_add_u64 v[218:219], s[40:41], 0, v[148:149]
	global_load_lds_dwordx4 v[216:217], off
	s_mov_b32 m0, s48
	s_nop 0
	global_load_lds_dwordx4 v[218:219], off
	s_waitcnt vmcnt(8)
	s_waitcnt lgkmcnt(0)
	s_setprio 1
	s_barrier
	v_mfma_f32_16x16x32_bf16 v[92:95], v[128:131], v[176:179], v[92:95]
	v_mfma_f32_16x16x32_bf16 v[88:91], v[136:139], v[176:179], v[88:91]
	v_mfma_f32_16x16x32_bf16 v[84:87], v[128:131], v[184:187], v[84:87]
	v_mfma_f32_16x16x32_bf16 v[80:83], v[136:139], v[184:187], v[80:83]
	v_mfma_f32_16x16x32_bf16 v[76:79], v[128:131], v[192:195], v[76:79]
	v_mfma_f32_16x16x32_bf16 v[72:75], v[136:139], v[192:195], v[72:75]
	v_mfma_f32_16x16x32_bf16 v[68:71], v[128:131], v[200:203], v[68:71]
	v_mfma_f32_16x16x32_bf16 v[64:67], v[136:139], v[200:203], v[64:67]
	v_mfma_f32_16x16x32_bf16 v[92:95], v[132:135], v[180:183], v[92:95]
	v_mfma_f32_16x16x32_bf16 v[88:91], v[140:143], v[180:183], v[88:91]
	v_mfma_f32_16x16x32_bf16 v[84:87], v[132:135], v[188:191], v[84:87]
	v_mfma_f32_16x16x32_bf16 v[80:83], v[140:143], v[188:191], v[80:83]
	v_mfma_f32_16x16x32_bf16 v[76:79], v[132:135], v[196:199], v[76:79]
	v_mfma_f32_16x16x32_bf16 v[72:75], v[140:143], v[196:199], v[72:75]
	v_mfma_f32_16x16x32_bf16 v[68:71], v[132:135], v[204:207], v[68:71]
	v_mfma_f32_16x16x32_bf16 v[64:67], v[140:143], v[204:207], v[64:67]
	v_mfma_f32_16x16x32_bf16 v[28:31], v[160:163], v[176:179], v[28:31]
	v_mfma_f32_16x16x32_bf16 v[24:27], v[168:171], v[176:179], v[24:27]
	v_mfma_f32_16x16x32_bf16 v[20:23], v[160:163], v[184:187], v[20:23]
	v_mfma_f32_16x16x32_bf16 v[16:19], v[168:171], v[184:187], v[16:19]
	v_mfma_f32_16x16x32_bf16 v[12:15], v[160:163], v[192:195], v[12:15]
	v_mfma_f32_16x16x32_bf16 v[8:11], v[168:171], v[192:195], v[8:11]
	v_mfma_f32_16x16x32_bf16 v[4:7], v[160:163], v[200:203], v[4:7]
	v_mfma_f32_16x16x32_bf16 v[0:3], v[168:171], v[200:203], v[0:3]
	v_mfma_f32_16x16x32_bf16 v[28:31], v[164:167], v[180:183], v[28:31]
	v_mfma_f32_16x16x32_bf16 v[24:27], v[172:175], v[180:183], v[24:27]
	v_mfma_f32_16x16x32_bf16 v[20:23], v[164:167], v[188:191], v[20:23]
	v_mfma_f32_16x16x32_bf16 v[16:19], v[172:175], v[188:191], v[16:19]
	v_mfma_f32_16x16x32_bf16 v[12:15], v[164:167], v[196:199], v[12:15]
	v_mfma_f32_16x16x32_bf16 v[8:11], v[172:175], v[196:199], v[8:11]
	v_mfma_f32_16x16x32_bf16 v[4:7], v[164:167], v[204:207], v[4:7]
	v_mfma_f32_16x16x32_bf16 v[0:3], v[172:175], v[204:207], v[0:3]
	s_barrier
	s_setprio 0
	s_add_i32 s81, 0, 0x18000
	s_add_i32 s82, 0, 0x1c000
	v_add_u32_e32 v140, s81, v224
	v_add_u32_e32 v172, s82, v224
	ds_read_b128 v[128:131], v140
	ds_read_b128 v[132:135], v140 offset:1024
	ds_read_b128 v[136:139], v140 offset:2048
	ds_read_b128 v[140:143], v140 offset:3072
	ds_read_b128 v[160:163], v172
	ds_read_b128 v[164:167], v172 offset:1024
	ds_read_b128 v[168:171], v172 offset:2048
	ds_read_b128 v[172:175], v172 offset:3072
	s_add_u32 s40, s40, s10
	s_addc_u32 s41, s41, s11
	s_mov_b32 m0, s49
	v_lshl_add_u64 v[230:231], s[40:41], 0, v[144:145]
	ds_read_b128 v[176:179], v228 offset:32768
	ds_read_b128 v[180:183], v228 offset:33792
	ds_read_b128 v[184:187], v228 offset:34816
	ds_read_b128 v[188:191], v228 offset:35840
	ds_read_b128 v[192:195], v228 offset:36864
	ds_read_b128 v[196:199], v228 offset:37888
	ds_read_b128 v[200:203], v228 offset:38912
	ds_read_b128 v[204:207], v228 offset:39936
	global_load_lds_dwordx4 v[230:231], off
	v_lshl_add_u64 v[230:231], s[40:41], 0, v[148:149]
	s_mov_b32 m0, s52
	s_nop 0
	global_load_lds_dwordx4 v[230:231], off
	s_waitcnt vmcnt(8)
	s_waitcnt lgkmcnt(0)
	s_setprio 1
	s_barrier
	v_mfma_f32_16x16x32_bf16 v[124:127], v[128:131], v[176:179], v[124:127]
	v_mfma_f32_16x16x32_bf16 v[120:123], v[136:139], v[176:179], v[120:123]
	v_mfma_f32_16x16x32_bf16 v[116:119], v[128:131], v[184:187], v[116:119]
	v_mfma_f32_16x16x32_bf16 v[112:115], v[136:139], v[184:187], v[112:115]
	v_mfma_f32_16x16x32_bf16 v[108:111], v[128:131], v[192:195], v[108:111]
	v_mfma_f32_16x16x32_bf16 v[104:107], v[136:139], v[192:195], v[104:107]
	v_mfma_f32_16x16x32_bf16 v[100:103], v[128:131], v[200:203], v[100:103]
	v_mfma_f32_16x16x32_bf16 v[96:99], v[136:139], v[200:203], v[96:99]
	v_mfma_f32_16x16x32_bf16 v[124:127], v[132:135], v[180:183], v[124:127]
	v_mfma_f32_16x16x32_bf16 v[120:123], v[140:143], v[180:183], v[120:123]
	v_mfma_f32_16x16x32_bf16 v[116:119], v[132:135], v[188:191], v[116:119]
	v_mfma_f32_16x16x32_bf16 v[112:115], v[140:143], v[188:191], v[112:115]
	v_mfma_f32_16x16x32_bf16 v[108:111], v[132:135], v[196:199], v[108:111]
	v_mfma_f32_16x16x32_bf16 v[104:107], v[140:143], v[196:199], v[104:107]
	v_mfma_f32_16x16x32_bf16 v[100:103], v[132:135], v[204:207], v[100:103]
	v_mfma_f32_16x16x32_bf16 v[96:99], v[140:143], v[204:207], v[96:99]
	v_mfma_f32_16x16x32_bf16 v[60:63], v[160:163], v[176:179], v[60:63]
	v_mfma_f32_16x16x32_bf16 v[56:59], v[168:171], v[176:179], v[56:59]
	v_mfma_f32_16x16x32_bf16 v[52:55], v[160:163], v[184:187], v[52:55]
	v_mfma_f32_16x16x32_bf16 v[48:51], v[168:171], v[184:187], v[48:51]
	v_mfma_f32_16x16x32_bf16 v[44:47], v[160:163], v[192:195], v[44:47]
	v_mfma_f32_16x16x32_bf16 v[40:43], v[168:171], v[192:195], v[40:43]
	v_mfma_f32_16x16x32_bf16 v[36:39], v[160:163], v[200:203], v[36:39]
	v_mfma_f32_16x16x32_bf16 v[32:35], v[168:171], v[200:203], v[32:35]
	v_mfma_f32_16x16x32_bf16 v[60:63], v[164:167], v[180:183], v[60:63]
	v_mfma_f32_16x16x32_bf16 v[56:59], v[172:175], v[180:183], v[56:59]
	v_mfma_f32_16x16x32_bf16 v[52:55], v[164:167], v[188:191], v[52:55]
	v_mfma_f32_16x16x32_bf16 v[48:51], v[172:175], v[188:191], v[48:51]
	v_mfma_f32_16x16x32_bf16 v[44:47], v[164:167], v[196:199], v[44:47]
	v_mfma_f32_16x16x32_bf16 v[40:43], v[172:175], v[196:199], v[40:43]
	v_mfma_f32_16x16x32_bf16 v[36:39], v[164:167], v[204:207], v[36:39]
	v_mfma_f32_16x16x32_bf16 v[32:35], v[172:175], v[204:207], v[32:35]
	s_barrier
	s_setprio 0
	s_add_i32 s40, s81, s44
	v_lshl_add_u64 v[208:209], v[208:209], 0, s[24:25]
	s_mov_b32 m0, s40
	ds_read_b128 v[176:179], v228 offset:49152
	ds_read_b128 v[180:183], v228 offset:50176
	ds_read_b128 v[184:187], v228 offset:51200
	ds_read_b128 v[188:191], v228 offset:52224
	ds_read_b128 v[192:195], v228 offset:53248
	ds_read_b128 v[196:199], v228 offset:54272
	ds_read_b128 v[200:203], v228 offset:55296
	ds_read_b128 v[204:207], v228 offset:56320
	global_load_lds_dwordx4 v[208:209], off
	v_lshl_add_u64 v[208:209], v[210:211], 0, s[24:25]
	s_add_i32 m0, s40, 0x2000
	s_add_i32 s40, s82, s44
	global_load_lds_dwordx4 v[208:209], off
	v_lshl_add_u64 v[208:209], v[212:213], 0, s[24:25]
	s_mov_b32 m0, s40
	s_nop 0
	global_load_lds_dwordx4 v[208:209], off
	v_lshl_add_u64 v[208:209], v[214:215], 0, s[24:25]
	s_add_i32 m0, s40, 0x2000
	s_nop 0
	global_load_lds_dwordx4 v[208:209], off
	v_lshl_add_u64 v[208:209], v[216:217], 0, s[24:25]
	s_mov_b32 m0, s54
	s_nop 0
	global_load_lds_dwordx4 v[208:209], off
	v_lshl_add_u64 v[208:209], v[218:219], 0, s[24:25]
	s_mov_b32 m0, s55
	s_nop 0
	global_load_lds_dwordx4 v[208:209], off
	s_waitcnt vmcnt(8)
	s_waitcnt lgkmcnt(0)
	s_setprio 1
	s_barrier
	v_mfma_f32_16x16x32_bf16 v[92:95], v[128:131], v[176:179], v[92:95]
	v_mfma_f32_16x16x32_bf16 v[88:91], v[136:139], v[176:179], v[88:91]
	v_mfma_f32_16x16x32_bf16 v[84:87], v[128:131], v[184:187], v[84:87]
	v_mfma_f32_16x16x32_bf16 v[80:83], v[136:139], v[184:187], v[80:83]
	v_mfma_f32_16x16x32_bf16 v[76:79], v[128:131], v[192:195], v[76:79]
	v_mfma_f32_16x16x32_bf16 v[72:75], v[136:139], v[192:195], v[72:75]
	v_mfma_f32_16x16x32_bf16 v[68:71], v[128:131], v[200:203], v[68:71]
	v_mfma_f32_16x16x32_bf16 v[64:67], v[136:139], v[200:203], v[64:67]
	v_mfma_f32_16x16x32_bf16 v[92:95], v[132:135], v[180:183], v[92:95]
	v_mfma_f32_16x16x32_bf16 v[88:91], v[140:143], v[180:183], v[88:91]
	v_mfma_f32_16x16x32_bf16 v[84:87], v[132:135], v[188:191], v[84:87]
	v_mfma_f32_16x16x32_bf16 v[80:83], v[140:143], v[188:191], v[80:83]
	v_mfma_f32_16x16x32_bf16 v[76:79], v[132:135], v[196:199], v[76:79]
	v_mfma_f32_16x16x32_bf16 v[72:75], v[140:143], v[196:199], v[72:75]
	v_mfma_f32_16x16x32_bf16 v[68:71], v[132:135], v[204:207], v[68:71]
	v_mfma_f32_16x16x32_bf16 v[64:67], v[140:143], v[204:207], v[64:67]
	v_mfma_f32_16x16x32_bf16 v[28:31], v[160:163], v[176:179], v[28:31]
	v_mfma_f32_16x16x32_bf16 v[24:27], v[168:171], v[176:179], v[24:27]
	v_mfma_f32_16x16x32_bf16 v[20:23], v[160:163], v[184:187], v[20:23]
	v_mfma_f32_16x16x32_bf16 v[16:19], v[168:171], v[184:187], v[16:19]
	v_mfma_f32_16x16x32_bf16 v[12:15], v[160:163], v[192:195], v[12:15]
	v_mfma_f32_16x16x32_bf16 v[8:11], v[168:171], v[192:195], v[8:11]
	v_mfma_f32_16x16x32_bf16 v[4:7], v[160:163], v[200:203], v[4:7]
	v_mfma_f32_16x16x32_bf16 v[0:3], v[168:171], v[200:203], v[0:3]
	v_mfma_f32_16x16x32_bf16 v[28:31], v[164:167], v[180:183], v[28:31]
	v_mfma_f32_16x16x32_bf16 v[24:27], v[172:175], v[180:183], v[24:27]
	v_mfma_f32_16x16x32_bf16 v[20:23], v[164:167], v[188:191], v[20:23]
	v_mfma_f32_16x16x32_bf16 v[16:19], v[172:175], v[188:191], v[16:19]
	v_mfma_f32_16x16x32_bf16 v[12:15], v[164:167], v[196:199], v[12:15]
	v_mfma_f32_16x16x32_bf16 v[8:11], v[172:175], v[196:199], v[8:11]
	v_mfma_f32_16x16x32_bf16 v[4:7], v[164:167], v[204:207], v[4:7]
	v_mfma_f32_16x16x32_bf16 v[0:3], v[172:175], v[204:207], v[0:3]
	s_barrier
	s_setprio 0
	s_add_u32 s0, s0, 0x100
	s_addc_u32 s1, s1, 0
	s_add_u32 s42, s42, 0x100
	s_addc_u32 s43, s43, 0
	s_cmp_ge_i32 s80, s56
	s_mov_b32 s40, s80
	s_cbranch_scc0 .LBB0_1292

.LBB0_1389:
	ds_read_b128 v[128:131], v183
	ds_read_b128 v[132:135], v183 offset:1024
	ds_read_b128 v[136:139], v183 offset:2048
	ds_read_b128 v[140:143], v183 offset:3072
	ds_read_b128 v[160:163], v185
	ds_read_b128 v[164:167], v185 offset:1024
	ds_read_b128 v[168:171], v185 offset:2048
	ds_read_b128 v[190:193], v185 offset:3072
	s_add_i32 s63, s8, 2
	s_add_u32 s76, s0, 0x80
	s_addc_u32 s9, s1, 0
	s_cmp_eq_u32 s53, s8
	s_cselect_b32 s8, s36, s76
	s_cselect_b32 s9, s37, s9
	s_cselect_b32 s77, s39, s11
	s_cselect_b32 s76, s38, s10
	v_lshl_add_u64 v[172:173], s[0:1], 0, v[152:153]
	s_add_i32 m0, s42, 0xc000
	ds_read_b128 v[194:197], v187
	ds_read_b128 v[198:201], v187 offset:1024
	ds_read_b128 v[202:205], v187 offset:2048
	ds_read_b128 v[206:209], v187 offset:3072
	ds_read_b128 v[210:213], v187 offset:4096
	ds_read_b128 v[214:217], v187 offset:5120
	ds_read_b128 v[224:227], v187 offset:6144
	ds_read_b128 v[228:231], v187 offset:7168
	global_load_lds_dwordx4 v[172:173], off
	v_lshl_add_u64 v[172:173], s[0:1], 0, v[154:155]
	s_add_i32 m0, s42, 0xe000
	s_nop 0
	global_load_lds_dwordx4 v[172:173], off
	s_waitcnt vmcnt(8)
	s_waitcnt lgkmcnt(0)
	s_setprio 1
	s_barrier
	v_mfma_f32_16x16x32_bf16 v[124:127], v[128:131], v[194:197], v[124:127]
	v_mfma_f32_16x16x32_bf16 v[120:123], v[136:139], v[194:197], v[120:123]
	v_mfma_f32_16x16x32_bf16 v[116:119], v[128:131], v[202:205], v[116:119]
	v_mfma_f32_16x16x32_bf16 v[112:115], v[136:139], v[202:205], v[112:115]
	v_mfma_f32_16x16x32_bf16 v[108:111], v[128:131], v[210:213], v[108:111]
	v_mfma_f32_16x16x32_bf16 v[104:107], v[136:139], v[210:213], v[104:107]
	v_mfma_f32_16x16x32_bf16 v[100:103], v[128:131], v[224:227], v[100:103]
	v_mfma_f32_16x16x32_bf16 v[96:99], v[136:139], v[224:227], v[96:99]
	v_mfma_f32_16x16x32_bf16 v[124:127], v[132:135], v[198:201], v[124:127]
	v_mfma_f32_16x16x32_bf16 v[120:123], v[140:143], v[198:201], v[120:123]
	v_mfma_f32_16x16x32_bf16 v[116:119], v[132:135], v[206:209], v[116:119]
	v_mfma_f32_16x16x32_bf16 v[112:115], v[140:143], v[206:209], v[112:115]
	v_mfma_f32_16x16x32_bf16 v[108:111], v[132:135], v[214:217], v[108:111]
	v_mfma_f32_16x16x32_bf16 v[104:107], v[140:143], v[214:217], v[104:107]
	v_mfma_f32_16x16x32_bf16 v[100:103], v[132:135], v[228:231], v[100:103]
	v_mfma_f32_16x16x32_bf16 v[96:99], v[140:143], v[228:231], v[96:99]
	v_mfma_f32_16x16x32_bf16 v[60:63], v[160:163], v[194:197], v[60:63]
	v_mfma_f32_16x16x32_bf16 v[56:59], v[168:171], v[194:197], v[56:59]
	v_mfma_f32_16x16x32_bf16 v[52:55], v[160:163], v[202:205], v[52:55]
	v_mfma_f32_16x16x32_bf16 v[48:51], v[168:171], v[202:205], v[48:51]
	v_mfma_f32_16x16x32_bf16 v[44:47], v[160:163], v[210:213], v[44:47]
	v_mfma_f32_16x16x32_bf16 v[40:43], v[168:171], v[210:213], v[40:43]
	v_mfma_f32_16x16x32_bf16 v[36:39], v[160:163], v[224:227], v[36:39]
	v_mfma_f32_16x16x32_bf16 v[32:35], v[168:171], v[224:227], v[32:35]
	v_mfma_f32_16x16x32_bf16 v[60:63], v[164:167], v[198:201], v[60:63]
	v_mfma_f32_16x16x32_bf16 v[56:59], v[190:193], v[198:201], v[56:59]
	v_mfma_f32_16x16x32_bf16 v[52:55], v[164:167], v[206:209], v[52:55]
	v_mfma_f32_16x16x32_bf16 v[48:51], v[190:193], v[206:209], v[48:51]
	v_mfma_f32_16x16x32_bf16 v[44:47], v[164:167], v[214:217], v[44:47]
	v_mfma_f32_16x16x32_bf16 v[40:43], v[190:193], v[214:217], v[40:43]
	v_mfma_f32_16x16x32_bf16 v[36:39], v[164:167], v[228:231], v[36:39]
	v_mfma_f32_16x16x32_bf16 v[32:35], v[190:193], v[228:231], v[32:35]
	s_barrier
	s_setprio 0
	s_add_i32 s78, s56, s41
	v_lshl_add_u64 v[172:173], s[76:77], 0, v[146:147]
	s_mov_b32 m0, s78
	ds_read_b128 v[194:197], v187 offset:16384
	ds_read_b128 v[198:201], v187 offset:17408
	ds_read_b128 v[202:205], v187 offset:18432
	ds_read_b128 v[206:209], v187 offset:19456
	ds_read_b128 v[210:213], v187 offset:20480
	ds_read_b128 v[214:217], v187 offset:21504
	ds_read_b128 v[224:227], v187 offset:22528
	ds_read_b128 v[228:231], v187 offset:23552
	global_load_lds_dwordx4 v[172:173], off
	s_add_i32 m0, s78, 0x2000
	v_lshl_add_u64 v[178:179], s[76:77], 0, v[150:151]
	s_add_u32 s76, s76, s12
	s_addc_u32 s77, s77, s13
	s_add_i32 s78, s57, s41
	global_load_lds_dwordx4 v[178:179], off
	v_lshl_add_u64 v[218:219], s[76:77], 0, v[146:147]
	s_mov_b32 m0, s78
	v_lshl_add_u64 v[232:233], s[76:77], 0, v[150:151]
	global_load_lds_dwordx4 v[218:219], off
	s_add_i32 m0, s78, 0x2000
	v_lshl_add_u64 v[234:235], s[8:9], 0, v[144:145]
	global_load_lds_dwordx4 v[232:233], off
	s_mov_b32 m0, s42
	v_lshl_add_u64 v[236:237], s[8:9], 0, v[148:149]
	global_load_lds_dwordx4 v[234:235], off
	s_mov_b32 m0, s43
	s_nop 0
	global_load_lds_dwordx4 v[236:237], off
	s_waitcnt vmcnt(8)
	s_waitcnt lgkmcnt(0)
	s_setprio 1
	s_barrier
	v_mfma_f32_16x16x32_bf16 v[92:95], v[128:131], v[194:197], v[92:95]
	v_mfma_f32_16x16x32_bf16 v[88:91], v[136:139], v[194:197], v[88:91]
	v_mfma_f32_16x16x32_bf16 v[84:87], v[128:131], v[202:205], v[84:87]
	v_mfma_f32_16x16x32_bf16 v[80:83], v[136:139], v[202:205], v[80:83]
	v_mfma_f32_16x16x32_bf16 v[76:79], v[128:131], v[210:213], v[76:79]
	v_mfma_f32_16x16x32_bf16 v[72:75], v[136:139], v[210:213], v[72:75]
	v_mfma_f32_16x16x32_bf16 v[68:71], v[128:131], v[224:227], v[68:71]
	v_mfma_f32_16x16x32_bf16 v[64:67], v[136:139], v[224:227], v[64:67]
	v_mfma_f32_16x16x32_bf16 v[92:95], v[132:135], v[198:201], v[92:95]
	v_mfma_f32_16x16x32_bf16 v[88:91], v[140:143], v[198:201], v[88:91]
	v_mfma_f32_16x16x32_bf16 v[84:87], v[132:135], v[206:209], v[84:87]
	v_mfma_f32_16x16x32_bf16 v[80:83], v[140:143], v[206:209], v[80:83]
	v_mfma_f32_16x16x32_bf16 v[76:79], v[132:135], v[214:217], v[76:79]
	v_mfma_f32_16x16x32_bf16 v[72:75], v[140:143], v[214:217], v[72:75]
	v_mfma_f32_16x16x32_bf16 v[68:71], v[132:135], v[228:231], v[68:71]
	v_mfma_f32_16x16x32_bf16 v[64:67], v[140:143], v[228:231], v[64:67]
	v_mfma_f32_16x16x32_bf16 v[28:31], v[160:163], v[194:197], v[28:31]
	v_mfma_f32_16x16x32_bf16 v[24:27], v[168:171], v[194:197], v[24:27]
	v_mfma_f32_16x16x32_bf16 v[20:23], v[160:163], v[202:205], v[20:23]
	v_mfma_f32_16x16x32_bf16 v[16:19], v[168:171], v[202:205], v[16:19]
	v_mfma_f32_16x16x32_bf16 v[12:15], v[160:163], v[210:213], v[12:15]
	v_mfma_f32_16x16x32_bf16 v[8:11], v[168:171], v[210:213], v[8:11]
	v_mfma_f32_16x16x32_bf16 v[4:7], v[160:163], v[224:227], v[4:7]
	v_mfma_f32_16x16x32_bf16 v[0:3], v[168:171], v[224:227], v[0:3]
	v_mfma_f32_16x16x32_bf16 v[28:31], v[164:167], v[198:201], v[28:31]
	v_mfma_f32_16x16x32_bf16 v[24:27], v[190:193], v[198:201], v[24:27]
	v_mfma_f32_16x16x32_bf16 v[20:23], v[164:167], v[206:209], v[20:23]
	v_mfma_f32_16x16x32_bf16 v[16:19], v[190:193], v[206:209], v[16:19]
	v_mfma_f32_16x16x32_bf16 v[12:15], v[164:167], v[214:217], v[12:15]
	v_mfma_f32_16x16x32_bf16 v[8:11], v[190:193], v[214:217], v[8:11]
	v_mfma_f32_16x16x32_bf16 v[4:7], v[164:167], v[228:231], v[4:7]
	v_mfma_f32_16x16x32_bf16 v[0:3], v[190:193], v[228:231], v[0:3]
	s_barrier
	s_setprio 0
	s_add_i32 s76, 0, 0x18000
	s_add_i32 s77, 0, 0x1c000
	v_add_u32_e32 v140, s76, v177
	v_add_u32_e32 v174, s77, v177
	ds_read_b128 v[128:131], v140
	ds_read_b128 v[132:135], v140 offset:1024
	ds_read_b128 v[136:139], v140 offset:2048
	ds_read_b128 v[140:143], v140 offset:3072
	ds_read_b128 v[160:163], v174
	ds_read_b128 v[164:167], v174 offset:1024
	ds_read_b128 v[168:171], v174 offset:2048
	ds_read_b128 v[190:193], v174 offset:3072
	s_add_u32 s8, s8, s12
	s_addc_u32 s9, s9, s13
	s_mov_b32 m0, s44
	v_lshl_add_u64 v[238:239], s[8:9], 0, v[144:145]
	ds_read_b128 v[194:197], v187 offset:32768
	ds_read_b128 v[198:201], v187 offset:33792
	ds_read_b128 v[202:205], v187 offset:34816
	ds_read_b128 v[206:209], v187 offset:35840
	ds_read_b128 v[210:213], v187 offset:36864
	ds_read_b128 v[214:217], v187 offset:37888
	ds_read_b128 v[224:227], v187 offset:38912
	ds_read_b128 v[228:231], v187 offset:39936
	global_load_lds_dwordx4 v[238:239], off
	v_lshl_add_u64 v[238:239], s[8:9], 0, v[148:149]
	s_mov_b32 m0, s45
	s_nop 0
	global_load_lds_dwordx4 v[238:239], off
	s_waitcnt vmcnt(8)
	s_waitcnt lgkmcnt(0)
	s_setprio 1
	s_barrier
	v_mfma_f32_16x16x32_bf16 v[124:127], v[128:131], v[194:197], v[124:127]
	v_mfma_f32_16x16x32_bf16 v[120:123], v[136:139], v[194:197], v[120:123]
	v_mfma_f32_16x16x32_bf16 v[116:119], v[128:131], v[202:205], v[116:119]
	v_mfma_f32_16x16x32_bf16 v[112:115], v[136:139], v[202:205], v[112:115]
	v_mfma_f32_16x16x32_bf16 v[108:111], v[128:131], v[210:213], v[108:111]
	v_mfma_f32_16x16x32_bf16 v[104:107], v[136:139], v[210:213], v[104:107]
	v_mfma_f32_16x16x32_bf16 v[100:103], v[128:131], v[224:227], v[100:103]
	v_mfma_f32_16x16x32_bf16 v[96:99], v[136:139], v[224:227], v[96:99]
	v_mfma_f32_16x16x32_bf16 v[124:127], v[132:135], v[198:201], v[124:127]
	v_mfma_f32_16x16x32_bf16 v[120:123], v[140:143], v[198:201], v[120:123]
	v_mfma_f32_16x16x32_bf16 v[116:119], v[132:135], v[206:209], v[116:119]
	v_mfma_f32_16x16x32_bf16 v[112:115], v[140:143], v[206:209], v[112:115]
	v_mfma_f32_16x16x32_bf16 v[108:111], v[132:135], v[214:217], v[108:111]
	v_mfma_f32_16x16x32_bf16 v[104:107], v[140:143], v[214:217], v[104:107]
	v_mfma_f32_16x16x32_bf16 v[100:103], v[132:135], v[228:231], v[100:103]
	v_mfma_f32_16x16x32_bf16 v[96:99], v[140:143], v[228:231], v[96:99]
	v_mfma_f32_16x16x32_bf16 v[60:63], v[160:163], v[194:197], v[60:63]
	v_mfma_f32_16x16x32_bf16 v[56:59], v[168:171], v[194:197], v[56:59]
	v_mfma_f32_16x16x32_bf16 v[52:55], v[160:163], v[202:205], v[52:55]
	v_mfma_f32_16x16x32_bf16 v[48:51], v[168:171], v[202:205], v[48:51]
	v_mfma_f32_16x16x32_bf16 v[44:47], v[160:163], v[210:213], v[44:47]
	v_mfma_f32_16x16x32_bf16 v[40:43], v[168:171], v[210:213], v[40:43]
	v_mfma_f32_16x16x32_bf16 v[36:39], v[160:163], v[224:227], v[36:39]
	v_mfma_f32_16x16x32_bf16 v[32:35], v[168:171], v[224:227], v[32:35]
	v_mfma_f32_16x16x32_bf16 v[60:63], v[164:167], v[198:201], v[60:63]
	v_mfma_f32_16x16x32_bf16 v[56:59], v[190:193], v[198:201], v[56:59]
	v_mfma_f32_16x16x32_bf16 v[52:55], v[164:167], v[206:209], v[52:55]
	v_mfma_f32_16x16x32_bf16 v[48:51], v[190:193], v[206:209], v[48:51]
	v_mfma_f32_16x16x32_bf16 v[44:47], v[164:167], v[214:217], v[44:47]
	v_mfma_f32_16x16x32_bf16 v[40:43], v[190:193], v[214:217], v[40:43]
	v_mfma_f32_16x16x32_bf16 v[36:39], v[164:167], v[228:231], v[36:39]
	v_mfma_f32_16x16x32_bf16 v[32:35], v[190:193], v[228:231], v[32:35]
	s_barrier
	s_setprio 0
	s_add_i32 s8, s76, s41
	v_lshl_add_u64 v[172:173], v[172:173], 0, s[26:27]
	s_mov_b32 m0, s8
	ds_read_b128 v[194:197], v187 offset:49152
	ds_read_b128 v[198:201], v187 offset:50176
	ds_read_b128 v[202:205], v187 offset:51200
	ds_read_b128 v[206:209], v187 offset:52224
	ds_read_b128 v[210:213], v187 offset:53248
	ds_read_b128 v[214:217], v187 offset:54272
	ds_read_b128 v[224:227], v187 offset:55296
	ds_read_b128 v[228:231], v187 offset:56320
	global_load_lds_dwordx4 v[172:173], off
	v_lshl_add_u64 v[172:173], v[178:179], 0, s[26:27]
	s_add_i32 m0, s8, 0x2000
	s_add_i32 s8, s77, s41
	global_load_lds_dwordx4 v[172:173], off
	v_lshl_add_u64 v[172:173], v[218:219], 0, s[26:27]
	s_mov_b32 m0, s8
	s_nop 0
	global_load_lds_dwordx4 v[172:173], off
	v_lshl_add_u64 v[172:173], v[232:233], 0, s[26:27]
	s_add_i32 m0, s8, 0x2000
	s_nop 0
	global_load_lds_dwordx4 v[172:173], off
	v_lshl_add_u64 v[172:173], v[234:235], 0, s[26:27]
	s_mov_b32 m0, s48
	s_nop 0
	global_load_lds_dwordx4 v[172:173], off
	v_lshl_add_u64 v[172:173], v[236:237], 0, s[26:27]
	s_mov_b32 m0, s49
	s_nop 0
	global_load_lds_dwordx4 v[172:173], off
	s_waitcnt vmcnt(8)
	s_waitcnt lgkmcnt(0)
	s_setprio 1
	s_barrier
	v_mfma_f32_16x16x32_bf16 v[92:95], v[128:131], v[194:197], v[92:95]
	v_mfma_f32_16x16x32_bf16 v[88:91], v[136:139], v[194:197], v[88:91]
	v_mfma_f32_16x16x32_bf16 v[84:87], v[128:131], v[202:205], v[84:87]
	v_mfma_f32_16x16x32_bf16 v[80:83], v[136:139], v[202:205], v[80:83]
	v_mfma_f32_16x16x32_bf16 v[76:79], v[128:131], v[210:213], v[76:79]
	v_mfma_f32_16x16x32_bf16 v[72:75], v[136:139], v[210:213], v[72:75]
	v_mfma_f32_16x16x32_bf16 v[68:71], v[128:131], v[224:227], v[68:71]
	v_mfma_f32_16x16x32_bf16 v[64:67], v[136:139], v[224:227], v[64:67]
	v_mfma_f32_16x16x32_bf16 v[92:95], v[132:135], v[198:201], v[92:95]
	v_mfma_f32_16x16x32_bf16 v[88:91], v[140:143], v[198:201], v[88:91]
	v_mfma_f32_16x16x32_bf16 v[84:87], v[132:135], v[206:209], v[84:87]
	v_mfma_f32_16x16x32_bf16 v[80:83], v[140:143], v[206:209], v[80:83]
	v_mfma_f32_16x16x32_bf16 v[76:79], v[132:135], v[214:217], v[76:79]
	v_mfma_f32_16x16x32_bf16 v[72:75], v[140:143], v[214:217], v[72:75]
	v_mfma_f32_16x16x32_bf16 v[68:71], v[132:135], v[228:231], v[68:71]
	v_mfma_f32_16x16x32_bf16 v[64:67], v[140:143], v[228:231], v[64:67]
	v_mfma_f32_16x16x32_bf16 v[28:31], v[160:163], v[194:197], v[28:31]
	v_mfma_f32_16x16x32_bf16 v[24:27], v[168:171], v[194:197], v[24:27]
	v_mfma_f32_16x16x32_bf16 v[20:23], v[160:163], v[202:205], v[20:23]
	v_mfma_f32_16x16x32_bf16 v[16:19], v[168:171], v[202:205], v[16:19]
	v_mfma_f32_16x16x32_bf16 v[12:15], v[160:163], v[210:213], v[12:15]
	v_mfma_f32_16x16x32_bf16 v[8:11], v[168:171], v[210:213], v[8:11]
	v_mfma_f32_16x16x32_bf16 v[4:7], v[160:163], v[224:227], v[4:7]
	v_mfma_f32_16x16x32_bf16 v[0:3], v[168:171], v[224:227], v[0:3]
	v_mfma_f32_16x16x32_bf16 v[28:31], v[164:167], v[198:201], v[28:31]
	v_mfma_f32_16x16x32_bf16 v[24:27], v[190:193], v[198:201], v[24:27]
	v_mfma_f32_16x16x32_bf16 v[20:23], v[164:167], v[206:209], v[20:23]
	v_mfma_f32_16x16x32_bf16 v[16:19], v[190:193], v[206:209], v[16:19]
	v_mfma_f32_16x16x32_bf16 v[12:15], v[164:167], v[214:217], v[12:15]
	v_mfma_f32_16x16x32_bf16 v[8:11], v[190:193], v[214:217], v[8:11]
	v_mfma_f32_16x16x32_bf16 v[4:7], v[164:167], v[228:231], v[4:7]
	v_mfma_f32_16x16x32_bf16 v[0:3], v[190:193], v[228:231], v[0:3]
	s_barrier
	s_setprio 0
	s_add_u32 s0, s0, 0x100
	s_addc_u32 s1, s1, 0
	s_add_u32 s10, s10, 0x100
	s_addc_u32 s11, s11, 0
	s_cmp_ge_i32 s63, s52
	s_mov_b32 s8, s63
	s_cbranch_scc0 .LBB0_1389

.LBB0_1392:
	v_lshl_add_u32 v202, s62, 8, v175
	v_ashrrev_i32_e32 v203, 31, v202
	v_lshl_add_u64 v[128:129], v[202:203], 3, s[18:19]
	global_load_dwordx2 v[128:129], v[128:129], off
	v_or_b32_e32 v200, 16, v202
	v_or_b32_e32 v198, 32, v202
	v_ashrrev_i32_e32 v201, 31, v200
	v_ashrrev_i32_e32 v199, 31, v198
	v_lshl_add_u64 v[130:131], v[200:201], 3, s[18:19]
	v_lshl_add_u64 v[132:133], v[198:199], 3, s[18:19]
	global_load_dwordx2 v[130:131], v[130:131], off
	s_nop 0
	global_load_dwordx2 v[132:133], v[132:133], off
	v_or_b32_e32 v196, 48, v202
	v_add_u32_e32 v194, 0x80, v202
	v_ashrrev_i32_e32 v197, 31, v196
	v_ashrrev_i32_e32 v195, 31, v194
	v_lshl_add_u64 v[134:135], v[196:197], 3, s[18:19]
	v_lshl_add_u64 v[136:137], v[194:195], 3, s[18:19]
	global_load_dwordx2 v[134:135], v[134:135], off
	s_nop 0
	global_load_dwordx2 v[136:137], v[136:137], off
	v_add_u32_e32 v192, 0x90, v202
	v_ashrrev_i32_e32 v193, 31, v192
	v_add_u32_e32 v206, 0xa0, v202
	v_ashrrev_i32_e32 v207, 31, v206
	v_add_u32_e32 v204, 0xb0, v202
	v_ashrrev_i32_e32 v205, 31, v204
	v_lshl_or_b32 v208, s61, 8, v181
	v_ashrrev_i32_e32 v209, 31, v208
	v_lshlrev_b32_e32 v252, 3, v192
	v_lshlrev_b32_e32 v253, 3, v206
	v_lshlrev_b32_e32 v254, 3, v204
	v_lshlrev_b32_e32 v255, 2, v208
	global_load_dword v252, v252, s[18:19]
	global_load_dword v253, v253, s[18:19]
	global_load_dword v254, v254, s[18:19]
	global_load_dword v252, v255, s[22:23]
	global_load_dword v253, v255, s[24:25]
	s_waitcnt vmcnt(0)
	v_pk_mul_f32 v[166:167], v[128:129], s[34:35] op_sel_hi:[1,0]
	s_nop 0
	v_fma_f32 v128, -v166, v166, v167
	v_max_f32_e32 v128, 0, v128
	v_add_f32_e32 v128, 0x3727c5ac, v128
	v_cmp_gt_f32_e32 vcc, s58, v128
	v_pk_mul_f32 v[162:163], v[130:131], s[34:35] op_sel_hi:[1,0]
	v_pk_mul_f32 v[160:161], v[132:133], s[34:35] op_sel_hi:[1,0]
	v_fma_f32 v129, -v162, v162, v163
	v_fma_f32 v130, -v160, v160, v161
	v_max_f32_e32 v129, 0, v129
	v_mul_f32_e32 v131, 0x4f800000, v128
	v_max_f32_e32 v130, 0, v130
	v_add_f32_e32 v129, 0x3727c5ac, v129
	v_cndmask_b32_e32 v128, v128, v131, vcc
	v_add_f32_e32 v130, 0x3727c5ac, v130
	v_mul_f32_e32 v131, 0x4f800000, v129
	v_sqrt_f32_e32 v133, v128
	v_cmp_gt_f32_e64 s[0:1], s58, v129
	v_mul_f32_e32 v132, 0x4f800000, v130
	v_cmp_gt_f32_e64 s[8:9], s58, v130
	v_cndmask_b32_e64 v129, v129, v131, s[0:1]
	v_sqrt_f32_e32 v131, v129
	v_cndmask_b32_e64 v130, v130, v132, s[8:9]
	v_sqrt_f32_e32 v132, v130
	v_add_u32_e32 v138, -1, v133
	v_add_u32_e32 v139, 1, v133
	v_fma_f32 v140, -v138, v133, v128
	v_fma_f32 v141, -v139, v133, v128
	v_add_u32_e32 v142, -1, v131
	v_cmp_ge_f32_e64 s[10:11], 0, v140
	v_add_u32_e32 v164, -1, v132
	v_add_u32_e32 v143, 1, v131
	v_cndmask_b32_e64 v133, v133, v138, s[10:11]
	v_fma_f32 v138, -v142, v131, v129
	v_cmp_lt_f32_e64 s[10:11], 0, v141
	v_fma_f32 v168, -v164, v132, v130
	v_add_u32_e32 v165, 1, v132
	v_cndmask_b32_e64 v133, v133, v139, s[10:11]
	v_cmp_ge_f32_e64 s[10:11], 0, v138
	v_fma_f32 v140, -v143, v131, v129
	v_fma_f32 v169, -v165, v132, v130
	v_cndmask_b32_e64 v131, v131, v142, s[10:11]
	v_cmp_ge_f32_e64 s[10:11], 0, v168
	v_mul_f32_e32 v138, 0x37800000, v133
	v_cndmask_b32_e32 v133, v133, v138, vcc
	v_cndmask_b32_e64 v132, v132, v164, s[10:11]
	v_cmp_lt_f32_e64 s[10:11], 0, v140
	v_cmp_class_f32_e32 vcc, v128, v189
	v_pk_mul_f32 v[170:171], v[136:137], s[34:35] op_sel_hi:[1,0]
	v_cndmask_b32_e64 v131, v131, v143, s[10:11]
	v_cmp_lt_f32_e64 s[10:11], 0, v169
	v_mul_f32_e32 v138, 0x37800000, v131
	v_cndmask_b32_e32 v128, v133, v128, vcc
	v_cndmask_b32_e64 v132, v132, v165, s[10:11]
	v_cndmask_b32_e64 v131, v131, v138, s[0:1]
	v_div_scale_f32 v133, s[0:1], v128, v128, 1.0
	v_mul_f32_e32 v139, 0x37800000, v132
	v_cmp_class_f32_e64 s[0:1], v129, v189
	v_cndmask_b32_e64 v132, v132, v139, s[8:9]
	v_div_scale_f32 v138, vcc, 1.0, v128, 1.0
	v_cndmask_b32_e64 v129, v131, v129, s[0:1]
	v_cmp_class_f32_e64 s[0:1], v130, v189
	v_rcp_f32_e32 v131, v133
	s_nop 0
	v_cndmask_b32_e64 v130, v132, v130, s[0:1]
	v_div_scale_f32 v132, s[0:1], v129, v129, 1.0
	v_div_scale_f32 v140, s[8:9], v130, v130, 1.0
	v_rcp_f32_e32 v141, v132
	v_rcp_f32_e32 v142, v140
	v_fma_f32 v143, -v133, v131, 1.0
	v_fmac_f32_e32 v131, v143, v131
	v_fma_f32 v143, -v132, v141, 1.0
	v_div_scale_f32 v139, s[0:1], 1.0, v129, 1.0
	v_fma_f32 v164, -v140, v142, 1.0
	v_mul_f32_e32 v165, v138, v131
	v_fmac_f32_e32 v141, v143, v141
	v_fmac_f32_e32 v142, v164, v142
	v_fma_f32 v143, -v133, v165, v138
	v_mul_f32_e32 v164, v139, v141
	v_fmac_f32_e32 v165, v143, v131
	v_fma_f32 v143, -v132, v164, v139
	v_fma_f32 v133, -v133, v165, v138
	v_fmac_f32_e32 v164, v143, v141
	v_div_fmas_f32 v131, v133, v131, v165
	v_fma_f32 v132, -v132, v164, v139
	s_mov_b64 vcc, s[0:1]
	v_div_fixup_f32 v184, v131, v128, 1.0
	v_div_fmas_f32 v128, v132, v141, v164
	v_div_fixup_f32 v176, v128, v129, 1.0
	v_lshl_add_u64 v[128:129], v[192:193], 3, s[18:19]
	global_load_dwordx2 v[128:129], v[128:129], off
	v_pk_mul_f32 v[164:165], v[134:135], s[34:35] op_sel_hi:[1,0]
	v_div_scale_f32 v131, vcc, 1.0, v130, 1.0
	v_fma_f32 v133, -v164, v164, v165
	v_max_f32_e32 v133, 0, v133
	v_add_f32_e32 v133, 0x3727c5ac, v133
	v_mul_f32_e32 v134, 0x4f800000, v133
	v_cmp_gt_f32_e64 s[0:1], s58, v133
	v_mul_f32_e32 v132, v131, v142
	v_fma_f32 v135, -v140, v132, v131
	v_cndmask_b32_e64 v133, v133, v134, s[0:1]
	v_sqrt_f32_e32 v134, v133
	v_fmac_f32_e32 v132, v135, v142
	v_fma_f32 v131, -v140, v132, v131
	v_div_fmas_f32 v131, v131, v142, v132
	v_add_u32_e32 v135, -1, v134
	v_fma_f32 v138, -v135, v134, v133
	v_cmp_ge_f32_e64 s[8:9], 0, v138
	v_add_u32_e32 v138, 1, v134
	v_div_fixup_f32 v174, v131, v130, 1.0
	v_cndmask_b32_e64 v135, v134, v135, s[8:9]
	v_fma_f32 v134, -v138, v134, v133
	v_cmp_lt_f32_e64 s[8:9], 0, v134
	s_nop 1
	v_cndmask_b32_e64 v134, v135, v138, s[8:9]
	v_mul_f32_e32 v135, 0x37800000, v134
	v_cndmask_b32_e64 v134, v134, v135, s[0:1]
	v_cmp_class_f32_e64 s[0:1], v133, v189
	s_nop 1
	v_cndmask_b32_e64 v133, v134, v133, s[0:1]
	v_div_scale_f32 v134, s[0:1], v133, v133, 1.0
	v_rcp_f32_e32 v135, v134
	v_div_scale_f32 v132, vcc, 1.0, v133, 1.0
	v_fma_f32 v130, -v134, v135, 1.0
	v_fmac_f32_e32 v135, v130, v135
	v_lshl_add_u64 v[130:131], v[206:207], 3, s[18:19]
	global_load_dwordx2 v[172:173], v[130:131], off
	v_lshl_add_u64 v[130:131], v[204:205], 3, s[18:19]
	global_load_dwordx2 v[210:211], v[130:131], off
	v_fma_f32 v130, -v170, v170, v171
	v_max_f32_e32 v130, 0, v130
	v_add_f32_e32 v130, 0x3727c5ac, v130
	v_mul_f32_e32 v131, 0x4f800000, v130
	v_cmp_gt_f32_e64 s[0:1], s58, v130
	v_mul_f32_e32 v138, v132, v135
	v_fma_f32 v136, -v134, v138, v132
	v_cndmask_b32_e64 v130, v130, v131, s[0:1]
	v_sqrt_f32_e32 v131, v130
	v_fmac_f32_e32 v138, v136, v135
	v_fma_f32 v132, -v134, v138, v132
	v_div_fmas_f32 v132, v132, v135, v138
	v_add_u32_e32 v134, -1, v131
	v_fma_f32 v136, -v134, v131, v130
	v_cmp_ge_f32_e64 s[8:9], 0, v136
	v_add_u32_e32 v136, 1, v131
	v_div_fixup_f32 v186, v132, v133, 1.0
	v_cndmask_b32_e64 v134, v131, v134, s[8:9]
	v_fma_f32 v131, -v136, v131, v130
	v_cmp_lt_f32_e64 s[8:9], 0, v131
	s_waitcnt vmcnt(0)
	v_pk_mul_f32 v[168:169], v[128:129], s[34:35] op_sel_hi:[1,0]
	v_cndmask_b32_e64 v131, v134, v136, s[8:9]
	v_mul_f32_e32 v134, 0x37800000, v131
	v_cndmask_b32_e64 v131, v131, v134, s[0:1]
	v_cmp_class_f32_e64 s[0:1], v130, v189
	v_fma_f32 v128, -v168, v168, v169
	v_max_f32_e32 v128, 0, v128
	v_cndmask_b32_e64 v130, v131, v130, s[0:1]
	v_div_scale_f32 v131, s[0:1], v130, v130, 1.0
	v_rcp_f32_e32 v134, v131
	v_add_f32_e32 v128, 0x3727c5ac, v128
	v_mul_f32_e32 v129, 0x4f800000, v128
	v_cmp_gt_f32_e64 s[0:1], s58, v128
	v_fma_f32 v132, -v131, v134, 1.0
	v_fmac_f32_e32 v134, v132, v134
	v_cndmask_b32_e64 v128, v128, v129, s[0:1]
	v_div_scale_f32 v132, vcc, 1.0, v130, 1.0
	v_sqrt_f32_e32 v129, v128
	v_mul_f32_e32 v133, v132, v134
	v_fma_f32 v135, -v131, v133, v132
	v_fmac_f32_e32 v133, v135, v134
	v_fma_f32 v131, -v131, v133, v132
	v_add_u32_e32 v132, -1, v129
	v_fma_f32 v135, -v132, v129, v128
	v_cmp_ge_f32_e64 s[8:9], 0, v135
	v_add_u32_e32 v135, 1, v129
	v_pk_mul_f32 v[178:179], v[172:173], s[34:35] op_sel_hi:[1,0]
	v_cndmask_b32_e64 v132, v129, v132, s[8:9]
	v_fma_f32 v129, -v135, v129, v128
	v_cmp_lt_f32_e64 s[8:9], 0, v129
	v_fma_f32 v172, -v178, v178, v179
	v_max_f32_e32 v172, 0, v172
	v_cndmask_b32_e64 v129, v132, v135, s[8:9]
	v_mul_f32_e32 v132, 0x37800000, v129
	v_cndmask_b32_e64 v129, v129, v132, s[0:1]
	v_cmp_class_f32_e64 s[0:1], v128, v189
	v_add_f32_e32 v172, 0x3727c5ac, v172
	v_mul_f32_e32 v173, 0x4f800000, v172
	v_cndmask_b32_e64 v180, v129, v128, s[0:1]
	v_div_scale_f32 v188, s[0:1], v180, v180, 1.0
	v_rcp_f32_e32 v190, v188
	v_div_fmas_f32 v128, v131, v134, v133
	v_lshlrev_b64 v[132:133], 2, v[208:209]
	v_div_fixup_f32 v182, v128, v130, 1.0
	v_fma_f32 v128, -v188, v190, 1.0
	v_lshl_add_u64 v[134:135], s[22:23], 0, v[132:133]
	v_fmac_f32_e32 v190, v128, v190
	global_load_dwordx4 v[128:131], v[134:135], off offset:16
	global_load_dwordx4 v[140:143], v[134:135], off
	v_lshl_add_u64 v[136:137], s[24:25], 0, v[132:133]
	global_load_dwordx4 v[132:135], v[136:137], off offset:16
	s_nop 0
	global_load_dwordx4 v[136:139], v[136:137], off
	v_cmp_gt_f32_e64 s[0:1], s58, v172
	v_div_scale_f32 v191, vcc, 1.0, v180, 1.0
	s_nop 0
	v_cndmask_b32_e64 v172, v172, v173, s[0:1]
	v_sqrt_f32_e32 v173, v172
	v_mul_f32_e32 v212, v191, v190
	v_fma_f32 v213, -v188, v212, v191
	v_fmac_f32_e32 v212, v213, v190
	v_fma_f32 v188, -v188, v212, v191
	v_add_u32_e32 v191, -1, v173
	v_fma_f32 v213, -v191, v173, v172
	v_cmp_ge_f32_e64 s[8:9], 0, v213
	v_add_u32_e32 v213, 1, v173
	s_waitcnt vmcnt(0)
	v_pk_fma_f32 v[120:121], v[166:167], v[128:129], v[120:121] op_sel_hi:[0,1,1] neg_lo:[1,0,0] neg_hi:[1,0,0]
	v_cndmask_b32_e64 v191, v173, v191, s[8:9]
	v_fma_f32 v173, -v213, v173, v172
	v_cmp_lt_f32_e64 s[8:9], 0, v173
	v_pk_fma_f32 v[124:125], v[166:167], v[140:141], v[124:125] op_sel_hi:[0,1,1] neg_lo:[1,0,0] neg_hi:[1,0,0]
	v_pk_fma_f32 v[126:127], v[166:167], v[142:143], v[126:127] op_sel_hi:[0,1,1] neg_lo:[1,0,0] neg_hi:[1,0,0]
	v_cndmask_b32_e64 v173, v191, v213, s[8:9]
	v_mul_f32_e32 v191, 0x37800000, v173
	v_cndmask_b32_e64 v173, v173, v191, s[0:1]
	v_cmp_class_f32_e64 s[0:1], v172, v189
	v_pk_fma_f32 v[126:127], v[184:185], v[126:127], v[138:139] op_sel_hi:[0,1,1]
	v_pk_fma_f32 v[124:125], v[184:185], v[124:125], v[136:137] op_sel_hi:[0,1,1]
	v_cndmask_b32_e64 v191, v173, v172, s[0:1]
	v_div_scale_f32 v213, s[0:1], v191, v191, 1.0
	v_rcp_f32_e32 v214, v213
	v_div_fmas_f32 v172, v188, v190, v212
	v_div_fixup_f32 v190, v172, v180, 1.0
	v_div_scale_f32 v180, vcc, 1.0, v191, 1.0
	v_fma_f32 v172, -v213, v214, 1.0
	v_fmac_f32_e32 v214, v172, v214
	v_pk_mul_f32 v[172:173], v[210:211], s[34:35] op_sel_hi:[1,0]
	v_mul_f32_e32 v188, v180, v214
	v_fma_f32 v210, -v172, v172, v173
	v_max_f32_e32 v210, 0, v210
	v_add_f32_e32 v210, 0x3727c5ac, v210
	v_mul_f32_e32 v211, 0x4f800000, v210
	v_cmp_gt_f32_e64 s[0:1], s58, v210
	v_fma_f32 v212, -v213, v188, v180
	v_fmac_f32_e32 v188, v212, v214
	v_cndmask_b32_e64 v210, v210, v211, s[0:1]
	v_sqrt_f32_e32 v211, v210
	v_fma_f32 v180, -v213, v188, v180
	v_pk_fma_f32 v[122:123], v[166:167], v[130:131], v[122:123] op_sel_hi:[0,1,1] neg_lo:[1,0,0] neg_hi:[1,0,0]
	v_pk_fma_f32 v[120:121], v[184:185], v[120:121], v[132:133] op_sel_hi:[0,1,1]
	v_add_u32_e32 v212, -1, v211
	v_fma_f32 v213, -v212, v211, v210
	v_cmp_ge_f32_e64 s[8:9], 0, v213
	v_add_u32_e32 v213, 1, v211
	v_pk_fma_f32 v[122:123], v[184:185], v[122:123], v[134:135] op_sel_hi:[0,1,1]
	v_cndmask_b32_e64 v212, v211, v212, s[8:9]
	v_fma_f32 v211, -v213, v211, v210
	v_cmp_lt_f32_e64 s[8:9], 0, v211
	v_max_f32_e32 v124, 0, v124
	v_max_f32_e32 v120, 0, v120
	v_cndmask_b32_e64 v211, v212, v213, s[8:9]
	v_max_f32_e32 v125, 0, v125
	v_max_f32_e32 v121, 0, v121
	v_max_f32_e32 v126, 0, v126
	v_max_f32_e32 v127, 0, v127
	v_mul_f32_e32 v212, 0x37800000, v211
	v_pk_mul_f32 v[124:125], v[124:125], v[124:125]
	v_pk_mul_f32 v[120:121], v[120:121], v[120:121]
	v_max_f32_e32 v122, 0, v122
	v_max_f32_e32 v123, 0, v123
	v_pk_mul_f32 v[126:127], v[126:127], v[126:127]
	v_pk_fma_f32 v[116:117], v[162:163], v[140:141], v[116:117] op_sel_hi:[0,1,1] neg_lo:[1,0,0] neg_hi:[1,0,0]
	v_pk_fma_f32 v[112:113], v[162:163], v[128:129], v[112:113] op_sel_hi:[0,1,1] neg_lo:[1,0,0] neg_hi:[1,0,0]
	v_cndmask_b32_e64 v211, v211, v212, s[0:1]
	v_cmp_class_f32_e64 s[0:1], v210, v189
	v_pk_mul_f32 v[122:123], v[122:123], v[122:123]
	v_cvt_pk_bf16_f32 v124, v124, v125
	v_cvt_pk_bf16_f32 v125, v126, v127
	v_cvt_pk_bf16_f32 v126, v120, v121
	v_lshlrev_b64 v[120:121], 14, v[202:203]
	v_pk_fma_f32 v[116:117], v[176:177], v[116:117], v[136:137] op_sel_hi:[0,1,1]
	v_pk_fma_f32 v[114:115], v[162:163], v[130:131], v[114:115] op_sel_hi:[0,1,1] neg_lo:[1,0,0] neg_hi:[1,0,0]
	v_pk_fma_f32 v[112:113], v[176:177], v[112:113], v[132:133] op_sel_hi:[0,1,1]
	v_cndmask_b32_e64 v210, v211, v210, s[0:1]
	v_cvt_pk_bf16_f32 v127, v122, v123
	v_lshl_add_u64 v[120:121], s[50:51], 0, v[120:121]
	v_lshlrev_b64 v[122:123], 1, v[208:209]
	v_pk_fma_f32 v[118:119], v[162:163], v[142:143], v[118:119] op_sel_hi:[0,1,1] neg_lo:[1,0,0] neg_hi:[1,0,0]
	v_pk_fma_f32 v[114:115], v[176:177], v[114:115], v[134:135] op_sel_hi:[0,1,1]
	v_max_f32_e32 v116, 0, v116
	v_max_f32_e32 v112, 0, v112
	v_max_f32_e32 v117, 0, v117
	v_max_f32_e32 v113, 0, v113
	v_div_scale_f32 v211, s[0:1], v210, v210, 1.0
	v_lshl_add_u64 v[120:121], v[120:121], 0, v[122:123]
	v_pk_fma_f32 v[118:119], v[176:177], v[118:119], v[138:139] op_sel_hi:[0,1,1]
	v_pk_mul_f32 v[116:117], v[116:117], v[116:117]
	v_pk_mul_f32 v[112:113], v[112:113], v[112:113]
	v_max_f32_e32 v114, 0, v114
	v_max_f32_e32 v115, 0, v115
	v_pk_fma_f32 v[108:109], v[160:161], v[140:141], v[108:109] op_sel_hi:[0,1,1] neg_lo:[1,0,0] neg_hi:[1,0,0]
	v_pk_fma_f32 v[104:105], v[160:161], v[128:129], v[104:105] op_sel_hi:[0,1,1] neg_lo:[1,0,0] neg_hi:[1,0,0]
	v_rcp_f32_e32 v212, v211
	global_store_dwordx4 v[120:121], v[124:127], off
	v_max_f32_e32 v118, 0, v118
	v_max_f32_e32 v119, 0, v119
	v_pk_mul_f32 v[124:125], v[114:115], v[114:115]
	v_cvt_pk_bf16_f32 v114, v116, v117
	v_cvt_pk_bf16_f32 v116, v112, v113
	v_lshlrev_b64 v[112:113], 14, v[200:201]
	v_pk_fma_f32 v[108:109], v[174:175], v[108:109], v[136:137] op_sel_hi:[0,1,1]
	v_pk_fma_f32 v[106:107], v[160:161], v[130:131], v[106:107] op_sel_hi:[0,1,1] neg_lo:[1,0,0] neg_hi:[1,0,0]
	v_pk_fma_f32 v[104:105], v[174:175], v[104:105], v[132:133] op_sel_hi:[0,1,1]
	v_pk_mul_f32 v[118:119], v[118:119], v[118:119]
	v_lshl_add_u64 v[112:113], s[50:51], 0, v[112:113]
	v_pk_fma_f32 v[110:111], v[160:161], v[142:143], v[110:111] op_sel_hi:[0,1,1] neg_lo:[1,0,0] neg_hi:[1,0,0]
	v_pk_fma_f32 v[106:107], v[174:175], v[106:107], v[134:135] op_sel_hi:[0,1,1]
	v_max_f32_e32 v108, 0, v108
	v_max_f32_e32 v104, 0, v104
	v_max_f32_e32 v109, 0, v109
	v_max_f32_e32 v105, 0, v105
	v_cvt_pk_bf16_f32 v115, v118, v119
	v_cvt_pk_bf16_f32 v117, v124, v125
	v_lshl_add_u64 v[112:113], v[112:113], 0, v[122:123]
	v_pk_fma_f32 v[110:111], v[174:175], v[110:111], v[138:139] op_sel_hi:[0,1,1]
	v_pk_mul_f32 v[108:109], v[108:109], v[108:109]
	v_pk_mul_f32 v[104:105], v[104:105], v[104:105]
	v_max_f32_e32 v106, 0, v106
	v_max_f32_e32 v107, 0, v107
	v_pk_fma_f32 v[100:101], v[164:165], v[140:141], v[100:101] op_sel_hi:[0,1,1] neg_lo:[1,0,0] neg_hi:[1,0,0]
	v_pk_fma_f32 v[96:97], v[164:165], v[128:129], v[96:97] op_sel_hi:[0,1,1] neg_lo:[1,0,0] neg_hi:[1,0,0]
	v_div_fmas_f32 v180, v180, v214, v188
	global_store_dwordx4 v[112:113], v[114:117], off
	v_max_f32_e32 v110, 0, v110
	v_max_f32_e32 v111, 0, v111
	v_pk_mul_f32 v[114:115], v[106:107], v[106:107]
	v_cvt_pk_bf16_f32 v106, v108, v109
	v_cvt_pk_bf16_f32 v108, v104, v105
	v_lshlrev_b64 v[104:105], 14, v[198:199]
	v_pk_fma_f32 v[100:101], v[186:187], v[100:101], v[136:137] op_sel_hi:[0,1,1]
	v_pk_fma_f32 v[98:99], v[164:165], v[130:131], v[98:99] op_sel_hi:[0,1,1] neg_lo:[1,0,0] neg_hi:[1,0,0]
	v_pk_fma_f32 v[96:97], v[186:187], v[96:97], v[132:133] op_sel_hi:[0,1,1]
	v_div_fixup_f32 v188, v180, v191, 1.0
	v_fma_f32 v180, -v211, v212, 1.0
	v_pk_mul_f32 v[110:111], v[110:111], v[110:111]
	v_lshl_add_u64 v[104:105], s[50:51], 0, v[104:105]
	v_pk_fma_f32 v[102:103], v[164:165], v[142:143], v[102:103] op_sel_hi:[0,1,1] neg_lo:[1,0,0] neg_hi:[1,0,0]
	v_pk_fma_f32 v[98:99], v[186:187], v[98:99], v[134:135] op_sel_hi:[0,1,1]
	v_max_f32_e32 v100, 0, v100
	v_max_f32_e32 v96, 0, v96
	v_max_f32_e32 v101, 0, v101
	v_max_f32_e32 v97, 0, v97
	v_fmac_f32_e32 v212, v180, v212
	v_div_scale_f32 v180, vcc, 1.0, v210, 1.0
	v_cvt_pk_bf16_f32 v107, v110, v111
	v_cvt_pk_bf16_f32 v109, v114, v115
	v_lshl_add_u64 v[104:105], v[104:105], 0, v[122:123]
	v_pk_fma_f32 v[102:103], v[186:187], v[102:103], v[138:139] op_sel_hi:[0,1,1]
	v_pk_mul_f32 v[100:101], v[100:101], v[100:101]
	v_pk_mul_f32 v[96:97], v[96:97], v[96:97]
	v_max_f32_e32 v98, 0, v98
	v_max_f32_e32 v99, 0, v99
	v_pk_fma_f32 v[92:93], v[170:171], v[140:141], v[92:93] op_sel_hi:[0,1,1] neg_lo:[1,0,0] neg_hi:[1,0,0]
	v_pk_fma_f32 v[88:89], v[170:171], v[128:129], v[88:89] op_sel_hi:[0,1,1] neg_lo:[1,0,0] neg_hi:[1,0,0]
	v_mul_f32_e32 v191, v180, v212
	global_store_dwordx4 v[104:105], v[106:109], off
	v_max_f32_e32 v102, 0, v102
	v_max_f32_e32 v103, 0, v103
	v_pk_mul_f32 v[106:107], v[98:99], v[98:99]
	v_cvt_pk_bf16_f32 v98, v100, v101
	v_cvt_pk_bf16_f32 v100, v96, v97
	v_lshlrev_b64 v[96:97], 14, v[196:197]
	v_pk_fma_f32 v[92:93], v[182:183], v[92:93], v[136:137] op_sel_hi:[0,1,1]
	v_pk_fma_f32 v[90:91], v[170:171], v[130:131], v[90:91] op_sel_hi:[0,1,1] neg_lo:[1,0,0] neg_hi:[1,0,0]
	v_pk_fma_f32 v[88:89], v[182:183], v[88:89], v[132:133] op_sel_hi:[0,1,1]
	v_fma_f32 v213, -v211, v191, v180
	v_pk_mul_f32 v[102:103], v[102:103], v[102:103]
	v_lshl_add_u64 v[96:97], s[50:51], 0, v[96:97]
	v_pk_fma_f32 v[94:95], v[170:171], v[142:143], v[94:95] op_sel_hi:[0,1,1] neg_lo:[1,0,0] neg_hi:[1,0,0]
	v_pk_fma_f32 v[90:91], v[182:183], v[90:91], v[134:135] op_sel_hi:[0,1,1]
	v_max_f32_e32 v92, 0, v92
	v_max_f32_e32 v88, 0, v88
	v_max_f32_e32 v93, 0, v93
	v_max_f32_e32 v89, 0, v89
	v_fmac_f32_e32 v191, v213, v212
	v_cvt_pk_bf16_f32 v99, v102, v103
	v_cvt_pk_bf16_f32 v101, v106, v107
	v_lshl_add_u64 v[96:97], v[96:97], 0, v[122:123]
	v_pk_fma_f32 v[94:95], v[182:183], v[94:95], v[138:139] op_sel_hi:[0,1,1]
	v_pk_mul_f32 v[92:93], v[92:93], v[92:93]
	v_pk_mul_f32 v[88:89], v[88:89], v[88:89]
	v_max_f32_e32 v90, 0, v90
	v_max_f32_e32 v91, 0, v91
	v_pk_fma_f32 v[84:85], v[168:169], v[140:141], v[84:85] op_sel_hi:[0,1,1] neg_lo:[1,0,0] neg_hi:[1,0,0]
	v_pk_fma_f32 v[80:81], v[168:169], v[128:129], v[80:81] op_sel_hi:[0,1,1] neg_lo:[1,0,0] neg_hi:[1,0,0]
	global_store_dwordx4 v[96:97], v[98:101], off
	v_max_f32_e32 v94, 0, v94
	v_max_f32_e32 v95, 0, v95
	v_pk_mul_f32 v[98:99], v[90:91], v[90:91]
	v_cvt_pk_bf16_f32 v90, v92, v93
	v_cvt_pk_bf16_f32 v92, v88, v89
	v_lshlrev_b64 v[88:89], 14, v[194:195]
	v_pk_fma_f32 v[84:85], v[84:85], v[190:191], v[136:137] op_sel_hi:[1,0,1]
	v_pk_fma_f32 v[82:83], v[168:169], v[130:131], v[82:83] op_sel_hi:[0,1,1] neg_lo:[1,0,0] neg_hi:[1,0,0]
	v_pk_fma_f32 v[80:81], v[190:191], v[80:81], v[132:133] op_sel_hi:[0,1,1]
	v_pk_mul_f32 v[94:95], v[94:95], v[94:95]
	v_lshl_add_u64 v[88:89], s[50:51], 0, v[88:89]
	v_pk_fma_f32 v[86:87], v[168:169], v[142:143], v[86:87] op_sel_hi:[0,1,1] neg_lo:[1,0,0] neg_hi:[1,0,0]
	v_pk_fma_f32 v[82:83], v[190:191], v[82:83], v[134:135] op_sel_hi:[0,1,1]
	v_max_f32_e32 v84, 0, v84
	v_max_f32_e32 v80, 0, v80
	v_max_f32_e32 v85, 0, v85
	v_max_f32_e32 v81, 0, v81
	v_cvt_pk_bf16_f32 v91, v94, v95
	v_cvt_pk_bf16_f32 v93, v98, v99
	v_lshl_add_u64 v[88:89], v[88:89], 0, v[122:123]
	v_pk_fma_f32 v[86:87], v[86:87], v[190:191], v[138:139] op_sel_hi:[1,0,1]
	v_pk_mul_f32 v[84:85], v[84:85], v[84:85]
	v_pk_mul_f32 v[80:81], v[80:81], v[80:81]
	v_max_f32_e32 v82, 0, v82
	v_max_f32_e32 v83, 0, v83
	global_store_dwordx4 v[88:89], v[90:93], off
	v_max_f32_e32 v86, 0, v86
	v_max_f32_e32 v87, 0, v87
	v_pk_mul_f32 v[90:91], v[82:83], v[82:83]
	v_cvt_pk_bf16_f32 v82, v84, v85
	v_cvt_pk_bf16_f32 v84, v80, v81
	v_lshlrev_b64 v[80:81], 14, v[192:193]
	v_pk_fma_f32 v[76:77], v[178:179], v[140:141], v[76:77] op_sel_hi:[0,1,1] neg_lo:[1,0,0] neg_hi:[1,0,0]
	v_pk_fma_f32 v[72:73], v[178:179], v[128:129], v[72:73] op_sel_hi:[0,1,1] neg_lo:[1,0,0] neg_hi:[1,0,0]
	v_pk_mul_f32 v[86:87], v[86:87], v[86:87]
	v_lshl_add_u64 v[80:81], s[50:51], 0, v[80:81]
	v_pk_fma_f32 v[78:79], v[178:179], v[142:143], v[78:79] op_sel_hi:[0,1,1] neg_lo:[1,0,0] neg_hi:[1,0,0]
	v_pk_fma_f32 v[76:77], v[76:77], v[188:189], v[136:137] op_sel_hi:[1,0,1]
	v_pk_fma_f32 v[72:73], v[72:73], v[188:189], v[132:133] op_sel_hi:[1,0,1]
	v_cvt_pk_bf16_f32 v83, v86, v87
	v_cvt_pk_bf16_f32 v85, v90, v91
	v_lshl_add_u64 v[80:81], v[80:81], 0, v[122:123]
	v_pk_fma_f32 v[78:79], v[78:79], v[188:189], v[138:139] op_sel_hi:[1,0,1]
	v_pk_fma_f32 v[74:75], v[178:179], v[130:131], v[74:75] op_sel_hi:[0,1,1] neg_lo:[1,0,0] neg_hi:[1,0,0]
	v_max_f32_e32 v76, 0, v76
	v_max_f32_e32 v72, 0, v72
	v_max_f32_e32 v77, 0, v77
	v_max_f32_e32 v73, 0, v73
	global_store_dwordx4 v[80:81], v[82:85], off
	v_pk_fma_f32 v[74:75], v[74:75], v[188:189], v[134:135] op_sel_hi:[1,0,1]
	v_pk_mul_f32 v[76:77], v[76:77], v[76:77]
	v_pk_mul_f32 v[82:83], v[72:73], v[72:73]
	v_max_f32_e32 v72, 0, v78
	v_max_f32_e32 v73, 0, v79
	v_max_f32_e32 v74, 0, v74
	v_max_f32_e32 v75, 0, v75
	v_pk_mul_f32 v[78:79], v[72:73], v[72:73]
	v_cvt_pk_bf16_f32 v72, v76, v77
	v_lshlrev_b64 v[76:77], 14, v[206:207]
	v_fma_f32 v180, -v211, v191, v180
	v_pk_mul_f32 v[84:85], v[74:75], v[74:75]
	v_lshl_add_u64 v[76:77], s[50:51], 0, v[76:77]
	v_div_fmas_f32 v180, v180, v212, v191
	v_cvt_pk_bf16_f32 v73, v78, v79
	v_cvt_pk_bf16_f32 v74, v82, v83
	v_cvt_pk_bf16_f32 v75, v84, v85
	v_lshl_add_u64 v[82:83], v[76:77], 0, v[122:123]
	v_div_fixup_f32 v180, v180, v210, 1.0
	global_store_dwordx4 v[82:83], v[72:75], off
	v_pk_fma_f32 v[68:69], v[140:141], v[172:173], v[68:69] op_sel_hi:[1,0,1] neg_lo:[1,0,0] neg_hi:[1,0,0]
	v_pk_fma_f32 v[64:65], v[172:173], v[128:129], v[64:65] op_sel_hi:[0,1,1] neg_lo:[1,0,0] neg_hi:[1,0,0]
	v_xor_b32_e32 v73, 0x80000000, v143
	v_xor_b32_e32 v72, 0x80000000, v142
	v_pk_fma_f32 v[70:71], v[72:73], v[172:173], v[70:71] op_sel_hi:[1,0,1]
	v_pk_fma_f32 v[68:69], v[68:69], v[180:181], v[136:137] op_sel_hi:[1,0,1]
	v_pk_fma_f32 v[64:65], v[64:65], v[180:181], v[132:133] op_sel_hi:[1,0,1]
	v_pk_fma_f32 v[70:71], v[70:71], v[180:181], v[138:139] op_sel_hi:[1,0,1]
	v_pk_fma_f32 v[66:67], v[172:173], v[130:131], v[66:67] op_sel_hi:[0,1,1] neg_lo:[1,0,0] neg_hi:[1,0,0]
	v_max_f32_e32 v68, 0, v68
	v_max_f32_e32 v64, 0, v64
	v_max_f32_e32 v69, 0, v69
	v_max_f32_e32 v65, 0, v65
	v_pk_fma_f32 v[66:67], v[66:67], v[180:181], v[134:135] op_sel_hi:[1,0,1]
	v_pk_mul_f32 v[68:69], v[68:69], v[68:69]
	v_pk_mul_f32 v[72:73], v[64:65], v[64:65]
	v_max_f32_e32 v64, 0, v70
	v_max_f32_e32 v65, 0, v71
	v_max_f32_e32 v66, 0, v66
	v_max_f32_e32 v67, 0, v67
	v_pk_mul_f32 v[70:71], v[64:65], v[64:65]
	v_cvt_pk_bf16_f32 v64, v68, v69
	v_lshlrev_b64 v[68:69], 14, v[204:205]
	v_pk_mul_f32 v[74:75], v[66:67], v[66:67]
	v_lshl_add_u64 v[68:69], s[50:51], 0, v[68:69]
	v_cvt_pk_bf16_f32 v65, v70, v71
	v_cvt_pk_bf16_f32 v66, v72, v73
	v_cvt_pk_bf16_f32 v67, v74, v75
	v_lshl_add_u64 v[84:85], v[68:69], 0, v[122:123]
	global_store_dwordx4 v[84:85], v[64:67], off
	s_and_b64 vcc, exec, s[6:7]
	s_mov_b64 s[0:1], -1
	v_or_b32_e32 v64, 0x80, v208
	v_ashrrev_i32_e32 v65, 31, v64
	v_lshlrev_b64 v[64:65], 2, v[64:65]
	v_lshl_add_u64 v[66:67], s[22:23], 0, v[64:65]
	v_lshl_add_u64 v[64:65], s[24:25], 0, v[64:65]
	global_load_dwordx4 v[72:75], v[66:67], off
	global_load_dwordx4 v[76:79], v[64:65], off
	global_load_dwordx4 v[68:71], v[66:67], off offset:16
	s_nop 0
	global_load_dwordx4 v[64:67], v[64:65], off offset:16
	s_waitcnt vmcnt(0)
	v_pk_fma_f32 v[56:57], v[166:167], v[68:69], v[56:57] op_sel_hi:[0,1,1] neg_lo:[1,0,0] neg_hi:[1,0,0]
	v_pk_fma_f32 v[60:61], v[166:167], v[72:73], v[60:61] op_sel_hi:[0,1,1] neg_lo:[1,0,0] neg_hi:[1,0,0]
	v_pk_fma_f32 v[62:63], v[166:167], v[74:75], v[62:63] op_sel_hi:[0,1,1] neg_lo:[1,0,0] neg_hi:[1,0,0]
	v_pk_fma_f32 v[58:59], v[166:167], v[70:71], v[58:59] op_sel_hi:[0,1,1] neg_lo:[1,0,0] neg_hi:[1,0,0]
	v_pk_fma_f32 v[56:57], v[184:185], v[56:57], v[64:65] op_sel_hi:[0,1,1]
	v_pk_fma_f32 v[62:63], v[184:185], v[62:63], v[78:79] op_sel_hi:[0,1,1]
	v_pk_fma_f32 v[60:61], v[184:185], v[60:61], v[76:77] op_sel_hi:[0,1,1]
	v_pk_fma_f32 v[58:59], v[184:185], v[58:59], v[66:67] op_sel_hi:[0,1,1]
	v_max_f32_e32 v56, 0, v56
	v_max_f32_e32 v57, 0, v57
	v_max_f32_e32 v60, 0, v60
	v_max_f32_e32 v61, 0, v61
	v_pk_mul_f32 v[86:87], v[56:57], v[56:57]
	v_max_f32_e32 v56, 0, v62
	v_max_f32_e32 v58, 0, v58
	v_max_f32_e32 v57, 0, v63
	v_max_f32_e32 v59, 0, v59
	v_pk_fma_f32 v[48:49], v[162:163], v[68:69], v[48:49] op_sel_hi:[0,1,1] neg_lo:[1,0,0] neg_hi:[1,0,0]
	v_pk_mul_f32 v[60:61], v[60:61], v[60:61]
	v_pk_mul_f32 v[62:63], v[56:57], v[56:57]
	v_pk_mul_f32 v[90:91], v[58:59], v[58:59]
	v_pk_fma_f32 v[52:53], v[162:163], v[72:73], v[52:53] op_sel_hi:[0,1,1] neg_lo:[1,0,0] neg_hi:[1,0,0]
	v_pk_fma_f32 v[54:55], v[162:163], v[74:75], v[54:55] op_sel_hi:[0,1,1] neg_lo:[1,0,0] neg_hi:[1,0,0]
	v_pk_fma_f32 v[50:51], v[162:163], v[70:71], v[50:51] op_sel_hi:[0,1,1] neg_lo:[1,0,0] neg_hi:[1,0,0]
	v_pk_fma_f32 v[48:49], v[176:177], v[48:49], v[64:65] op_sel_hi:[0,1,1]
	v_cvt_pk_bf16_f32 v56, v60, v61
	v_cvt_pk_bf16_f32 v57, v62, v63
	v_cvt_pk_bf16_f32 v58, v86, v87
	v_cvt_pk_bf16_f32 v59, v90, v91
	v_pk_fma_f32 v[54:55], v[176:177], v[54:55], v[78:79] op_sel_hi:[0,1,1]
	v_pk_fma_f32 v[52:53], v[176:177], v[52:53], v[76:77] op_sel_hi:[0,1,1]
	v_pk_fma_f32 v[50:51], v[176:177], v[50:51], v[66:67] op_sel_hi:[0,1,1]
	v_max_f32_e32 v48, 0, v48
	v_max_f32_e32 v49, 0, v49
	global_store_dwordx4 v[120:121], v[56:59], off offset:256
	v_max_f32_e32 v52, 0, v52
	v_max_f32_e32 v53, 0, v53
	v_pk_mul_f32 v[56:57], v[48:49], v[48:49]
	v_max_f32_e32 v48, 0, v54
	v_max_f32_e32 v50, 0, v50
	v_max_f32_e32 v49, 0, v55
	v_max_f32_e32 v51, 0, v51
	v_pk_fma_f32 v[40:41], v[160:161], v[68:69], v[40:41] op_sel_hi:[0,1,1] neg_lo:[1,0,0] neg_hi:[1,0,0]
	v_pk_mul_f32 v[52:53], v[52:53], v[52:53]
	v_pk_mul_f32 v[54:55], v[48:49], v[48:49]
	v_pk_mul_f32 v[58:59], v[50:51], v[50:51]
	v_pk_fma_f32 v[44:45], v[160:161], v[72:73], v[44:45] op_sel_hi:[0,1,1] neg_lo:[1,0,0] neg_hi:[1,0,0]
	v_pk_fma_f32 v[46:47], v[160:161], v[74:75], v[46:47] op_sel_hi:[0,1,1] neg_lo:[1,0,0] neg_hi:[1,0,0]
	v_pk_fma_f32 v[42:43], v[160:161], v[70:71], v[42:43] op_sel_hi:[0,1,1] neg_lo:[1,0,0] neg_hi:[1,0,0]
	v_pk_fma_f32 v[40:41], v[174:175], v[40:41], v[64:65] op_sel_hi:[0,1,1]
	v_cvt_pk_bf16_f32 v48, v52, v53
	v_cvt_pk_bf16_f32 v49, v54, v55
	v_cvt_pk_bf16_f32 v50, v56, v57
	v_cvt_pk_bf16_f32 v51, v58, v59
	v_pk_fma_f32 v[46:47], v[174:175], v[46:47], v[78:79] op_sel_hi:[0,1,1]
	v_pk_fma_f32 v[44:45], v[174:175], v[44:45], v[76:77] op_sel_hi:[0,1,1]
	v_pk_fma_f32 v[42:43], v[174:175], v[42:43], v[66:67] op_sel_hi:[0,1,1]
	v_max_f32_e32 v40, 0, v40
	v_max_f32_e32 v41, 0, v41
	global_store_dwordx4 v[112:113], v[48:51], off offset:256
	v_max_f32_e32 v44, 0, v44
	v_max_f32_e32 v45, 0, v45
	v_pk_mul_f32 v[48:49], v[40:41], v[40:41]
	v_max_f32_e32 v40, 0, v46
	v_max_f32_e32 v42, 0, v42
	v_max_f32_e32 v41, 0, v47
	v_max_f32_e32 v43, 0, v43
	v_pk_fma_f32 v[32:33], v[164:165], v[68:69], v[32:33] op_sel_hi:[0,1,1] neg_lo:[1,0,0] neg_hi:[1,0,0]
	v_pk_mul_f32 v[44:45], v[44:45], v[44:45]
	v_pk_mul_f32 v[46:47], v[40:41], v[40:41]
	v_pk_mul_f32 v[50:51], v[42:43], v[42:43]
	v_pk_fma_f32 v[36:37], v[164:165], v[72:73], v[36:37] op_sel_hi:[0,1,1] neg_lo:[1,0,0] neg_hi:[1,0,0]
	v_pk_fma_f32 v[38:39], v[164:165], v[74:75], v[38:39] op_sel_hi:[0,1,1] neg_lo:[1,0,0] neg_hi:[1,0,0]
	v_pk_fma_f32 v[34:35], v[164:165], v[70:71], v[34:35] op_sel_hi:[0,1,1] neg_lo:[1,0,0] neg_hi:[1,0,0]
	v_pk_fma_f32 v[32:33], v[186:187], v[32:33], v[64:65] op_sel_hi:[0,1,1]
	v_cvt_pk_bf16_f32 v40, v44, v45
	v_cvt_pk_bf16_f32 v41, v46, v47
	v_cvt_pk_bf16_f32 v42, v48, v49
	v_cvt_pk_bf16_f32 v43, v50, v51
	v_pk_fma_f32 v[38:39], v[186:187], v[38:39], v[78:79] op_sel_hi:[0,1,1]
	v_pk_fma_f32 v[36:37], v[186:187], v[36:37], v[76:77] op_sel_hi:[0,1,1]
	v_pk_fma_f32 v[34:35], v[186:187], v[34:35], v[66:67] op_sel_hi:[0,1,1]
	v_max_f32_e32 v32, 0, v32
	v_max_f32_e32 v33, 0, v33
	global_store_dwordx4 v[104:105], v[40:43], off offset:256
	v_max_f32_e32 v36, 0, v36
	v_max_f32_e32 v37, 0, v37
	v_pk_mul_f32 v[40:41], v[32:33], v[32:33]
	v_max_f32_e32 v32, 0, v38
	v_max_f32_e32 v34, 0, v34
	v_max_f32_e32 v33, 0, v39
	v_max_f32_e32 v35, 0, v35
	v_pk_fma_f32 v[24:25], v[170:171], v[68:69], v[24:25] op_sel_hi:[0,1,1] neg_lo:[1,0,0] neg_hi:[1,0,0]
	v_pk_mul_f32 v[36:37], v[36:37], v[36:37]
	v_pk_mul_f32 v[38:39], v[32:33], v[32:33]
	v_pk_mul_f32 v[42:43], v[34:35], v[34:35]
	v_pk_fma_f32 v[28:29], v[170:171], v[72:73], v[28:29] op_sel_hi:[0,1,1] neg_lo:[1,0,0] neg_hi:[1,0,0]
	v_pk_fma_f32 v[30:31], v[170:171], v[74:75], v[30:31] op_sel_hi:[0,1,1] neg_lo:[1,0,0] neg_hi:[1,0,0]
	v_pk_fma_f32 v[26:27], v[170:171], v[70:71], v[26:27] op_sel_hi:[0,1,1] neg_lo:[1,0,0] neg_hi:[1,0,0]
	v_pk_fma_f32 v[24:25], v[182:183], v[24:25], v[64:65] op_sel_hi:[0,1,1]
	v_cvt_pk_bf16_f32 v32, v36, v37
	v_cvt_pk_bf16_f32 v33, v38, v39
	v_cvt_pk_bf16_f32 v34, v40, v41
	v_cvt_pk_bf16_f32 v35, v42, v43
	v_pk_fma_f32 v[30:31], v[182:183], v[30:31], v[78:79] op_sel_hi:[0,1,1]
	v_pk_fma_f32 v[28:29], v[182:183], v[28:29], v[76:77] op_sel_hi:[0,1,1]
	v_pk_fma_f32 v[26:27], v[182:183], v[26:27], v[66:67] op_sel_hi:[0,1,1]
	v_max_f32_e32 v24, 0, v24
	v_max_f32_e32 v25, 0, v25
	global_store_dwordx4 v[96:97], v[32:35], off offset:256
	v_max_f32_e32 v28, 0, v28
	v_max_f32_e32 v29, 0, v29
	v_pk_mul_f32 v[32:33], v[24:25], v[24:25]
	v_max_f32_e32 v24, 0, v30
	v_max_f32_e32 v26, 0, v26
	v_max_f32_e32 v25, 0, v31
	v_max_f32_e32 v27, 0, v27
	v_pk_fma_f32 v[16:17], v[168:169], v[68:69], v[16:17] op_sel_hi:[0,1,1] neg_lo:[1,0,0] neg_hi:[1,0,0]
	v_pk_mul_f32 v[28:29], v[28:29], v[28:29]
	v_pk_mul_f32 v[30:31], v[24:25], v[24:25]
	v_pk_mul_f32 v[34:35], v[26:27], v[26:27]
	v_pk_fma_f32 v[20:21], v[168:169], v[72:73], v[20:21] op_sel_hi:[0,1,1] neg_lo:[1,0,0] neg_hi:[1,0,0]
	v_pk_fma_f32 v[22:23], v[168:169], v[74:75], v[22:23] op_sel_hi:[0,1,1] neg_lo:[1,0,0] neg_hi:[1,0,0]
	v_pk_fma_f32 v[18:19], v[168:169], v[70:71], v[18:19] op_sel_hi:[0,1,1] neg_lo:[1,0,0] neg_hi:[1,0,0]
	v_pk_fma_f32 v[16:17], v[190:191], v[16:17], v[64:65] op_sel_hi:[0,1,1]
	v_cvt_pk_bf16_f32 v24, v28, v29
	v_cvt_pk_bf16_f32 v25, v30, v31
	v_cvt_pk_bf16_f32 v26, v32, v33
	v_cvt_pk_bf16_f32 v27, v34, v35
	v_pk_fma_f32 v[22:23], v[190:191], v[22:23], v[78:79] op_sel_hi:[0,1,1]
	v_pk_fma_f32 v[20:21], v[190:191], v[20:21], v[76:77] op_sel_hi:[0,1,1]
	v_pk_fma_f32 v[18:19], v[190:191], v[18:19], v[66:67] op_sel_hi:[0,1,1]
	v_max_f32_e32 v16, 0, v16
	v_max_f32_e32 v17, 0, v17
	global_store_dwordx4 v[88:89], v[24:27], off offset:256
	v_max_f32_e32 v20, 0, v20
	v_max_f32_e32 v21, 0, v21
	v_pk_mul_f32 v[24:25], v[16:17], v[16:17]
	v_max_f32_e32 v16, 0, v22
	v_max_f32_e32 v18, 0, v18
	v_max_f32_e32 v17, 0, v23
	v_max_f32_e32 v19, 0, v19
	v_pk_fma_f32 v[8:9], v[178:179], v[68:69], v[8:9] op_sel_hi:[0,1,1] neg_lo:[1,0,0] neg_hi:[1,0,0]
	v_pk_mul_f32 v[20:21], v[20:21], v[20:21]
	v_pk_mul_f32 v[22:23], v[16:17], v[16:17]
	v_pk_mul_f32 v[26:27], v[18:19], v[18:19]
	v_pk_fma_f32 v[12:13], v[178:179], v[72:73], v[12:13] op_sel_hi:[0,1,1] neg_lo:[1,0,0] neg_hi:[1,0,0]
	v_pk_fma_f32 v[14:15], v[178:179], v[74:75], v[14:15] op_sel_hi:[0,1,1] neg_lo:[1,0,0] neg_hi:[1,0,0]
	v_pk_fma_f32 v[10:11], v[178:179], v[70:71], v[10:11] op_sel_hi:[0,1,1] neg_lo:[1,0,0] neg_hi:[1,0,0]
	v_pk_fma_f32 v[8:9], v[188:189], v[8:9], v[64:65] op_sel_hi:[0,1,1]
	v_cvt_pk_bf16_f32 v16, v20, v21
	v_cvt_pk_bf16_f32 v17, v22, v23
	v_cvt_pk_bf16_f32 v18, v24, v25
	v_cvt_pk_bf16_f32 v19, v26, v27
	v_pk_fma_f32 v[14:15], v[188:189], v[14:15], v[78:79] op_sel_hi:[0,1,1]
	v_pk_fma_f32 v[12:13], v[188:189], v[12:13], v[76:77] op_sel_hi:[0,1,1]
	v_pk_fma_f32 v[10:11], v[188:189], v[10:11], v[66:67] op_sel_hi:[0,1,1]
	v_max_f32_e32 v8, 0, v8
	v_max_f32_e32 v9, 0, v9
	global_store_dwordx4 v[80:81], v[16:19], off offset:256
	v_max_f32_e32 v12, 0, v12
	v_max_f32_e32 v13, 0, v13
	v_pk_mul_f32 v[16:17], v[8:9], v[8:9]
	v_max_f32_e32 v8, 0, v14
	v_max_f32_e32 v10, 0, v10
	v_max_f32_e32 v9, 0, v15
	v_max_f32_e32 v11, 0, v11
	v_pk_fma_f32 v[0:1], v[172:173], v[68:69], v[0:1] op_sel_hi:[0,1,1] neg_lo:[1,0,0] neg_hi:[1,0,0]
	v_pk_mul_f32 v[12:13], v[12:13], v[12:13]
	v_pk_mul_f32 v[14:15], v[8:9], v[8:9]
	v_pk_mul_f32 v[18:19], v[10:11], v[10:11]
	v_pk_fma_f32 v[4:5], v[172:173], v[72:73], v[4:5] op_sel_hi:[0,1,1] neg_lo:[1,0,0] neg_hi:[1,0,0]
	v_pk_fma_f32 v[6:7], v[172:173], v[74:75], v[6:7] op_sel_hi:[0,1,1] neg_lo:[1,0,0] neg_hi:[1,0,0]
	v_pk_fma_f32 v[2:3], v[172:173], v[70:71], v[2:3] op_sel_hi:[0,1,1] neg_lo:[1,0,0] neg_hi:[1,0,0]
	v_pk_fma_f32 v[0:1], v[180:181], v[0:1], v[64:65] op_sel_hi:[0,1,1]
	v_cvt_pk_bf16_f32 v8, v12, v13
	v_cvt_pk_bf16_f32 v9, v14, v15
	v_cvt_pk_bf16_f32 v10, v16, v17
	v_cvt_pk_bf16_f32 v11, v18, v19
	v_pk_fma_f32 v[6:7], v[180:181], v[6:7], v[78:79] op_sel_hi:[0,1,1]
	v_pk_fma_f32 v[4:5], v[180:181], v[4:5], v[76:77] op_sel_hi:[0,1,1]
	v_pk_fma_f32 v[2:3], v[180:181], v[2:3], v[66:67] op_sel_hi:[0,1,1]
	v_max_f32_e32 v0, 0, v0
	v_max_f32_e32 v1, 0, v1
	global_store_dwordx4 v[82:83], v[8:11], off offset:256
	v_max_f32_e32 v4, 0, v4
	v_max_f32_e32 v5, 0, v5
	v_pk_mul_f32 v[8:9], v[0:1], v[0:1]
	v_max_f32_e32 v0, 0, v6
	v_max_f32_e32 v2, 0, v2
	v_max_f32_e32 v1, 0, v7
	v_max_f32_e32 v3, 0, v3
	v_pk_mul_f32 v[4:5], v[4:5], v[4:5]
	v_pk_mul_f32 v[6:7], v[0:1], v[0:1]
	v_pk_mul_f32 v[10:11], v[2:3], v[2:3]
	v_cvt_pk_bf16_f32 v0, v4, v5
	v_cvt_pk_bf16_f32 v1, v6, v7
	v_cvt_pk_bf16_f32 v2, v8, v9
	v_cvt_pk_bf16_f32 v3, v10, v11
	global_store_dwordx4 v[84:85], v[0:3], off offset:256
	s_cbranch_vccnz .LBB0_1376
	s_andn2_b64 vcc, exec, s[20:21]
	s_cbranch_vccnz .LBB0_1375
	s_barrier
	s_branch .LBB0_1375

.LBB0_1472:
	ds_read_b128 v[128:131], v224
	ds_read_b128 v[132:135], v224 offset:1024
	ds_read_b128 v[136:139], v224 offset:2048
	ds_read_b128 v[140:143], v224 offset:3072
	ds_read_b128 v[160:163], v225
	ds_read_b128 v[164:167], v225 offset:1024
	ds_read_b128 v[168:171], v225 offset:2048
	ds_read_b128 v[172:175], v225 offset:3072
	s_add_i32 s64, s40, 2
	s_add_u32 s65, s0, 0x80
	s_addc_u32 s41, s1, 0
	s_cmp_eq_u32 s56, s40
	s_cselect_b32 s40, s36, s65
	s_cselect_b32 s41, s37, s41
	s_cselect_b32 s67, s39, s43
	s_cselect_b32 s66, s38, s42
	v_lshl_add_u64 v[208:209], s[0:1], 0, v[152:153]
	s_add_i32 m0, s45, 0xc000
	ds_read_b128 v[176:179], v226
	ds_read_b128 v[180:183], v226 offset:1024
	ds_read_b128 v[184:187], v226 offset:2048
	ds_read_b128 v[188:191], v226 offset:3072
	ds_read_b128 v[192:195], v226 offset:4096
	ds_read_b128 v[196:199], v226 offset:5120
	ds_read_b128 v[200:203], v226 offset:6144
	ds_read_b128 v[204:207], v226 offset:7168
	global_load_lds_dwordx4 v[208:209], off
	v_lshl_add_u64 v[208:209], s[0:1], 0, v[154:155]
	s_add_i32 m0, s45, 0xe000
	s_nop 0
	global_load_lds_dwordx4 v[208:209], off
	s_waitcnt vmcnt(8)
	s_waitcnt lgkmcnt(0)
	s_setprio 1
	s_barrier
	v_mfma_f32_16x16x32_bf16 v[124:127], v[128:131], v[176:179], v[124:127]
	v_mfma_f32_16x16x32_bf16 v[120:123], v[136:139], v[176:179], v[120:123]
	v_mfma_f32_16x16x32_bf16 v[116:119], v[128:131], v[184:187], v[116:119]
	v_mfma_f32_16x16x32_bf16 v[112:115], v[136:139], v[184:187], v[112:115]
	v_mfma_f32_16x16x32_bf16 v[108:111], v[128:131], v[192:195], v[108:111]
	v_mfma_f32_16x16x32_bf16 v[104:107], v[136:139], v[192:195], v[104:107]
	v_mfma_f32_16x16x32_bf16 v[100:103], v[128:131], v[200:203], v[100:103]
	v_mfma_f32_16x16x32_bf16 v[96:99], v[136:139], v[200:203], v[96:99]
	v_mfma_f32_16x16x32_bf16 v[124:127], v[132:135], v[180:183], v[124:127]
	v_mfma_f32_16x16x32_bf16 v[120:123], v[140:143], v[180:183], v[120:123]
	v_mfma_f32_16x16x32_bf16 v[116:119], v[132:135], v[188:191], v[116:119]
	v_mfma_f32_16x16x32_bf16 v[112:115], v[140:143], v[188:191], v[112:115]
	v_mfma_f32_16x16x32_bf16 v[108:111], v[132:135], v[196:199], v[108:111]
	v_mfma_f32_16x16x32_bf16 v[104:107], v[140:143], v[196:199], v[104:107]
	v_mfma_f32_16x16x32_bf16 v[100:103], v[132:135], v[204:207], v[100:103]
	v_mfma_f32_16x16x32_bf16 v[96:99], v[140:143], v[204:207], v[96:99]
	v_mfma_f32_16x16x32_bf16 v[60:63], v[160:163], v[176:179], v[60:63]
	v_mfma_f32_16x16x32_bf16 v[56:59], v[168:171], v[176:179], v[56:59]
	v_mfma_f32_16x16x32_bf16 v[52:55], v[160:163], v[184:187], v[52:55]
	v_mfma_f32_16x16x32_bf16 v[48:51], v[168:171], v[184:187], v[48:51]
	v_mfma_f32_16x16x32_bf16 v[44:47], v[160:163], v[192:195], v[44:47]
	v_mfma_f32_16x16x32_bf16 v[40:43], v[168:171], v[192:195], v[40:43]
	v_mfma_f32_16x16x32_bf16 v[36:39], v[160:163], v[200:203], v[36:39]
	v_mfma_f32_16x16x32_bf16 v[32:35], v[168:171], v[200:203], v[32:35]
	v_mfma_f32_16x16x32_bf16 v[60:63], v[164:167], v[180:183], v[60:63]
	v_mfma_f32_16x16x32_bf16 v[56:59], v[172:175], v[180:183], v[56:59]
	v_mfma_f32_16x16x32_bf16 v[52:55], v[164:167], v[188:191], v[52:55]
	v_mfma_f32_16x16x32_bf16 v[48:51], v[172:175], v[188:191], v[48:51]
	v_mfma_f32_16x16x32_bf16 v[44:47], v[164:167], v[196:199], v[44:47]
	v_mfma_f32_16x16x32_bf16 v[40:43], v[172:175], v[196:199], v[40:43]
	v_mfma_f32_16x16x32_bf16 v[36:39], v[164:167], v[204:207], v[36:39]
	v_mfma_f32_16x16x32_bf16 v[32:35], v[172:175], v[204:207], v[32:35]
	s_barrier
	s_setprio 0
	s_add_i32 s65, s59, s44
	v_lshl_add_u64 v[208:209], s[66:67], 0, v[146:147]
	s_mov_b32 m0, s65
	ds_read_b128 v[176:179], v226 offset:16384
	ds_read_b128 v[180:183], v226 offset:17408
	ds_read_b128 v[184:187], v226 offset:18432
	ds_read_b128 v[188:191], v226 offset:19456
	ds_read_b128 v[192:195], v226 offset:20480
	ds_read_b128 v[196:199], v226 offset:21504
	ds_read_b128 v[200:203], v226 offset:22528
	ds_read_b128 v[204:207], v226 offset:23552
	global_load_lds_dwordx4 v[208:209], off
	s_add_i32 m0, s65, 0x2000
	v_lshl_add_u64 v[210:211], s[66:67], 0, v[150:151]
	s_add_u32 s66, s66, s8
	s_addc_u32 s67, s67, s9
	s_add_i32 s65, s60, s44
	global_load_lds_dwordx4 v[210:211], off
	v_lshl_add_u64 v[212:213], s[66:67], 0, v[146:147]
	s_mov_b32 m0, s65
	v_lshl_add_u64 v[214:215], s[66:67], 0, v[150:151]
	global_load_lds_dwordx4 v[212:213], off
	s_add_i32 m0, s65, 0x2000
	v_lshl_add_u64 v[216:217], s[40:41], 0, v[144:145]
	global_load_lds_dwordx4 v[214:215], off
	s_mov_b32 m0, s45
	v_lshl_add_u64 v[228:229], s[40:41], 0, v[148:149]
	global_load_lds_dwordx4 v[216:217], off
	s_mov_b32 m0, s47
	s_nop 0
	global_load_lds_dwordx4 v[228:229], off
	s_waitcnt vmcnt(8)
	s_waitcnt lgkmcnt(0)
	s_setprio 1
	s_barrier
	v_mfma_f32_16x16x32_bf16 v[92:95], v[128:131], v[176:179], v[92:95]
	v_mfma_f32_16x16x32_bf16 v[88:91], v[136:139], v[176:179], v[88:91]
	v_mfma_f32_16x16x32_bf16 v[84:87], v[128:131], v[184:187], v[84:87]
	v_mfma_f32_16x16x32_bf16 v[80:83], v[136:139], v[184:187], v[80:83]
	v_mfma_f32_16x16x32_bf16 v[76:79], v[128:131], v[192:195], v[76:79]
	v_mfma_f32_16x16x32_bf16 v[72:75], v[136:139], v[192:195], v[72:75]
	v_mfma_f32_16x16x32_bf16 v[68:71], v[128:131], v[200:203], v[68:71]
	v_mfma_f32_16x16x32_bf16 v[64:67], v[136:139], v[200:203], v[64:67]
	v_mfma_f32_16x16x32_bf16 v[92:95], v[132:135], v[180:183], v[92:95]
	v_mfma_f32_16x16x32_bf16 v[88:91], v[140:143], v[180:183], v[88:91]
	v_mfma_f32_16x16x32_bf16 v[84:87], v[132:135], v[188:191], v[84:87]
	v_mfma_f32_16x16x32_bf16 v[80:83], v[140:143], v[188:191], v[80:83]
	v_mfma_f32_16x16x32_bf16 v[76:79], v[132:135], v[196:199], v[76:79]
	v_mfma_f32_16x16x32_bf16 v[72:75], v[140:143], v[196:199], v[72:75]
	v_mfma_f32_16x16x32_bf16 v[68:71], v[132:135], v[204:207], v[68:71]
	v_mfma_f32_16x16x32_bf16 v[64:67], v[140:143], v[204:207], v[64:67]
	v_mfma_f32_16x16x32_bf16 v[28:31], v[160:163], v[176:179], v[28:31]
	v_mfma_f32_16x16x32_bf16 v[24:27], v[168:171], v[176:179], v[24:27]
	v_mfma_f32_16x16x32_bf16 v[20:23], v[160:163], v[184:187], v[20:23]
	v_mfma_f32_16x16x32_bf16 v[16:19], v[168:171], v[184:187], v[16:19]
	v_mfma_f32_16x16x32_bf16 v[12:15], v[160:163], v[192:195], v[12:15]
	v_mfma_f32_16x16x32_bf16 v[8:11], v[168:171], v[192:195], v[8:11]
	v_mfma_f32_16x16x32_bf16 v[4:7], v[160:163], v[200:203], v[4:7]
	v_mfma_f32_16x16x32_bf16 v[0:3], v[168:171], v[200:203], v[0:3]
	v_mfma_f32_16x16x32_bf16 v[28:31], v[164:167], v[180:183], v[28:31]
	v_mfma_f32_16x16x32_bf16 v[24:27], v[172:175], v[180:183], v[24:27]
	v_mfma_f32_16x16x32_bf16 v[20:23], v[164:167], v[188:191], v[20:23]
	v_mfma_f32_16x16x32_bf16 v[16:19], v[172:175], v[188:191], v[16:19]
	v_mfma_f32_16x16x32_bf16 v[12:15], v[164:167], v[196:199], v[12:15]
	v_mfma_f32_16x16x32_bf16 v[8:11], v[172:175], v[196:199], v[8:11]
	v_mfma_f32_16x16x32_bf16 v[4:7], v[164:167], v[204:207], v[4:7]
	v_mfma_f32_16x16x32_bf16 v[0:3], v[172:175], v[204:207], v[0:3]
	s_barrier
	s_setprio 0
	s_add_i32 s65, 0, 0x18000
	s_add_i32 s66, 0, 0x1c000
	v_add_u32_e32 v140, s65, v219
	v_add_u32_e32 v172, s66, v219
	ds_read_b128 v[128:131], v140
	ds_read_b128 v[132:135], v140 offset:1024
	ds_read_b128 v[136:139], v140 offset:2048
	ds_read_b128 v[140:143], v140 offset:3072
	ds_read_b128 v[160:163], v172
	ds_read_b128 v[164:167], v172 offset:1024
	ds_read_b128 v[168:171], v172 offset:2048
	ds_read_b128 v[172:175], v172 offset:3072
	s_add_u32 s40, s40, s8
	s_addc_u32 s41, s41, s9
	s_mov_b32 m0, s48
	v_lshl_add_u64 v[230:231], s[40:41], 0, v[144:145]
	ds_read_b128 v[176:179], v226 offset:32768
	ds_read_b128 v[180:183], v226 offset:33792
	ds_read_b128 v[184:187], v226 offset:34816
	ds_read_b128 v[188:191], v226 offset:35840
	ds_read_b128 v[192:195], v226 offset:36864
	ds_read_b128 v[196:199], v226 offset:37888
	ds_read_b128 v[200:203], v226 offset:38912
	ds_read_b128 v[204:207], v226 offset:39936
	global_load_lds_dwordx4 v[230:231], off
	v_lshl_add_u64 v[230:231], s[40:41], 0, v[148:149]
	s_mov_b32 m0, s49
	s_nop 0
	global_load_lds_dwordx4 v[230:231], off
	s_waitcnt vmcnt(8)
	s_waitcnt lgkmcnt(0)
	s_setprio 1
	s_barrier
	v_mfma_f32_16x16x32_bf16 v[124:127], v[128:131], v[176:179], v[124:127]
	v_mfma_f32_16x16x32_bf16 v[120:123], v[136:139], v[176:179], v[120:123]
	v_mfma_f32_16x16x32_bf16 v[116:119], v[128:131], v[184:187], v[116:119]
	v_mfma_f32_16x16x32_bf16 v[112:115], v[136:139], v[184:187], v[112:115]
	v_mfma_f32_16x16x32_bf16 v[108:111], v[128:131], v[192:195], v[108:111]
	v_mfma_f32_16x16x32_bf16 v[104:107], v[136:139], v[192:195], v[104:107]
	v_mfma_f32_16x16x32_bf16 v[100:103], v[128:131], v[200:203], v[100:103]
	v_mfma_f32_16x16x32_bf16 v[96:99], v[136:139], v[200:203], v[96:99]
	v_mfma_f32_16x16x32_bf16 v[124:127], v[132:135], v[180:183], v[124:127]
	v_mfma_f32_16x16x32_bf16 v[120:123], v[140:143], v[180:183], v[120:123]
	v_mfma_f32_16x16x32_bf16 v[116:119], v[132:135], v[188:191], v[116:119]
	v_mfma_f32_16x16x32_bf16 v[112:115], v[140:143], v[188:191], v[112:115]
	v_mfma_f32_16x16x32_bf16 v[108:111], v[132:135], v[196:199], v[108:111]
	v_mfma_f32_16x16x32_bf16 v[104:107], v[140:143], v[196:199], v[104:107]
	v_mfma_f32_16x16x32_bf16 v[100:103], v[132:135], v[204:207], v[100:103]
	v_mfma_f32_16x16x32_bf16 v[96:99], v[140:143], v[204:207], v[96:99]
	v_mfma_f32_16x16x32_bf16 v[60:63], v[160:163], v[176:179], v[60:63]
	v_mfma_f32_16x16x32_bf16 v[56:59], v[168:171], v[176:179], v[56:59]
	v_mfma_f32_16x16x32_bf16 v[52:55], v[160:163], v[184:187], v[52:55]
	v_mfma_f32_16x16x32_bf16 v[48:51], v[168:171], v[184:187], v[48:51]
	v_mfma_f32_16x16x32_bf16 v[44:47], v[160:163], v[192:195], v[44:47]
	v_mfma_f32_16x16x32_bf16 v[40:43], v[168:171], v[192:195], v[40:43]
	v_mfma_f32_16x16x32_bf16 v[36:39], v[160:163], v[200:203], v[36:39]
	v_mfma_f32_16x16x32_bf16 v[32:35], v[168:171], v[200:203], v[32:35]
	v_mfma_f32_16x16x32_bf16 v[60:63], v[164:167], v[180:183], v[60:63]
	v_mfma_f32_16x16x32_bf16 v[56:59], v[172:175], v[180:183], v[56:59]
	v_mfma_f32_16x16x32_bf16 v[52:55], v[164:167], v[188:191], v[52:55]
	v_mfma_f32_16x16x32_bf16 v[48:51], v[172:175], v[188:191], v[48:51]
	v_mfma_f32_16x16x32_bf16 v[44:47], v[164:167], v[196:199], v[44:47]
	v_mfma_f32_16x16x32_bf16 v[40:43], v[172:175], v[196:199], v[40:43]
	v_mfma_f32_16x16x32_bf16 v[36:39], v[164:167], v[204:207], v[36:39]
	v_mfma_f32_16x16x32_bf16 v[32:35], v[172:175], v[204:207], v[32:35]
	s_barrier
	s_setprio 0
	s_add_i32 s40, s65, s44
	v_lshl_add_u64 v[208:209], v[208:209], 0, s[24:25]
	s_mov_b32 m0, s40
	ds_read_b128 v[176:179], v226 offset:49152
	ds_read_b128 v[180:183], v226 offset:50176
	ds_read_b128 v[184:187], v226 offset:51200
	ds_read_b128 v[188:191], v226 offset:52224
	ds_read_b128 v[192:195], v226 offset:53248
	ds_read_b128 v[196:199], v226 offset:54272
	ds_read_b128 v[200:203], v226 offset:55296
	ds_read_b128 v[204:207], v226 offset:56320
	global_load_lds_dwordx4 v[208:209], off
	v_lshl_add_u64 v[208:209], v[210:211], 0, s[24:25]
	s_add_i32 m0, s40, 0x2000
	s_add_i32 s40, s66, s44
	global_load_lds_dwordx4 v[208:209], off
	v_lshl_add_u64 v[208:209], v[212:213], 0, s[24:25]
	s_mov_b32 m0, s40
	s_nop 0
	global_load_lds_dwordx4 v[208:209], off
	v_lshl_add_u64 v[208:209], v[214:215], 0, s[24:25]
	s_add_i32 m0, s40, 0x2000
	s_nop 0
	global_load_lds_dwordx4 v[208:209], off
	v_lshl_add_u64 v[208:209], v[216:217], 0, s[24:25]
	s_mov_b32 m0, s53
	s_nop 0
	global_load_lds_dwordx4 v[208:209], off
	v_lshl_add_u64 v[208:209], v[228:229], 0, s[24:25]
	s_mov_b32 m0, s54
	s_nop 0
	global_load_lds_dwordx4 v[208:209], off
	s_waitcnt vmcnt(8)
	s_waitcnt lgkmcnt(0)
	s_setprio 1
	s_barrier
	v_mfma_f32_16x16x32_bf16 v[92:95], v[128:131], v[176:179], v[92:95]
	v_mfma_f32_16x16x32_bf16 v[88:91], v[136:139], v[176:179], v[88:91]
	v_mfma_f32_16x16x32_bf16 v[84:87], v[128:131], v[184:187], v[84:87]
	v_mfma_f32_16x16x32_bf16 v[80:83], v[136:139], v[184:187], v[80:83]
	v_mfma_f32_16x16x32_bf16 v[76:79], v[128:131], v[192:195], v[76:79]
	v_mfma_f32_16x16x32_bf16 v[72:75], v[136:139], v[192:195], v[72:75]
	v_mfma_f32_16x16x32_bf16 v[68:71], v[128:131], v[200:203], v[68:71]
	v_mfma_f32_16x16x32_bf16 v[64:67], v[136:139], v[200:203], v[64:67]
	v_mfma_f32_16x16x32_bf16 v[92:95], v[132:135], v[180:183], v[92:95]
	v_mfma_f32_16x16x32_bf16 v[88:91], v[140:143], v[180:183], v[88:91]
	v_mfma_f32_16x16x32_bf16 v[84:87], v[132:135], v[188:191], v[84:87]
	v_mfma_f32_16x16x32_bf16 v[80:83], v[140:143], v[188:191], v[80:83]
	v_mfma_f32_16x16x32_bf16 v[76:79], v[132:135], v[196:199], v[76:79]
	v_mfma_f32_16x16x32_bf16 v[72:75], v[140:143], v[196:199], v[72:75]
	v_mfma_f32_16x16x32_bf16 v[68:71], v[132:135], v[204:207], v[68:71]
	v_mfma_f32_16x16x32_bf16 v[64:67], v[140:143], v[204:207], v[64:67]
	v_mfma_f32_16x16x32_bf16 v[28:31], v[160:163], v[176:179], v[28:31]
	v_mfma_f32_16x16x32_bf16 v[24:27], v[168:171], v[176:179], v[24:27]
	v_mfma_f32_16x16x32_bf16 v[20:23], v[160:163], v[184:187], v[20:23]
	v_mfma_f32_16x16x32_bf16 v[16:19], v[168:171], v[184:187], v[16:19]
	v_mfma_f32_16x16x32_bf16 v[12:15], v[160:163], v[192:195], v[12:15]
	v_mfma_f32_16x16x32_bf16 v[8:11], v[168:171], v[192:195], v[8:11]
	v_mfma_f32_16x16x32_bf16 v[4:7], v[160:163], v[200:203], v[4:7]
	v_mfma_f32_16x16x32_bf16 v[0:3], v[168:171], v[200:203], v[0:3]
	v_mfma_f32_16x16x32_bf16 v[28:31], v[164:167], v[180:183], v[28:31]
	v_mfma_f32_16x16x32_bf16 v[24:27], v[172:175], v[180:183], v[24:27]
	v_mfma_f32_16x16x32_bf16 v[20:23], v[164:167], v[188:191], v[20:23]
	v_mfma_f32_16x16x32_bf16 v[16:19], v[172:175], v[188:191], v[16:19]
	v_mfma_f32_16x16x32_bf16 v[12:15], v[164:167], v[196:199], v[12:15]
	v_mfma_f32_16x16x32_bf16 v[8:11], v[172:175], v[196:199], v[8:11]
	v_mfma_f32_16x16x32_bf16 v[4:7], v[164:167], v[204:207], v[4:7]
	v_mfma_f32_16x16x32_bf16 v[0:3], v[172:175], v[204:207], v[0:3]
	s_barrier
	s_setprio 0
	s_add_u32 s0, s0, 0x100
	s_addc_u32 s1, s1, 0
	s_add_u32 s42, s42, 0x100
	s_addc_u32 s43, s43, 0
	s_cmp_ge_i32 s64, s55
	s_mov_b32 s40, s64
	s_cbranch_scc0 .LBB0_1472

	.amdhsa_kernel _Z8yoco_fwd6Params
		.amdhsa_group_segment_fixed_size 0
		.amdhsa_private_segment_fixed_size 0
		.amdhsa_kernarg_size 432
		.amdhsa_user_sgpr_count 2
		.amdhsa_user_sgpr_dispatch_ptr 0
		.amdhsa_user_sgpr_queue_ptr 0
		.amdhsa_user_sgpr_kernarg_segment_ptr 1
		.amdhsa_user_sgpr_dispatch_id 0
		.amdhsa_user_sgpr_kernarg_preload_length 0
		.amdhsa_user_sgpr_kernarg_preload_offset 0
		.amdhsa_user_sgpr_private_segment_size 0
		.amdhsa_uses_dynamic_stack 0
		.amdhsa_enable_private_segment 0
		.amdhsa_system_sgpr_workgroup_id_x 1
		.amdhsa_system_sgpr_workgroup_id_y 0
		.amdhsa_system_sgpr_workgroup_id_z 0
		.amdhsa_system_sgpr_workgroup_info 0
		.amdhsa_system_vgpr_workitem_id 2
		.amdhsa_next_free_vgpr 256
		.amdhsa_next_free_sgpr 98
		.amdhsa_accum_offset 256
		.amdhsa_reserve_vcc 1
		.amdhsa_float_round_mode_32 0
		.amdhsa_float_round_mode_16_64 0
		.amdhsa_float_denorm_mode_32 3
		.amdhsa_float_denorm_mode_16_64 3
		.amdhsa_dx10_clamp 1
		.amdhsa_ieee_mode 1
		.amdhsa_fp16_overflow 0
		.amdhsa_tg_split 0
		.amdhsa_exception_fp_ieee_invalid_op 0
		.amdhsa_exception_fp_denorm_src 0
		.amdhsa_exception_fp_ieee_div_zero 0
		.amdhsa_exception_fp_ieee_overflow 0
		.amdhsa_exception_fp_ieee_underflow 0
		.amdhsa_exception_fp_ieee_inexact 0
		.amdhsa_exception_int_div_zero 0
	.end_amdhsa_kernel

amdhsa.kernels:
  - .agpr_count:     0
    .args:
      - .offset:         0
        .size:           176
        .value_kind:     by_value
      - .offset:         176
        .size:           4
        .value_kind:     hidden_block_count_x
      - .offset:         180
        .size:           4
        .value_kind:     hidden_block_count_y
      - .offset:         184
        .size:           4
        .value_kind:     hidden_block_count_z
      - .offset:         188
        .size:           2
        .value_kind:     hidden_group_size_x
      - .offset:         190
        .size:           2
        .value_kind:     hidden_group_size_y
      - .offset:         192
        .size:           2
        .value_kind:     hidden_group_size_z
      - .offset:         194
        .size:           2
        .value_kind:     hidden_remainder_x
      - .offset:         196
        .size:           2
        .value_kind:     hidden_remainder_y
      - .offset:         198
        .size:           2
        .value_kind:     hidden_remainder_z
      - .offset:         216
        .size:           8
        .value_kind:     hidden_global_offset_x
      - .offset:         224
        .size:           8
        .value_kind:     hidden_global_offset_y
      - .offset:         232
        .size:           8
        .value_kind:     hidden_global_offset_z
      - .offset:         240
        .size:           2
        .value_kind:     hidden_grid_dims
      - .offset:         264
        .size:           8
        .value_kind:     hidden_multigrid_sync_arg
      - .offset:         296
        .size:           4
        .value_kind:     hidden_dynamic_lds_size
    .group_segment_fixed_size: 0
    .kernarg_segment_align: 8
    .kernarg_segment_size: 432
    .language:       OpenCL C
    .language_version:
      - 2
      - 0
    .max_flat_workgroup_size: 512
    .name:           _Z8yoco_fwd6Params
    .private_segment_fixed_size: 0
    .sgpr_count:     104
    .sgpr_spill_count: 34
    .symbol:         _Z8yoco_fwd6Params.kd
    .uniform_work_group_size: 1
    .uses_dynamic_stack: false
    .vgpr_count:     256
    .vgpr_spill_count: 0
    .wavefront_size: 64
